# v55 minus the mid-burst s_setprio 0 / s_setprio 1 pairs (priority stays 1 across the whole 32-MFMA burst)
# speedup vs baseline: 1.0144x; 1.0016x over previous
; #define PG8_STAGE(bufoff, gbase, voff) do { _Pragma("unroll") for (int _i = 0; _i < 2; ++_i) \
;         __builtin_amdgcn_global_load_lds((const unsigned*)((const char*)(gbase) + (voff)[_i]), (LAS unsigned*)(lds + (bufoff) + ldsw + _i * 8192), 16, 0, 0); } while (0)
; #define PG8_LDA(dst, b, h) do { _Pragma("unroll") for (int m = 0; m < 4; ++m) _Pragma("unroll") for (int k = 0; k < 2; ++k) dst[m][k] = *(const LAS bf16x8*)(lds + PG8_SA(b, h) + aoff + m * 2048 + k * 1024); } while (0)
; #define PG8_LDB(dst, b, h) do { _Pragma("unroll") for (int n = 0; n < 2; ++n) _Pragma("unroll") for (int k = 0; k < 2; ++k) dst[n][k] = *(const LAS bf16x8*)(lds + PG8_SB(b, h) + boff + n * 2048 + k * 1024); } while (0)
; #define PG8_MMA(ai, bj, At, Bt) do { __builtin_amdgcn_s_setprio(1); _Pragma("unroll") for (int m = 0; m < 4; ++m) _Pragma("unroll") for (int n = 0; n < 2; ++n) _Pragma("unroll") for (int k = 0; k < 2; ++k) \
;         acc[ai][bj][m][n] = __builtin_amdgcn_mfma_f32_16x16x32_bf16(Bt[n][k], At[m][k], acc[ai][bj][m][n], 0, 0, 0); __builtin_amdgcn_s_setprio(0); } while (0)
; #define PG8_WAIT_V(n) asm volatile("s_waitcnt vmcnt(" #n ")" ::: "memory")
; #define PG8_WAIT_L(n) asm volatile("s_waitcnt lgkmcnt(" #n ")" ::: "memory")
; #define PG8_BAR __builtin_amdgcn_s_barrier()
; template <class Epi, class Sched, bool ALIGN_EPI>
; __device__ __forceinline__ void gemm_phase(LAS unsigned char* lds, const Gemm g, const Sched& S, const Epi& E, const int wid) {
;     ...
;             const bool last = (t == nt - 2);
;             if constexpr (Epi::HAS_PRE) { if (last) X.pre = E.pre(cur, tid); }
;             const char* a1 = cA + (size_t)(t + 1) * kstepA;
;             const char* a2 = last ? nA : cA + (size_t)(t + 2) * kstepA; const char* b2 = last ? nB : cB + (size_t)(t + 2) * kstep;
;             const char* a3 = a2 + kstepA; const char* b3 = b2 + kstep;
;             PG8_LDB(B0, 0, 0); PG8_LDB(B1, 0, 1); PG8_SCHED; PG8_LDA(At, 0, 0); PG8_STAGE(PG8_SA(1, 1), a1 + hstepA, voffA);
;             PG8_WAIT_V(8); PG8_WAIT_L(0); PG8_BAR; PG8_MMA(0, 0, At, B0); PG8_MMA(0, 1, At, B1); PG8_BAR; PG8_SCHED;
;             PG8_LDA(At, 0, 1); PG8_STAGE(PG8_SB(0, 0), b2, voffB); PG8_STAGE(PG8_SB(0, 1), b2 + hstepB, voffB); PG8_STAGE(PG8_SA(0, 0), a2, voffA);
;             PG8_WAIT_V(8); PG8_WAIT_L(0); PG8_BAR; PG8_MMA(1, 0, At, B0); PG8_MMA(1, 1, At, B1); PG8_BAR; PG8_SCHED;
.LBB0_166:
	ds_read_b128 v[152:155], v149
	ds_read_b128 v[156:159], v149 offset:1024
	ds_read_b128 v[160:163], v149 offset:2048
	ds_read_b128 v[164:167], v149 offset:3072
	ds_read_b128 v[168:171], v150
	ds_read_b128 v[172:175], v150 offset:1024
	ds_read_b128 v[176:179], v150 offset:2048
	ds_read_b128 v[180:183], v150 offset:3072
	s_add_u32 s26, s24, 0x4000
	s_addc_u32 s27, s25, 0
	s_cmp_eq_u32 s66, 60
	s_cselect_b32 s50, s35, s26
	s_cselect_b32 s51, s17, s27
	s_cselect_b32 s48, s63, s64
	s_cselect_b32 s49, s15, s65
	s_add_u32 s26, s50, 0x8000
	s_addc_u32 s27, s51, 0
	s_add_i32 m0, s47, 0xc000
	ds_read_b128 v[184:187], v151
	ds_read_b128 v[188:191], v151 offset:1024
	ds_read_b128 v[192:195], v151 offset:2048
	ds_read_b128 v[196:199], v151 offset:3072
	ds_read_b128 v[200:203], v151 offset:4096
	ds_read_b128 v[204:207], v151 offset:5120
	ds_read_b128 v[208:211], v151 offset:6144
	ds_read_b128 v[212:215], v151 offset:7168
	global_load_lds_dwordx4 v138, s[24:25]
	s_add_i32 m0, s47, 0xe000
	s_nop 0
	global_load_lds_dwordx4 v140, s[24:25]
	s_waitcnt vmcnt(8)
	s_waitcnt lgkmcnt(0)
	s_setprio 1
	s_barrier
	v_mfma_f32_16x16x32_bf16 v[124:127], v[152:155], v[184:187], v[124:127]
	v_mfma_f32_16x16x32_bf16 v[120:123], v[160:163], v[184:187], v[120:123]
	v_mfma_f32_16x16x32_bf16 v[108:111], v[152:155], v[192:195], v[108:111]
	v_mfma_f32_16x16x32_bf16 v[104:107], v[160:163], v[192:195], v[104:107]
	v_mfma_f32_16x16x32_bf16 v[92:95], v[152:155], v[200:203], v[92:95]
	v_mfma_f32_16x16x32_bf16 v[88:91], v[160:163], v[200:203], v[88:91]
	v_mfma_f32_16x16x32_bf16 v[76:79], v[152:155], v[208:211], v[76:79]
	v_mfma_f32_16x16x32_bf16 v[72:75], v[160:163], v[208:211], v[72:75]
	v_mfma_f32_16x16x32_bf16 v[124:127], v[156:159], v[188:191], v[124:127]
	v_mfma_f32_16x16x32_bf16 v[120:123], v[164:167], v[188:191], v[120:123]
	v_mfma_f32_16x16x32_bf16 v[108:111], v[156:159], v[196:199], v[108:111]
	v_mfma_f32_16x16x32_bf16 v[104:107], v[164:167], v[196:199], v[104:107]
	v_mfma_f32_16x16x32_bf16 v[92:95], v[156:159], v[204:207], v[92:95]
	v_mfma_f32_16x16x32_bf16 v[88:91], v[164:167], v[204:207], v[88:91]
	v_mfma_f32_16x16x32_bf16 v[76:79], v[156:159], v[212:215], v[76:79]
	v_mfma_f32_16x16x32_bf16 v[72:75], v[164:167], v[212:215], v[72:75]
	v_mfma_f32_16x16x32_bf16 v[116:119], v[168:171], v[184:187], v[116:119]
	v_mfma_f32_16x16x32_bf16 v[112:115], v[176:179], v[184:187], v[112:115]
	v_mfma_f32_16x16x32_bf16 v[100:103], v[168:171], v[192:195], v[100:103]
	v_mfma_f32_16x16x32_bf16 v[96:99], v[176:179], v[192:195], v[96:99]
	v_mfma_f32_16x16x32_bf16 v[84:87], v[168:171], v[200:203], v[84:87]
	v_mfma_f32_16x16x32_bf16 v[80:83], v[176:179], v[200:203], v[80:83]
	v_mfma_f32_16x16x32_bf16 v[68:71], v[168:171], v[208:211], v[68:71]
	v_mfma_f32_16x16x32_bf16 v[64:67], v[176:179], v[208:211], v[64:67]
	v_mfma_f32_16x16x32_bf16 v[116:119], v[172:175], v[188:191], v[116:119]
	v_mfma_f32_16x16x32_bf16 v[112:115], v[180:183], v[188:191], v[112:115]
	v_mfma_f32_16x16x32_bf16 v[100:103], v[172:175], v[196:199], v[100:103]
	v_mfma_f32_16x16x32_bf16 v[96:99], v[180:183], v[196:199], v[96:99]
	v_mfma_f32_16x16x32_bf16 v[84:87], v[172:175], v[204:207], v[84:87]
	v_mfma_f32_16x16x32_bf16 v[80:83], v[180:183], v[204:207], v[80:83]
	v_mfma_f32_16x16x32_bf16 v[68:71], v[172:175], v[212:215], v[68:71]
	v_mfma_f32_16x16x32_bf16 v[64:67], v[180:183], v[212:215], v[64:67]
	s_barrier
	s_setprio 0
	s_add_i32 s38, s61, s3
	s_mov_b32 m0, s38
	ds_read_b128 v[184:187], v151 offset:16384
	ds_read_b128 v[188:191], v151 offset:17408
	ds_read_b128 v[192:195], v151 offset:18432
	ds_read_b128 v[196:199], v151 offset:19456
	ds_read_b128 v[200:203], v151 offset:20480
	ds_read_b128 v[204:207], v151 offset:21504
	ds_read_b128 v[208:211], v151 offset:22528
	ds_read_b128 v[212:215], v151 offset:23552
	global_load_lds_dwordx4 v132, s[48:49]
	s_add_i32 m0, s38, 0x2000
	s_add_u32 s68, s48, 0x1000
	s_addc_u32 s69, s49, 0
	s_add_i32 s38, s62, s3
	global_load_lds_dwordx4 v128, s[48:49]
	s_mov_b32 m0, s38
	s_nop 0
	global_load_lds_dwordx4 v132, s[68:69]
	s_add_i32 m0, s38, 0x2000
	s_nop 0
	global_load_lds_dwordx4 v128, s[68:69]
	s_mov_b32 m0, s47
	s_nop 0
	global_load_lds_dwordx4 v134, s[50:51]
	s_mov_b32 m0, s52
	s_nop 0
	global_load_lds_dwordx4 v130, s[50:51]
	s_waitcnt vmcnt(8)
	s_waitcnt lgkmcnt(0)
	s_setprio 1
	s_barrier
	v_mfma_f32_16x16x32_bf16 v[60:63], v[152:155], v[184:187], v[60:63]
	v_mfma_f32_16x16x32_bf16 v[56:59], v[160:163], v[184:187], v[56:59]
	v_mfma_f32_16x16x32_bf16 v[44:47], v[152:155], v[192:195], v[44:47]
	v_mfma_f32_16x16x32_bf16 v[40:43], v[160:163], v[192:195], v[40:43]
	v_mfma_f32_16x16x32_bf16 v[28:31], v[152:155], v[200:203], v[28:31]
	v_mfma_f32_16x16x32_bf16 v[24:27], v[160:163], v[200:203], v[24:27]
	v_mfma_f32_16x16x32_bf16 v[12:15], v[152:155], v[208:211], v[12:15]
	v_mfma_f32_16x16x32_bf16 v[8:11], v[160:163], v[208:211], v[8:11]
	v_mfma_f32_16x16x32_bf16 v[60:63], v[156:159], v[188:191], v[60:63]
	v_mfma_f32_16x16x32_bf16 v[56:59], v[164:167], v[188:191], v[56:59]
	v_mfma_f32_16x16x32_bf16 v[44:47], v[156:159], v[196:199], v[44:47]
	v_mfma_f32_16x16x32_bf16 v[40:43], v[164:167], v[196:199], v[40:43]
	v_mfma_f32_16x16x32_bf16 v[28:31], v[156:159], v[204:207], v[28:31]
	v_mfma_f32_16x16x32_bf16 v[24:27], v[164:167], v[204:207], v[24:27]
	v_mfma_f32_16x16x32_bf16 v[12:15], v[156:159], v[212:215], v[12:15]
	v_mfma_f32_16x16x32_bf16 v[8:11], v[164:167], v[212:215], v[8:11]
	v_mfma_f32_16x16x32_bf16 v[52:55], v[168:171], v[184:187], v[52:55]
	v_mfma_f32_16x16x32_bf16 v[48:51], v[176:179], v[184:187], v[48:51]
	v_mfma_f32_16x16x32_bf16 v[36:39], v[168:171], v[192:195], v[36:39]
	v_mfma_f32_16x16x32_bf16 v[32:35], v[176:179], v[192:195], v[32:35]
	v_mfma_f32_16x16x32_bf16 v[20:23], v[168:171], v[200:203], v[20:23]
	v_mfma_f32_16x16x32_bf16 v[16:19], v[176:179], v[200:203], v[16:19]
	v_mfma_f32_16x16x32_bf16 v[4:7], v[168:171], v[208:211], v[4:7]
	v_mfma_f32_16x16x32_bf16 v[0:3], v[176:179], v[208:211], v[0:3]
	v_mfma_f32_16x16x32_bf16 v[52:55], v[172:175], v[188:191], v[52:55]
	v_mfma_f32_16x16x32_bf16 v[48:51], v[180:183], v[188:191], v[48:51]
	v_mfma_f32_16x16x32_bf16 v[36:39], v[172:175], v[196:199], v[36:39]
	v_mfma_f32_16x16x32_bf16 v[32:35], v[180:183], v[196:199], v[32:35]
	v_mfma_f32_16x16x32_bf16 v[20:23], v[172:175], v[204:207], v[20:23]
	v_mfma_f32_16x16x32_bf16 v[16:19], v[180:183], v[204:207], v[16:19]
	v_mfma_f32_16x16x32_bf16 v[4:7], v[172:175], v[212:215], v[4:7]
	v_mfma_f32_16x16x32_bf16 v[0:3], v[180:183], v[212:215], v[0:3]
	s_barrier
; #define PG8_STAGE(bufoff, gbase, voff) do { _Pragma("unroll") for (int _i = 0; _i < 2; ++_i) \
;         __builtin_amdgcn_global_load_lds((const unsigned*)((const char*)(gbase) + (voff)[_i]), (LAS unsigned*)(lds + (bufoff) + ldsw + _i * 8192), 16, 0, 0); } while (0)
; #define PG8_LDA(dst, b, h) do { _Pragma("unroll") for (int m = 0; m < 4; ++m) _Pragma("unroll") for (int k = 0; k < 2; ++k) dst[m][k] = *(const LAS bf16x8*)(lds + PG8_SA(b, h) + aoff + m * 2048 + k * 1024); } while (0)
; #define PG8_LDB(dst, b, h) do { _Pragma("unroll") for (int n = 0; n < 2; ++n) _Pragma("unroll") for (int k = 0; k < 2; ++k) dst[n][k] = *(const LAS bf16x8*)(lds + PG8_SB(b, h) + boff + n * 2048 + k * 1024); } while (0)
; #define PG8_MMA(ai, bj, At, Bt) do { __builtin_amdgcn_s_setprio(1); _Pragma("unroll") for (int m = 0; m < 4; ++m) _Pragma("unroll") for (int n = 0; n < 2; ++n) _Pragma("unroll") for (int k = 0; k < 2; ++k) \
;         acc[ai][bj][m][n] = __builtin_amdgcn_mfma_f32_16x16x32_bf16(Bt[n][k], At[m][k], acc[ai][bj][m][n], 0, 0, 0); __builtin_amdgcn_s_setprio(0); } while (0)
; #define PG8_WAIT_V(n) asm volatile("s_waitcnt vmcnt(" #n ")" ::: "memory")
; #define PG8_WAIT_L(n) asm volatile("s_waitcnt lgkmcnt(" #n ")" ::: "memory")
; #define PG8_BAR __builtin_amdgcn_s_barrier()
; #define PG8_SCHED __builtin_amdgcn_sched_barrier(0)
; template <class Epi, class Sched, bool ALIGN_EPI>
; __device__ __forceinline__ void gemm_phase(LAS unsigned char* lds, const Gemm g, const Sched& S, const Epi& E, const int wid) {
;     ...
;             PG8_LDB(B0, 1, 0); PG8_LDB(B1, 1, 1); PG8_SCHED; PG8_LDA(At, 1, 0); PG8_STAGE(PG8_SA(0, 1), a2 + hstepA, voffA);
;             PG8_WAIT_V(8); PG8_WAIT_L(0); PG8_BAR; PG8_MMA(0, 0, At, B0); PG8_MMA(0, 1, At, B1); PG8_BAR; PG8_SCHED;
;             PG8_LDA(At, 1, 1); PG8_STAGE(PG8_SB(1, 0), b3, voffB); PG8_STAGE(PG8_SB(1, 1), b3 + hstepB, voffB); PG8_STAGE(PG8_SA(1, 0), a3, voffA);
;             PG8_WAIT_V(8); PG8_WAIT_L(0); PG8_BAR; PG8_MMA(1, 0, At, B0); PG8_MMA(1, 1, At, B1); PG8_BAR; PG8_SCHED;
;         }
;         if constexpr (ALIGN_EPI) { if (wr == 0) PG8_BAR; }
	s_setprio 0
	s_add_i32 s38, 0, 0x18000
	v_add_u32_e32 v136, s38, v146
	s_add_i32 s39, 0, 0x1c000
	ds_read_b128 v[152:155], v136
	ds_read_b128 v[156:159], v136 offset:1024
	ds_read_b128 v[160:163], v136 offset:2048
	ds_read_b128 v[164:167], v136 offset:3072
	v_add_u32_e32 v136, s39, v146
	ds_read_b128 v[168:171], v136
	ds_read_b128 v[172:175], v136 offset:1024
	ds_read_b128 v[176:179], v136 offset:2048
	ds_read_b128 v[180:183], v136 offset:3072
	s_add_u32 s50, s50, 0x4000
	s_addc_u32 s51, s51, 0
	s_mov_b32 m0, s53
	ds_read_b128 v[184:187], v151 offset:32768
	ds_read_b128 v[188:191], v151 offset:33792
	ds_read_b128 v[192:195], v151 offset:34816
	ds_read_b128 v[196:199], v151 offset:35840
	ds_read_b128 v[200:203], v151 offset:36864
	ds_read_b128 v[204:207], v151 offset:37888
	ds_read_b128 v[208:211], v151 offset:38912
	ds_read_b128 v[212:215], v151 offset:39936
	global_load_lds_dwordx4 v134, s[50:51]
	s_mov_b32 m0, s54
	s_nop 0
	global_load_lds_dwordx4 v130, s[50:51]
	s_waitcnt vmcnt(8)
	s_waitcnt lgkmcnt(0)
	s_setprio 1
	s_barrier
	v_mfma_f32_16x16x32_bf16 v[124:127], v[152:155], v[184:187], v[124:127]
	v_mfma_f32_16x16x32_bf16 v[120:123], v[160:163], v[184:187], v[120:123]
	v_mfma_f32_16x16x32_bf16 v[108:111], v[152:155], v[192:195], v[108:111]
	v_mfma_f32_16x16x32_bf16 v[104:107], v[160:163], v[192:195], v[104:107]
	v_mfma_f32_16x16x32_bf16 v[92:95], v[152:155], v[200:203], v[92:95]
	v_mfma_f32_16x16x32_bf16 v[88:91], v[160:163], v[200:203], v[88:91]
	v_mfma_f32_16x16x32_bf16 v[76:79], v[152:155], v[208:211], v[76:79]
	v_mfma_f32_16x16x32_bf16 v[72:75], v[160:163], v[208:211], v[72:75]
	v_mfma_f32_16x16x32_bf16 v[124:127], v[156:159], v[188:191], v[124:127]
	v_mfma_f32_16x16x32_bf16 v[120:123], v[164:167], v[188:191], v[120:123]
	v_mfma_f32_16x16x32_bf16 v[108:111], v[156:159], v[196:199], v[108:111]
	v_mfma_f32_16x16x32_bf16 v[104:107], v[164:167], v[196:199], v[104:107]
	v_mfma_f32_16x16x32_bf16 v[92:95], v[156:159], v[204:207], v[92:95]
	v_mfma_f32_16x16x32_bf16 v[88:91], v[164:167], v[204:207], v[88:91]
	v_mfma_f32_16x16x32_bf16 v[76:79], v[156:159], v[212:215], v[76:79]
	v_mfma_f32_16x16x32_bf16 v[72:75], v[164:167], v[212:215], v[72:75]
	v_mfma_f32_16x16x32_bf16 v[116:119], v[168:171], v[184:187], v[116:119]
	v_mfma_f32_16x16x32_bf16 v[112:115], v[176:179], v[184:187], v[112:115]
	v_mfma_f32_16x16x32_bf16 v[100:103], v[168:171], v[192:195], v[100:103]
	v_mfma_f32_16x16x32_bf16 v[96:99], v[176:179], v[192:195], v[96:99]
	v_mfma_f32_16x16x32_bf16 v[84:87], v[168:171], v[200:203], v[84:87]
	v_mfma_f32_16x16x32_bf16 v[80:83], v[176:179], v[200:203], v[80:83]
	v_mfma_f32_16x16x32_bf16 v[68:71], v[168:171], v[208:211], v[68:71]
	v_mfma_f32_16x16x32_bf16 v[64:67], v[176:179], v[208:211], v[64:67]
	v_mfma_f32_16x16x32_bf16 v[116:119], v[172:175], v[188:191], v[116:119]
	v_mfma_f32_16x16x32_bf16 v[112:115], v[180:183], v[188:191], v[112:115]
	v_mfma_f32_16x16x32_bf16 v[100:103], v[172:175], v[196:199], v[100:103]
	v_mfma_f32_16x16x32_bf16 v[96:99], v[180:183], v[196:199], v[96:99]
	v_mfma_f32_16x16x32_bf16 v[84:87], v[172:175], v[204:207], v[84:87]
	v_mfma_f32_16x16x32_bf16 v[80:83], v[180:183], v[204:207], v[80:83]
	v_mfma_f32_16x16x32_bf16 v[68:71], v[172:175], v[212:215], v[68:71]
	v_mfma_f32_16x16x32_bf16 v[64:67], v[180:183], v[212:215], v[64:67]
	s_barrier
	s_setprio 0
	s_add_u32 s50, s48, 0x8000
	s_addc_u32 s51, s49, 0
	s_add_i32 s38, s38, s3
	s_mov_b32 m0, s38
	ds_read_b128 v[184:187], v151 offset:49152
	ds_read_b128 v[188:191], v151 offset:50176
	ds_read_b128 v[192:195], v151 offset:51200
	ds_read_b128 v[196:199], v151 offset:52224
	ds_read_b128 v[200:203], v151 offset:53248
	ds_read_b128 v[204:207], v151 offset:54272
	ds_read_b128 v[208:211], v151 offset:55296
	ds_read_b128 v[212:215], v151 offset:56320
	global_load_lds_dwordx4 v132, s[50:51]
	s_add_i32 m0, s38, 0x2000
	s_add_u32 s48, s48, 0x9000
	s_addc_u32 s49, s49, 0
	s_add_i32 s38, s39, s3
	global_load_lds_dwordx4 v128, s[50:51]
	s_mov_b32 m0, s38
	s_nop 0
	global_load_lds_dwordx4 v132, s[48:49]
	s_add_i32 m0, s38, 0x2000
	s_nop 0
	global_load_lds_dwordx4 v128, s[48:49]
	s_mov_b32 m0, s58
	s_nop 0
	global_load_lds_dwordx4 v134, s[26:27]
	s_mov_b32 m0, s59
	s_nop 0
	global_load_lds_dwordx4 v130, s[26:27]
	s_waitcnt vmcnt(8)
	s_waitcnt lgkmcnt(0)
	s_setprio 1
	s_barrier
	v_mfma_f32_16x16x32_bf16 v[60:63], v[152:155], v[184:187], v[60:63]
	v_mfma_f32_16x16x32_bf16 v[56:59], v[160:163], v[184:187], v[56:59]
	v_mfma_f32_16x16x32_bf16 v[44:47], v[152:155], v[192:195], v[44:47]
	v_mfma_f32_16x16x32_bf16 v[40:43], v[160:163], v[192:195], v[40:43]
	v_mfma_f32_16x16x32_bf16 v[28:31], v[152:155], v[200:203], v[28:31]
	v_mfma_f32_16x16x32_bf16 v[24:27], v[160:163], v[200:203], v[24:27]
	v_mfma_f32_16x16x32_bf16 v[12:15], v[152:155], v[208:211], v[12:15]
	v_mfma_f32_16x16x32_bf16 v[8:11], v[160:163], v[208:211], v[8:11]
	v_mfma_f32_16x16x32_bf16 v[60:63], v[156:159], v[188:191], v[60:63]
	v_mfma_f32_16x16x32_bf16 v[56:59], v[164:167], v[188:191], v[56:59]
	v_mfma_f32_16x16x32_bf16 v[44:47], v[156:159], v[196:199], v[44:47]
	v_mfma_f32_16x16x32_bf16 v[40:43], v[164:167], v[196:199], v[40:43]
	v_mfma_f32_16x16x32_bf16 v[28:31], v[156:159], v[204:207], v[28:31]
	v_mfma_f32_16x16x32_bf16 v[24:27], v[164:167], v[204:207], v[24:27]
	v_mfma_f32_16x16x32_bf16 v[12:15], v[156:159], v[212:215], v[12:15]
	v_mfma_f32_16x16x32_bf16 v[8:11], v[164:167], v[212:215], v[8:11]
	v_mfma_f32_16x16x32_bf16 v[52:55], v[168:171], v[184:187], v[52:55]
	v_mfma_f32_16x16x32_bf16 v[48:51], v[176:179], v[184:187], v[48:51]
	v_mfma_f32_16x16x32_bf16 v[36:39], v[168:171], v[192:195], v[36:39]
	v_mfma_f32_16x16x32_bf16 v[32:35], v[176:179], v[192:195], v[32:35]
	v_mfma_f32_16x16x32_bf16 v[20:23], v[168:171], v[200:203], v[20:23]
	v_mfma_f32_16x16x32_bf16 v[16:19], v[176:179], v[200:203], v[16:19]
	v_mfma_f32_16x16x32_bf16 v[4:7], v[168:171], v[208:211], v[4:7]
	v_mfma_f32_16x16x32_bf16 v[0:3], v[176:179], v[208:211], v[0:3]
	v_mfma_f32_16x16x32_bf16 v[52:55], v[172:175], v[188:191], v[52:55]
	v_mfma_f32_16x16x32_bf16 v[48:51], v[180:183], v[188:191], v[48:51]
	v_mfma_f32_16x16x32_bf16 v[36:39], v[172:175], v[196:199], v[36:39]
	v_mfma_f32_16x16x32_bf16 v[32:35], v[180:183], v[196:199], v[32:35]
	v_mfma_f32_16x16x32_bf16 v[20:23], v[172:175], v[204:207], v[20:23]
	v_mfma_f32_16x16x32_bf16 v[16:19], v[180:183], v[204:207], v[16:19]
	v_mfma_f32_16x16x32_bf16 v[4:7], v[172:175], v[212:215], v[4:7]
	v_mfma_f32_16x16x32_bf16 v[0:3], v[180:183], v[212:215], v[0:3]
	s_barrier
	s_setprio 0
	s_add_i32 s66, s66, 2
	s_add_u32 s24, s24, 0x10000
	s_addc_u32 s25, s25, 0
	s_add_u32 s64, s64, 0x10000
	s_addc_u32 s65, s65, 0
	s_cmp_gt_u32 s66, 61
	s_cbranch_scc0 .LBB0_166
	s_and_b64 vcc, exec, s[28:29]
	s_cbranch_vccz .LBB0_169
	s_barrier

; #define PG8_STAGE(bufoff, gbase, voff) do { _Pragma("unroll") for (int _i = 0; _i < 2; ++_i) \
;         __builtin_amdgcn_global_load_lds((const unsigned*)((const char*)(gbase) + (voff)[_i]), (LAS unsigned*)(lds + (bufoff) + ldsw + _i * 8192), 16, 0, 0); } while (0)
; #define PG8_LDA(dst, b, h) do { _Pragma("unroll") for (int m = 0; m < 4; ++m) _Pragma("unroll") for (int k = 0; k < 2; ++k) dst[m][k] = *(const LAS bf16x8*)(lds + PG8_SA(b, h) + aoff + m * 2048 + k * 1024); } while (0)
; #define PG8_LDB(dst, b, h) do { _Pragma("unroll") for (int n = 0; n < 2; ++n) _Pragma("unroll") for (int k = 0; k < 2; ++k) dst[n][k] = *(const LAS bf16x8*)(lds + PG8_SB(b, h) + boff + n * 2048 + k * 1024); } while (0)
; #define PG8_MMA(ai, bj, At, Bt) do { __builtin_amdgcn_s_setprio(1); _Pragma("unroll") for (int m = 0; m < 4; ++m) _Pragma("unroll") for (int n = 0; n < 2; ++n) _Pragma("unroll") for (int k = 0; k < 2; ++k) \
;         acc[ai][bj][m][n] = __builtin_amdgcn_mfma_f32_16x16x32_bf16(Bt[n][k], At[m][k], acc[ai][bj][m][n], 0, 0, 0); __builtin_amdgcn_s_setprio(0); } while (0)
; #define PG8_WAIT_V(n) asm volatile("s_waitcnt vmcnt(" #n ")" ::: "memory")
; #define PG8_WAIT_L(n) asm volatile("s_waitcnt lgkmcnt(" #n ")" ::: "memory")
; #define PG8_BAR __builtin_amdgcn_s_barrier()
; #define PG8_SCHED __builtin_amdgcn_sched_barrier(0)
; template <class Epi, class Sched, bool ALIGN_EPI>
; __device__ __forceinline__ void gemm_phase(LAS unsigned char* lds, const Gemm g, const Sched& S, const Epi& E, const int wid) {
;     ...
;             const char* a1 = cA + (size_t)(t + 1) * kstepA;
;             const char* a2 = last ? nA : cA + (size_t)(t + 2) * kstepA; const char* b2 = last ? nB : cB + (size_t)(t + 2) * kstep;
;             const char* a3 = a2 + kstepA; const char* b3 = b2 + kstep;
;             PG8_LDB(B0, 0, 0); PG8_LDB(B1, 0, 1); PG8_SCHED; PG8_LDA(At, 0, 0); PG8_STAGE(PG8_SA(1, 1), a1 + hstepA, voffA);
;             PG8_WAIT_V(8); PG8_WAIT_L(0); PG8_BAR; PG8_MMA(0, 0, At, B0); PG8_MMA(0, 1, At, B1); PG8_BAR; PG8_SCHED;
;             PG8_LDA(At, 0, 1); PG8_STAGE(PG8_SB(0, 0), b2, voffB); PG8_STAGE(PG8_SB(0, 1), b2 + hstepB, voffB); PG8_STAGE(PG8_SA(0, 0), a2, voffA);
;             PG8_WAIT_V(8); PG8_WAIT_L(0); PG8_BAR; PG8_MMA(1, 0, At, B0); PG8_MMA(1, 1, At, B1); PG8_BAR; PG8_SCHED;
.LBB0_243:
	s_add_u32 s38, s26, s60
	s_addc_u32 s39, s27, s61
	s_add_u32 s64, s38, 0x100
	s_addc_u32 s65, s39, 0
	s_and_b64 s[62:63], s[58:59], exec
	s_cselect_b32 s63, s21, s65
	s_cselect_b32 s62, s20, s64
	s_add_u32 s60, s10, s60
	s_addc_u32 s61, s11, s61
	s_add_u32 s60, s60, 0x100
	ds_read_b128 v[142:145], v137
	ds_read_b128 v[146:149], v137 offset:1024
	ds_read_b128 v[150:153], v137 offset:2048
	ds_read_b128 v[154:157], v137 offset:3072
	ds_read_b128 v[158:161], v138
	ds_read_b128 v[162:165], v138 offset:1024
	ds_read_b128 v[166:169], v138 offset:2048
	ds_read_b128 v[170:173], v138 offset:3072
	s_addc_u32 s61, s61, 0
	s_and_b64 s[58:59], s[58:59], exec
	s_cselect_b32 s65, s35, s61
	s_cselect_b32 s64, s55, s60
	s_add_u32 s68, s38, 0x18080
	s_addc_u32 s69, s39, 0
	s_add_u32 s66, s64, 0x4000
	s_addc_u32 s67, s65, 0
	s_add_u32 s60, s62, 0x18000
	s_addc_u32 s61, s63, 0
	s_add_u32 s58, s64, 0x4080
	s_addc_u32 s59, s65, 0
	s_mov_b32 m0, s30
	ds_read_b128 v[174:177], v139
	ds_read_b128 v[178:181], v139 offset:1024
	ds_read_b128 v[182:185], v139 offset:2048
	ds_read_b128 v[186:189], v139 offset:3072
	ds_read_b128 v[190:193], v139 offset:4096
	ds_read_b128 v[194:197], v139 offset:5120
	ds_read_b128 v[198:201], v139 offset:6144
	ds_read_b128 v[202:205], v139 offset:7168
	global_load_lds_dwordx4 v134, s[68:69]
	s_mov_b32 m0, s77
	s_nop 0
	global_load_lds_dwordx4 v130, s[68:69]
	s_waitcnt vmcnt(8)
	s_waitcnt lgkmcnt(0)
	s_setprio 1
	s_barrier
	v_mfma_f32_16x16x32_bf16 v[124:127], v[142:145], v[174:177], v[124:127]
	v_mfma_f32_16x16x32_bf16 v[120:123], v[150:153], v[174:177], v[120:123]
	v_mfma_f32_16x16x32_bf16 v[108:111], v[142:145], v[182:185], v[108:111]
	v_mfma_f32_16x16x32_bf16 v[104:107], v[150:153], v[182:185], v[104:107]
	v_mfma_f32_16x16x32_bf16 v[92:95], v[142:145], v[190:193], v[92:95]
	v_mfma_f32_16x16x32_bf16 v[88:91], v[150:153], v[190:193], v[88:91]
	v_mfma_f32_16x16x32_bf16 v[76:79], v[142:145], v[198:201], v[76:79]
	v_mfma_f32_16x16x32_bf16 v[72:75], v[150:153], v[198:201], v[72:75]
	v_mfma_f32_16x16x32_bf16 v[124:127], v[146:149], v[178:181], v[124:127]
	v_mfma_f32_16x16x32_bf16 v[120:123], v[154:157], v[178:181], v[120:123]
	v_mfma_f32_16x16x32_bf16 v[108:111], v[146:149], v[186:189], v[108:111]
	v_mfma_f32_16x16x32_bf16 v[104:107], v[154:157], v[186:189], v[104:107]
	v_mfma_f32_16x16x32_bf16 v[92:95], v[146:149], v[194:197], v[92:95]
	v_mfma_f32_16x16x32_bf16 v[88:91], v[154:157], v[194:197], v[88:91]
	v_mfma_f32_16x16x32_bf16 v[76:79], v[146:149], v[202:205], v[76:79]
	v_mfma_f32_16x16x32_bf16 v[72:75], v[154:157], v[202:205], v[72:75]
	v_mfma_f32_16x16x32_bf16 v[116:119], v[158:161], v[174:177], v[116:119]
	v_mfma_f32_16x16x32_bf16 v[112:115], v[166:169], v[174:177], v[112:115]
	v_mfma_f32_16x16x32_bf16 v[100:103], v[158:161], v[182:185], v[100:103]
	v_mfma_f32_16x16x32_bf16 v[96:99], v[166:169], v[182:185], v[96:99]
	v_mfma_f32_16x16x32_bf16 v[84:87], v[158:161], v[190:193], v[84:87]
	v_mfma_f32_16x16x32_bf16 v[80:83], v[166:169], v[190:193], v[80:83]
	v_mfma_f32_16x16x32_bf16 v[68:71], v[158:161], v[198:201], v[68:71]
	v_mfma_f32_16x16x32_bf16 v[64:67], v[166:169], v[198:201], v[64:67]
	v_mfma_f32_16x16x32_bf16 v[116:119], v[162:165], v[178:181], v[116:119]
	v_mfma_f32_16x16x32_bf16 v[112:115], v[170:173], v[178:181], v[112:115]
	v_mfma_f32_16x16x32_bf16 v[100:103], v[162:165], v[186:189], v[100:103]
	v_mfma_f32_16x16x32_bf16 v[96:99], v[170:173], v[186:189], v[96:99]
	v_mfma_f32_16x16x32_bf16 v[84:87], v[162:165], v[194:197], v[84:87]
	v_mfma_f32_16x16x32_bf16 v[80:83], v[170:173], v[194:197], v[80:83]
	v_mfma_f32_16x16x32_bf16 v[68:71], v[162:165], v[202:205], v[68:71]
	v_mfma_f32_16x16x32_bf16 v[64:67], v[170:173], v[202:205], v[64:67]
	s_barrier
	s_setprio 0
	s_mov_b32 m0, s79
	v_lshl_add_u64 v[206:207], s[64:65], 0, v[132:133]
	ds_read_b128 v[174:177], v139 offset:16384
	ds_read_b128 v[178:181], v139 offset:17408
	ds_read_b128 v[182:185], v139 offset:18432
	ds_read_b128 v[186:189], v139 offset:19456
	ds_read_b128 v[190:193], v139 offset:20480
	ds_read_b128 v[194:197], v139 offset:21504
	ds_read_b128 v[198:201], v139 offset:22528
	ds_read_b128 v[202:205], v139 offset:23552
	global_load_lds_dwordx4 v[206:207], off
	v_lshl_add_u64 v[208:209], s[64:65], 0, v[128:129]
	s_mov_b32 m0, s80
	s_nop 0
	global_load_lds_dwordx4 v[208:209], off
	s_mov_b32 m0, s81
	v_lshl_add_u64 v[212:213], s[62:63], 0, v[130:131]
	global_load_lds_dwordx4 v132, s[66:67]
	s_mov_b32 m0, s84
	s_nop 0
	global_load_lds_dwordx4 v128, s[66:67]
	v_lshl_add_u64 v[210:211], s[62:63], 0, v[134:135]
	s_mov_b32 m0, s13
	s_nop 0
	global_load_lds_dwordx4 v[210:211], off
	s_mov_b32 m0, s52
	s_nop 0
	global_load_lds_dwordx4 v[212:213], off
	s_waitcnt vmcnt(8)
	s_waitcnt lgkmcnt(0)
	s_setprio 1
	s_barrier
; #define PG8_STAGE(bufoff, gbase, voff) do { _Pragma("unroll") for (int _i = 0; _i < 2; ++_i) \
;         __builtin_amdgcn_global_load_lds((const unsigned*)((const char*)(gbase) + (voff)[_i]), (LAS unsigned*)(lds + (bufoff) + ldsw + _i * 8192), 16, 0, 0); } while (0)
; #define PG8_LDA(dst, b, h) do { _Pragma("unroll") for (int m = 0; m < 4; ++m) _Pragma("unroll") for (int k = 0; k < 2; ++k) dst[m][k] = *(const LAS bf16x8*)(lds + PG8_SA(b, h) + aoff + m * 2048 + k * 1024); } while (0)
; #define PG8_LDB(dst, b, h) do { _Pragma("unroll") for (int n = 0; n < 2; ++n) _Pragma("unroll") for (int k = 0; k < 2; ++k) dst[n][k] = *(const LAS bf16x8*)(lds + PG8_SB(b, h) + boff + n * 2048 + k * 1024); } while (0)
; #define PG8_MMA(ai, bj, At, Bt) do { __builtin_amdgcn_s_setprio(1); _Pragma("unroll") for (int m = 0; m < 4; ++m) _Pragma("unroll") for (int n = 0; n < 2; ++n) _Pragma("unroll") for (int k = 0; k < 2; ++k) \
;         acc[ai][bj][m][n] = __builtin_amdgcn_mfma_f32_16x16x32_bf16(Bt[n][k], At[m][k], acc[ai][bj][m][n], 0, 0, 0); __builtin_amdgcn_s_setprio(0); } while (0)
; #define PG8_WAIT_V(n) asm volatile("s_waitcnt vmcnt(" #n ")" ::: "memory")
; #define PG8_WAIT_L(n) asm volatile("s_waitcnt lgkmcnt(" #n ")" ::: "memory")
; #define PG8_BAR __builtin_amdgcn_s_barrier()
; #define PG8_SCHED __builtin_amdgcn_sched_barrier(0)
; template <class Epi, class Sched, bool ALIGN_EPI>
; __device__ __forceinline__ void gemm_phase(LAS unsigned char* lds, const Gemm g, const Sched& S, const Epi& E, const int wid) {
;     ...
;             PG8_WAIT_V(8); PG8_WAIT_L(0); PG8_BAR; PG8_MMA(0, 0, At, B0); PG8_MMA(0, 1, At, B1); PG8_BAR; PG8_SCHED;
;             PG8_LDA(At, 0, 1); PG8_STAGE(PG8_SB(0, 0), b2, voffB); PG8_STAGE(PG8_SB(0, 1), b2 + hstepB, voffB); PG8_STAGE(PG8_SA(0, 0), a2, voffA);
;             PG8_WAIT_V(8); PG8_WAIT_L(0); PG8_BAR; PG8_MMA(1, 0, At, B0); PG8_MMA(1, 1, At, B1); PG8_BAR; PG8_SCHED;
;             PG8_LDB(B0, 1, 0); PG8_LDB(B1, 1, 1); PG8_SCHED; PG8_LDA(At, 1, 0); PG8_STAGE(PG8_SA(0, 1), a2 + hstepA, voffA);
;             PG8_WAIT_V(8); PG8_WAIT_L(0); PG8_BAR; PG8_MMA(0, 0, At, B0); PG8_MMA(0, 1, At, B1); PG8_BAR; PG8_SCHED;
	v_mfma_f32_16x16x32_bf16 v[60:63], v[142:145], v[174:177], v[60:63]
	v_mfma_f32_16x16x32_bf16 v[56:59], v[150:153], v[174:177], v[56:59]
	v_mfma_f32_16x16x32_bf16 v[44:47], v[142:145], v[182:185], v[44:47]
	v_mfma_f32_16x16x32_bf16 v[40:43], v[150:153], v[182:185], v[40:43]
	v_mfma_f32_16x16x32_bf16 v[28:31], v[142:145], v[190:193], v[28:31]
	v_mfma_f32_16x16x32_bf16 v[24:27], v[150:153], v[190:193], v[24:27]
	v_mfma_f32_16x16x32_bf16 v[12:15], v[142:145], v[198:201], v[12:15]
	v_mfma_f32_16x16x32_bf16 v[8:11], v[150:153], v[198:201], v[8:11]
	v_mfma_f32_16x16x32_bf16 v[60:63], v[146:149], v[178:181], v[60:63]
	v_mfma_f32_16x16x32_bf16 v[56:59], v[154:157], v[178:181], v[56:59]
	v_mfma_f32_16x16x32_bf16 v[44:47], v[146:149], v[186:189], v[44:47]
	v_mfma_f32_16x16x32_bf16 v[40:43], v[154:157], v[186:189], v[40:43]
	v_mfma_f32_16x16x32_bf16 v[28:31], v[146:149], v[194:197], v[28:31]
	v_mfma_f32_16x16x32_bf16 v[24:27], v[154:157], v[194:197], v[24:27]
	v_mfma_f32_16x16x32_bf16 v[12:15], v[146:149], v[202:205], v[12:15]
	v_mfma_f32_16x16x32_bf16 v[8:11], v[154:157], v[202:205], v[8:11]
	v_mfma_f32_16x16x32_bf16 v[52:55], v[158:161], v[174:177], v[52:55]
	v_mfma_f32_16x16x32_bf16 v[48:51], v[166:169], v[174:177], v[48:51]
	v_mfma_f32_16x16x32_bf16 v[36:39], v[158:161], v[182:185], v[36:39]
	v_mfma_f32_16x16x32_bf16 v[32:35], v[166:169], v[182:185], v[32:35]
	v_mfma_f32_16x16x32_bf16 v[20:23], v[158:161], v[190:193], v[20:23]
	v_mfma_f32_16x16x32_bf16 v[16:19], v[166:169], v[190:193], v[16:19]
	v_mfma_f32_16x16x32_bf16 v[4:7], v[158:161], v[198:201], v[4:7]
	v_mfma_f32_16x16x32_bf16 v[0:3], v[166:169], v[198:201], v[0:3]
	v_mfma_f32_16x16x32_bf16 v[52:55], v[162:165], v[178:181], v[52:55]
	v_mfma_f32_16x16x32_bf16 v[48:51], v[170:173], v[178:181], v[48:51]
	v_mfma_f32_16x16x32_bf16 v[36:39], v[162:165], v[186:189], v[36:39]
	v_mfma_f32_16x16x32_bf16 v[32:35], v[170:173], v[186:189], v[32:35]
	v_mfma_f32_16x16x32_bf16 v[20:23], v[162:165], v[194:197], v[20:23]
	v_mfma_f32_16x16x32_bf16 v[16:19], v[170:173], v[194:197], v[16:19]
	v_mfma_f32_16x16x32_bf16 v[4:7], v[162:165], v[202:205], v[4:7]
	v_mfma_f32_16x16x32_bf16 v[0:3], v[170:173], v[202:205], v[0:3]
	s_barrier
	s_setprio 0
	ds_read_b128 v[142:145], v140
	ds_read_b128 v[146:149], v140 offset:1024
	ds_read_b128 v[150:153], v140 offset:2048
	ds_read_b128 v[154:157], v140 offset:3072
	ds_read_b128 v[158:161], v141
	ds_read_b128 v[162:165], v141 offset:1024
	ds_read_b128 v[166:169], v141 offset:2048
	ds_read_b128 v[170:173], v141 offset:3072
	s_mov_b32 m0, s70
	ds_read_b128 v[174:177], v139 offset:32768
	ds_read_b128 v[178:181], v139 offset:33792
	ds_read_b128 v[182:185], v139 offset:34816
	ds_read_b128 v[186:189], v139 offset:35840
	ds_read_b128 v[190:193], v139 offset:36864
	ds_read_b128 v[194:197], v139 offset:37888
	ds_read_b128 v[198:201], v139 offset:38912
	ds_read_b128 v[202:205], v139 offset:39936
	global_load_lds_dwordx4 v134, s[60:61]
	s_mov_b32 m0, s71
	s_nop 0
	global_load_lds_dwordx4 v130, s[60:61]
	s_waitcnt vmcnt(8)
	s_waitcnt lgkmcnt(0)
	s_setprio 1
	s_barrier
	v_mfma_f32_16x16x32_bf16 v[124:127], v[142:145], v[174:177], v[124:127]
	v_mfma_f32_16x16x32_bf16 v[120:123], v[150:153], v[174:177], v[120:123]
	v_mfma_f32_16x16x32_bf16 v[108:111], v[142:145], v[182:185], v[108:111]
	v_mfma_f32_16x16x32_bf16 v[104:107], v[150:153], v[182:185], v[104:107]
	v_mfma_f32_16x16x32_bf16 v[92:95], v[142:145], v[190:193], v[92:95]
	v_mfma_f32_16x16x32_bf16 v[88:91], v[150:153], v[190:193], v[88:91]
	v_mfma_f32_16x16x32_bf16 v[76:79], v[142:145], v[198:201], v[76:79]
	v_mfma_f32_16x16x32_bf16 v[72:75], v[150:153], v[198:201], v[72:75]
	v_mfma_f32_16x16x32_bf16 v[124:127], v[146:149], v[178:181], v[124:127]
	v_mfma_f32_16x16x32_bf16 v[120:123], v[154:157], v[178:181], v[120:123]
	v_mfma_f32_16x16x32_bf16 v[108:111], v[146:149], v[186:189], v[108:111]
	v_mfma_f32_16x16x32_bf16 v[104:107], v[154:157], v[186:189], v[104:107]
	v_mfma_f32_16x16x32_bf16 v[92:95], v[146:149], v[194:197], v[92:95]
	v_mfma_f32_16x16x32_bf16 v[88:91], v[154:157], v[194:197], v[88:91]
	v_mfma_f32_16x16x32_bf16 v[76:79], v[146:149], v[202:205], v[76:79]
	v_mfma_f32_16x16x32_bf16 v[72:75], v[154:157], v[202:205], v[72:75]
	v_mfma_f32_16x16x32_bf16 v[116:119], v[158:161], v[174:177], v[116:119]
	v_mfma_f32_16x16x32_bf16 v[112:115], v[166:169], v[174:177], v[112:115]
	v_mfma_f32_16x16x32_bf16 v[100:103], v[158:161], v[182:185], v[100:103]
	v_mfma_f32_16x16x32_bf16 v[96:99], v[166:169], v[182:185], v[96:99]
	v_mfma_f32_16x16x32_bf16 v[84:87], v[158:161], v[190:193], v[84:87]
	v_mfma_f32_16x16x32_bf16 v[80:83], v[166:169], v[190:193], v[80:83]
	v_mfma_f32_16x16x32_bf16 v[68:71], v[158:161], v[198:201], v[68:71]
	v_mfma_f32_16x16x32_bf16 v[64:67], v[166:169], v[198:201], v[64:67]
	v_mfma_f32_16x16x32_bf16 v[116:119], v[162:165], v[178:181], v[116:119]
	v_mfma_f32_16x16x32_bf16 v[112:115], v[170:173], v[178:181], v[112:115]
	v_mfma_f32_16x16x32_bf16 v[100:103], v[162:165], v[186:189], v[100:103]
	v_mfma_f32_16x16x32_bf16 v[96:99], v[170:173], v[186:189], v[96:99]
	v_mfma_f32_16x16x32_bf16 v[84:87], v[162:165], v[194:197], v[84:87]
	v_mfma_f32_16x16x32_bf16 v[80:83], v[170:173], v[194:197], v[80:83]
	v_mfma_f32_16x16x32_bf16 v[68:71], v[162:165], v[202:205], v[68:71]
	v_mfma_f32_16x16x32_bf16 v[64:67], v[170:173], v[202:205], v[64:67]
	s_barrier
; #define PG8_STAGE(bufoff, gbase, voff) do { _Pragma("unroll") for (int _i = 0; _i < 2; ++_i) \
;         __builtin_amdgcn_global_load_lds((const unsigned*)((const char*)(gbase) + (voff)[_i]), (LAS unsigned*)(lds + (bufoff) + ldsw + _i * 8192), 16, 0, 0); } while (0)
; #define PG8_LDA(dst, b, h) do { _Pragma("unroll") for (int m = 0; m < 4; ++m) _Pragma("unroll") for (int k = 0; k < 2; ++k) dst[m][k] = *(const LAS bf16x8*)(lds + PG8_SA(b, h) + aoff + m * 2048 + k * 1024); } while (0)
; #define PG8_MMA(ai, bj, At, Bt) do { __builtin_amdgcn_s_setprio(1); _Pragma("unroll") for (int m = 0; m < 4; ++m) _Pragma("unroll") for (int n = 0; n < 2; ++n) _Pragma("unroll") for (int k = 0; k < 2; ++k) \
;         acc[ai][bj][m][n] = __builtin_amdgcn_mfma_f32_16x16x32_bf16(Bt[n][k], At[m][k], acc[ai][bj][m][n], 0, 0, 0); __builtin_amdgcn_s_setprio(0); } while (0)
; #define PG8_WAIT_V(n) asm volatile("s_waitcnt vmcnt(" #n ")" ::: "memory")
; #define PG8_WAIT_L(n) asm volatile("s_waitcnt lgkmcnt(" #n ")" ::: "memory")
; #define PG8_BAR __builtin_amdgcn_s_barrier()
; #define PG8_SCHED __builtin_amdgcn_sched_barrier(0)
; template <class Epi, class Sched, bool ALIGN_EPI>
; __device__ __forceinline__ void gemm_phase(LAS unsigned char* lds, const Gemm g, const Sched& S, const Epi& E, const int wid) {
;     ...
;             PG8_WAIT_V(8); PG8_WAIT_L(0); PG8_BAR; PG8_MMA(0, 0, At, B0); PG8_MMA(0, 1, At, B1); PG8_BAR; PG8_SCHED;
;             PG8_LDA(At, 1, 1); PG8_STAGE(PG8_SB(1, 0), b3, voffB); PG8_STAGE(PG8_SB(1, 1), b3 + hstepB, voffB); PG8_STAGE(PG8_SA(1, 0), a3, voffA);
;             PG8_WAIT_V(8); PG8_WAIT_L(0); PG8_BAR; PG8_MMA(1, 0, At, B0); PG8_MMA(1, 1, At, B1); PG8_BAR; PG8_SCHED;
;         }
;         if constexpr (ALIGN_EPI) { if (wr == 0) PG8_BAR; }
	s_setprio 0
	s_mov_b32 m0, s85
	v_lshl_add_u64 v[206:207], v[206:207], 0, s[18:19]
	ds_read_b128 v[174:177], v139 offset:49152
	ds_read_b128 v[178:181], v139 offset:50176
	ds_read_b128 v[182:185], v139 offset:51200
	ds_read_b128 v[186:189], v139 offset:52224
	ds_read_b128 v[190:193], v139 offset:53248
	ds_read_b128 v[194:197], v139 offset:54272
	ds_read_b128 v[198:201], v139 offset:55296
	ds_read_b128 v[202:205], v139 offset:56320
	global_load_lds_dwordx4 v[206:207], off
	v_lshl_add_u64 v[206:207], v[208:209], 0, s[18:19]
	s_mov_b32 m0, s86
	s_nop 0
	global_load_lds_dwordx4 v[206:207], off
	s_mov_b32 m0, s87
	s_nop 0
	global_load_lds_dwordx4 v132, s[58:59]
	s_mov_b32 m0, s89
	s_nop 0
	global_load_lds_dwordx4 v128, s[58:59]
	v_lshl_add_u64 v[206:207], v[210:211], 0, s[18:19]
	s_mov_b32 m0, s75
	s_nop 0
	global_load_lds_dwordx4 v[206:207], off
	v_lshl_add_u64 v[206:207], v[212:213], 0, s[18:19]
	s_mov_b32 m0, s76
	s_nop 0
	global_load_lds_dwordx4 v[206:207], off
	s_waitcnt vmcnt(8)
	s_waitcnt lgkmcnt(0)
	s_setprio 1
	s_barrier
	v_mfma_f32_16x16x32_bf16 v[60:63], v[142:145], v[174:177], v[60:63]
	v_mfma_f32_16x16x32_bf16 v[56:59], v[150:153], v[174:177], v[56:59]
	v_mfma_f32_16x16x32_bf16 v[44:47], v[142:145], v[182:185], v[44:47]
	v_mfma_f32_16x16x32_bf16 v[40:43], v[150:153], v[182:185], v[40:43]
	v_mfma_f32_16x16x32_bf16 v[28:31], v[142:145], v[190:193], v[28:31]
	v_mfma_f32_16x16x32_bf16 v[24:27], v[150:153], v[190:193], v[24:27]
	v_mfma_f32_16x16x32_bf16 v[12:15], v[142:145], v[198:201], v[12:15]
	v_mfma_f32_16x16x32_bf16 v[8:11], v[150:153], v[198:201], v[8:11]
	v_mfma_f32_16x16x32_bf16 v[60:63], v[146:149], v[178:181], v[60:63]
	v_mfma_f32_16x16x32_bf16 v[56:59], v[154:157], v[178:181], v[56:59]
	v_mfma_f32_16x16x32_bf16 v[44:47], v[146:149], v[186:189], v[44:47]
	v_mfma_f32_16x16x32_bf16 v[40:43], v[154:157], v[186:189], v[40:43]
	v_mfma_f32_16x16x32_bf16 v[28:31], v[146:149], v[194:197], v[28:31]
	v_mfma_f32_16x16x32_bf16 v[24:27], v[154:157], v[194:197], v[24:27]
	v_mfma_f32_16x16x32_bf16 v[12:15], v[146:149], v[202:205], v[12:15]
	v_mfma_f32_16x16x32_bf16 v[8:11], v[154:157], v[202:205], v[8:11]
	v_mfma_f32_16x16x32_bf16 v[52:55], v[158:161], v[174:177], v[52:55]
	v_mfma_f32_16x16x32_bf16 v[48:51], v[166:169], v[174:177], v[48:51]
	v_mfma_f32_16x16x32_bf16 v[36:39], v[158:161], v[182:185], v[36:39]
	v_mfma_f32_16x16x32_bf16 v[32:35], v[166:169], v[182:185], v[32:35]
	v_mfma_f32_16x16x32_bf16 v[20:23], v[158:161], v[190:193], v[20:23]
	v_mfma_f32_16x16x32_bf16 v[16:19], v[166:169], v[190:193], v[16:19]
	v_mfma_f32_16x16x32_bf16 v[4:7], v[158:161], v[198:201], v[4:7]
	v_mfma_f32_16x16x32_bf16 v[0:3], v[166:169], v[198:201], v[0:3]
	v_mfma_f32_16x16x32_bf16 v[52:55], v[162:165], v[178:181], v[52:55]
	v_mfma_f32_16x16x32_bf16 v[48:51], v[170:173], v[178:181], v[48:51]
	v_mfma_f32_16x16x32_bf16 v[36:39], v[162:165], v[186:189], v[36:39]
	v_mfma_f32_16x16x32_bf16 v[32:35], v[170:173], v[186:189], v[32:35]
	v_mfma_f32_16x16x32_bf16 v[20:23], v[162:165], v[194:197], v[20:23]
	v_mfma_f32_16x16x32_bf16 v[16:19], v[170:173], v[194:197], v[16:19]
	v_mfma_f32_16x16x32_bf16 v[4:7], v[162:165], v[202:205], v[4:7]
	v_mfma_f32_16x16x32_bf16 v[0:3], v[170:173], v[202:205], v[0:3]
	s_barrier
	s_setprio 0
	s_andn2_b64 vcc, exec, s[56:57]
	s_mov_b64 s[58:59], -1
	s_mov_b64 s[56:57], 0
	s_mov_b64 s[60:61], 0x100
	s_cbranch_vccz .LBB0_243
	s_and_b64 vcc, exec, s[28:29]
	s_cbranch_vccz .LBB0_246
	s_barrier

; #define PG8_STAGE(bufoff, gbase, voff) do { _Pragma("unroll") for (int _i = 0; _i < 2; ++_i) \
;         __builtin_amdgcn_global_load_lds((const unsigned*)((const char*)(gbase) + (voff)[_i]), (LAS unsigned*)(lds + (bufoff) + ldsw + _i * 8192), 16, 0, 0); } while (0)
; #define PG8_LDA(dst, b, h) do { _Pragma("unroll") for (int m = 0; m < 4; ++m) _Pragma("unroll") for (int k = 0; k < 2; ++k) dst[m][k] = *(const LAS bf16x8*)(lds + PG8_SA(b, h) + aoff + m * 2048 + k * 1024); } while (0)
; #define PG8_LDB(dst, b, h) do { _Pragma("unroll") for (int n = 0; n < 2; ++n) _Pragma("unroll") for (int k = 0; k < 2; ++k) dst[n][k] = *(const LAS bf16x8*)(lds + PG8_SB(b, h) + boff + n * 2048 + k * 1024); } while (0)
; #define PG8_MMA(ai, bj, At, Bt) do { __builtin_amdgcn_s_setprio(1); _Pragma("unroll") for (int m = 0; m < 4; ++m) _Pragma("unroll") for (int n = 0; n < 2; ++n) _Pragma("unroll") for (int k = 0; k < 2; ++k) \
;         acc[ai][bj][m][n] = __builtin_amdgcn_mfma_f32_16x16x32_bf16(Bt[n][k], At[m][k], acc[ai][bj][m][n], 0, 0, 0); __builtin_amdgcn_s_setprio(0); } while (0)
; #define PG8_WAIT_V(n) asm volatile("s_waitcnt vmcnt(" #n ")" ::: "memory")
; #define PG8_WAIT_L(n) asm volatile("s_waitcnt lgkmcnt(" #n ")" ::: "memory")
; #define PG8_BAR __builtin_amdgcn_s_barrier()
; #define PG8_SCHED __builtin_amdgcn_sched_barrier(0)
; template <class Epi, class Sched, bool ALIGN_EPI>
; __device__ __forceinline__ void gemm_phase(LAS unsigned char* lds, const Gemm g, const Sched& S, const Epi& E, const int wid) {
;     ...
;             const char* a1 = cA + (size_t)(t + 1) * kstepA;
;             const char* a2 = last ? nA : cA + (size_t)(t + 2) * kstepA; const char* b2 = last ? nB : cB + (size_t)(t + 2) * kstep;
;             const char* a3 = a2 + kstepA; const char* b3 = b2 + kstep;
;             PG8_LDB(B0, 0, 0); PG8_LDB(B1, 0, 1); PG8_SCHED; PG8_LDA(At, 0, 0); PG8_STAGE(PG8_SA(1, 1), a1 + hstepA, voffA);
;             PG8_WAIT_V(8); PG8_WAIT_L(0); PG8_BAR; PG8_MMA(0, 0, At, B0); PG8_MMA(0, 1, At, B1); PG8_BAR; PG8_SCHED;
;             PG8_LDA(At, 0, 1); PG8_STAGE(PG8_SB(0, 0), b2, voffB); PG8_STAGE(PG8_SB(0, 1), b2 + hstepB, voffB); PG8_STAGE(PG8_SA(0, 0), a2, voffA);
;             PG8_WAIT_V(8); PG8_WAIT_L(0); PG8_BAR; PG8_MMA(1, 0, At, B0); PG8_MMA(1, 1, At, B1); PG8_BAR; PG8_SCHED;
.LBB0_282:
	ds_read_b128 v[40:43], v153
	ds_read_b128 v[44:47], v153 offset:1024
	ds_read_b128 v[156:159], v153 offset:2048
	ds_read_b128 v[160:163], v153 offset:3072
	ds_read_b128 v[164:167], v154
	ds_read_b128 v[168:171], v154 offset:1024
	ds_read_b128 v[172:175], v154 offset:2048
	ds_read_b128 v[176:179], v154 offset:3072
	s_add_u32 s24, s22, 0x100
	s_addc_u32 s25, s23, 0
	s_cmp_eq_u32 s68, 2
	s_cselect_b32 s55, s19, s25
	s_cselect_b32 s54, s18, s24
	s_cselect_b32 s27, s21, s67
	s_cselect_b32 s26, s20, s13
	s_mov_b32 m0, s63
	v_lshl_add_u64 v[212:213], s[22:23], 0, v[146:147]
	ds_read_b128 v[180:183], v155
	ds_read_b128 v[184:187], v155 offset:1024
	ds_read_b128 v[188:191], v155 offset:2048
	ds_read_b128 v[192:195], v155 offset:3072
	ds_read_b128 v[196:199], v155 offset:4096
	ds_read_b128 v[200:203], v155 offset:5120
	ds_read_b128 v[204:207], v155 offset:6144
	ds_read_b128 v[208:211], v155 offset:7168
	global_load_lds_dwordx4 v[212:213], off
	v_lshl_add_u64 v[212:213], s[22:23], 0, v[148:149]
	s_mov_b32 m0, s64
	s_nop 0
	global_load_lds_dwordx4 v[212:213], off
	s_waitcnt vmcnt(8)
	s_waitcnt lgkmcnt(0)
	s_setprio 1
	s_barrier
	v_mfma_f32_16x16x32_bf16 v[132:135], v[40:43], v[180:183], v[132:135]
	v_mfma_f32_16x16x32_bf16 v[128:131], v[156:159], v[180:183], v[128:131]
	v_mfma_f32_16x16x32_bf16 v[116:119], v[40:43], v[188:191], v[116:119]
	v_mfma_f32_16x16x32_bf16 v[112:115], v[156:159], v[188:191], v[112:115]
	v_mfma_f32_16x16x32_bf16 v[100:103], v[40:43], v[196:199], v[100:103]
	v_mfma_f32_16x16x32_bf16 v[96:99], v[156:159], v[196:199], v[96:99]
	v_mfma_f32_16x16x32_bf16 v[84:87], v[40:43], v[204:207], v[84:87]
	v_mfma_f32_16x16x32_bf16 v[80:83], v[156:159], v[204:207], v[80:83]
	v_mfma_f32_16x16x32_bf16 v[132:135], v[44:47], v[184:187], v[132:135]
	v_mfma_f32_16x16x32_bf16 v[128:131], v[160:163], v[184:187], v[128:131]
	v_mfma_f32_16x16x32_bf16 v[116:119], v[44:47], v[192:195], v[116:119]
	v_mfma_f32_16x16x32_bf16 v[112:115], v[160:163], v[192:195], v[112:115]
	v_mfma_f32_16x16x32_bf16 v[100:103], v[44:47], v[200:203], v[100:103]
	v_mfma_f32_16x16x32_bf16 v[96:99], v[160:163], v[200:203], v[96:99]
	v_mfma_f32_16x16x32_bf16 v[84:87], v[44:47], v[208:211], v[84:87]
	v_mfma_f32_16x16x32_bf16 v[80:83], v[160:163], v[208:211], v[80:83]
	v_mfma_f32_16x16x32_bf16 v[124:127], v[164:167], v[180:183], v[124:127]
	v_mfma_f32_16x16x32_bf16 v[120:123], v[172:175], v[180:183], v[120:123]
	v_mfma_f32_16x16x32_bf16 v[108:111], v[164:167], v[188:191], v[108:111]
	v_mfma_f32_16x16x32_bf16 v[104:107], v[172:175], v[188:191], v[104:107]
	v_mfma_f32_16x16x32_bf16 v[92:95], v[164:167], v[196:199], v[92:95]
	v_mfma_f32_16x16x32_bf16 v[88:91], v[172:175], v[196:199], v[88:91]
	v_mfma_f32_16x16x32_bf16 v[76:79], v[164:167], v[204:207], v[76:79]
	v_mfma_f32_16x16x32_bf16 v[72:75], v[172:175], v[204:207], v[72:75]
	v_mfma_f32_16x16x32_bf16 v[124:127], v[168:171], v[184:187], v[124:127]
	v_mfma_f32_16x16x32_bf16 v[120:123], v[176:179], v[184:187], v[120:123]
	v_mfma_f32_16x16x32_bf16 v[108:111], v[168:171], v[192:195], v[108:111]
	v_mfma_f32_16x16x32_bf16 v[104:107], v[176:179], v[192:195], v[104:107]
	v_mfma_f32_16x16x32_bf16 v[92:95], v[168:171], v[200:203], v[92:95]
	v_mfma_f32_16x16x32_bf16 v[88:91], v[176:179], v[200:203], v[88:91]
	v_mfma_f32_16x16x32_bf16 v[76:79], v[168:171], v[208:211], v[76:79]
	v_mfma_f32_16x16x32_bf16 v[72:75], v[176:179], v[208:211], v[72:75]
	s_barrier
	s_setprio 0
	s_add_i32 s22, s61, s3
	v_lshl_add_u64 v[212:213], s[26:27], 0, v[140:141]
	s_mov_b32 m0, s22
	ds_read_b128 v[180:183], v155 offset:16384
	ds_read_b128 v[184:187], v155 offset:17408
	ds_read_b128 v[188:191], v155 offset:18432
	ds_read_b128 v[192:195], v155 offset:19456
	ds_read_b128 v[196:199], v155 offset:20480
	ds_read_b128 v[200:203], v155 offset:21504
	ds_read_b128 v[204:207], v155 offset:22528
	ds_read_b128 v[208:211], v155 offset:23552
	global_load_lds_dwordx4 v[212:213], off
	s_add_i32 m0, s22, 0x2000
	s_add_u32 s22, s26, 0x6000
	v_lshl_add_u64 v[214:215], s[26:27], 0, v[136:137]
	s_addc_u32 s23, s27, 0
	s_add_i32 s38, s62, s3
	global_load_lds_dwordx4 v[214:215], off
	s_mov_b32 m0, s38
	v_lshl_add_u64 v[218:219], s[54:55], 0, v[138:139]
	global_load_lds_dwordx4 v140, s[22:23]
	s_add_i32 m0, s38, 0x2000
	s_nop 0
	global_load_lds_dwordx4 v136, s[22:23]
	v_lshl_add_u64 v[216:217], s[54:55], 0, v[142:143]
	s_mov_b32 m0, s52
	s_nop 0
	global_load_lds_dwordx4 v[216:217], off
	s_mov_b32 m0, s53
	s_nop 0
	global_load_lds_dwordx4 v[218:219], off
	s_waitcnt vmcnt(8)
	s_waitcnt lgkmcnt(0)
	s_setprio 1
	s_barrier
; #define PG8_STAGE(bufoff, gbase, voff) do { _Pragma("unroll") for (int _i = 0; _i < 2; ++_i) \
;         __builtin_amdgcn_global_load_lds((const unsigned*)((const char*)(gbase) + (voff)[_i]), (LAS unsigned*)(lds + (bufoff) + ldsw + _i * 8192), 16, 0, 0); } while (0)
; #define PG8_LDA(dst, b, h) do { _Pragma("unroll") for (int m = 0; m < 4; ++m) _Pragma("unroll") for (int k = 0; k < 2; ++k) dst[m][k] = *(const LAS bf16x8*)(lds + PG8_SA(b, h) + aoff + m * 2048 + k * 1024); } while (0)
; #define PG8_LDB(dst, b, h) do { _Pragma("unroll") for (int n = 0; n < 2; ++n) _Pragma("unroll") for (int k = 0; k < 2; ++k) dst[n][k] = *(const LAS bf16x8*)(lds + PG8_SB(b, h) + boff + n * 2048 + k * 1024); } while (0)
; #define PG8_MMA(ai, bj, At, Bt) do { __builtin_amdgcn_s_setprio(1); _Pragma("unroll") for (int m = 0; m < 4; ++m) _Pragma("unroll") for (int n = 0; n < 2; ++n) _Pragma("unroll") for (int k = 0; k < 2; ++k) \
;         acc[ai][bj][m][n] = __builtin_amdgcn_mfma_f32_16x16x32_bf16(Bt[n][k], At[m][k], acc[ai][bj][m][n], 0, 0, 0); __builtin_amdgcn_s_setprio(0); } while (0)
; #define PG8_WAIT_V(n) asm volatile("s_waitcnt vmcnt(" #n ")" ::: "memory")
; template <class Epi, class Sched, bool ALIGN_EPI>
; __device__ __forceinline__ void gemm_phase(LAS unsigned char* lds, const Gemm g, const Sched& S, const Epi& E, const int wid) {
;     ...
;             PG8_LDB(B0, 0, 0); PG8_LDB(B1, 0, 1); PG8_SCHED; PG8_LDA(At, 0, 0); PG8_STAGE(PG8_SA(1, 1), a1 + hstepA, voffA);
;             PG8_WAIT_V(8); PG8_WAIT_L(0); PG8_BAR; PG8_MMA(0, 0, At, B0); PG8_MMA(0, 1, At, B1); PG8_BAR; PG8_SCHED;
;             PG8_LDA(At, 0, 1); PG8_STAGE(PG8_SB(0, 0), b2, voffB); PG8_STAGE(PG8_SB(0, 1), b2 + hstepB, voffB); PG8_STAGE(PG8_SA(0, 0), a2, voffA);
;             PG8_WAIT_V(8); PG8_WAIT_L(0); PG8_BAR; PG8_MMA(1, 0, At, B0); PG8_MMA(1, 1, At, B1); PG8_BAR; PG8_SCHED;
;             PG8_LDB(B0, 1, 0); PG8_LDB(B1, 1, 1); PG8_SCHED; PG8_LDA(At, 1, 0); PG8_STAGE(PG8_SA(0, 1), a2 + hstepA, voffA);
;             PG8_WAIT_V(8); PG8_WAIT_L(0); PG8_BAR; PG8_MMA(0, 0, At, B0); PG8_MMA(0, 1, At, B1); PG8_BAR; PG8_SCHED;
;             PG8_LDA(At, 1, 1); PG8_STAGE(PG8_SB(1, 0), b3, voffB); PG8_STAGE(PG8_SB(1, 1), b3 + hstepB, voffB); PG8_STAGE(PG8_SA(1, 0), a3, voffA);
;             PG8_WAIT_V(8); PG8_WAIT_L(0); PG8_BAR; PG8_MMA(1, 0, At, B0); PG8_MMA(1, 1, At, B1); PG8_BAR; PG8_SCHED;
	v_mfma_f32_16x16x32_bf16 v[68:71], v[40:43], v[180:183], v[68:71]
	v_mfma_f32_16x16x32_bf16 v[64:67], v[156:159], v[180:183], v[64:67]
	v_mfma_f32_16x16x32_bf16 v[52:55], v[40:43], v[188:191], v[52:55]
	v_mfma_f32_16x16x32_bf16 v[48:51], v[156:159], v[188:191], v[48:51]
	v_mfma_f32_16x16x32_bf16 v[28:31], v[40:43], v[196:199], v[28:31]
	v_mfma_f32_16x16x32_bf16 v[24:27], v[156:159], v[196:199], v[24:27]
	v_mfma_f32_16x16x32_bf16 v[12:15], v[40:43], v[204:207], v[12:15]
	v_mfma_f32_16x16x32_bf16 v[8:11], v[156:159], v[204:207], v[8:11]
	v_mfma_f32_16x16x32_bf16 v[68:71], v[44:47], v[184:187], v[68:71]
	v_mfma_f32_16x16x32_bf16 v[64:67], v[160:163], v[184:187], v[64:67]
	v_mfma_f32_16x16x32_bf16 v[52:55], v[44:47], v[192:195], v[52:55]
	v_mfma_f32_16x16x32_bf16 v[48:51], v[160:163], v[192:195], v[48:51]
	v_mfma_f32_16x16x32_bf16 v[28:31], v[44:47], v[200:203], v[28:31]
	v_mfma_f32_16x16x32_bf16 v[24:27], v[160:163], v[200:203], v[24:27]
	v_mfma_f32_16x16x32_bf16 v[12:15], v[44:47], v[208:211], v[12:15]
	v_mfma_f32_16x16x32_bf16 v[8:11], v[160:163], v[208:211], v[8:11]
	v_mfma_f32_16x16x32_bf16 v[36:39], v[164:167], v[188:191], v[36:39]
	v_mfma_f32_16x16x32_bf16 v[32:35], v[172:175], v[188:191], v[32:35]
	v_mfma_f32_16x16x32_bf16 v[20:23], v[164:167], v[196:199], v[20:23]
	v_mfma_f32_16x16x32_bf16 v[16:19], v[172:175], v[196:199], v[16:19]
	v_mfma_f32_16x16x32_bf16 v[4:7], v[164:167], v[204:207], v[4:7]
	v_mfma_f32_16x16x32_bf16 v[0:3], v[172:175], v[204:207], v[0:3]
	v_mfma_f32_16x16x32_bf16 v[40:43], v[164:167], v[180:183], v[60:63]
	v_mfma_f32_16x16x32_bf16 v[44:47], v[172:175], v[180:183], v[56:59]
	v_mfma_f32_16x16x32_bf16 v[36:39], v[168:171], v[192:195], v[36:39]
	v_mfma_f32_16x16x32_bf16 v[32:35], v[176:179], v[192:195], v[32:35]
	v_mfma_f32_16x16x32_bf16 v[20:23], v[168:171], v[200:203], v[20:23]
	v_mfma_f32_16x16x32_bf16 v[16:19], v[176:179], v[200:203], v[16:19]
	v_mfma_f32_16x16x32_bf16 v[4:7], v[168:171], v[208:211], v[4:7]
	v_mfma_f32_16x16x32_bf16 v[0:3], v[176:179], v[208:211], v[0:3]
	v_mfma_f32_16x16x32_bf16 v[40:43], v[168:171], v[184:187], v[40:43]
	v_mfma_f32_16x16x32_bf16 v[44:47], v[176:179], v[184:187], v[44:47]
	s_barrier
	s_setprio 0
	s_add_i32 s38, 0, 0x18000
	s_add_i32 s39, 0, 0x1c000
	v_add_u32_e32 v160, s38, v150
	v_add_u32_e32 v176, s39, v150
	ds_read_b128 v[56:59], v160
	ds_read_b128 v[60:63], v160 offset:1024
	ds_read_b128 v[156:159], v160 offset:2048
	ds_read_b128 v[160:163], v160 offset:3072
	ds_read_b128 v[164:167], v176
	ds_read_b128 v[168:171], v176 offset:1024
	ds_read_b128 v[172:175], v176 offset:2048
	ds_read_b128 v[176:179], v176 offset:3072
	s_add_u32 s22, s54, 0x18000
	s_addc_u32 s23, s55, 0
	s_mov_b32 m0, s56
	ds_read_b128 v[180:183], v155 offset:32768
	ds_read_b128 v[184:187], v155 offset:33792
	ds_read_b128 v[188:191], v155 offset:34816
	ds_read_b128 v[192:195], v155 offset:35840
	ds_read_b128 v[196:199], v155 offset:36864
	ds_read_b128 v[200:203], v155 offset:37888
	ds_read_b128 v[204:207], v155 offset:38912
	ds_read_b128 v[208:211], v155 offset:39936
	global_load_lds_dwordx4 v142, s[22:23]
	s_mov_b32 m0, s57
	s_nop 0
	global_load_lds_dwordx4 v138, s[22:23]
	s_waitcnt vmcnt(8)
	s_waitcnt lgkmcnt(0)
	s_setprio 1
	s_barrier
	v_mfma_f32_16x16x32_bf16 v[132:135], v[56:59], v[180:183], v[132:135]
	v_mfma_f32_16x16x32_bf16 v[128:131], v[156:159], v[180:183], v[128:131]
	v_mfma_f32_16x16x32_bf16 v[116:119], v[56:59], v[188:191], v[116:119]
	v_mfma_f32_16x16x32_bf16 v[112:115], v[156:159], v[188:191], v[112:115]
	v_mfma_f32_16x16x32_bf16 v[100:103], v[56:59], v[196:199], v[100:103]
	v_mfma_f32_16x16x32_bf16 v[96:99], v[156:159], v[196:199], v[96:99]
	v_mfma_f32_16x16x32_bf16 v[84:87], v[56:59], v[204:207], v[84:87]
	v_mfma_f32_16x16x32_bf16 v[80:83], v[156:159], v[204:207], v[80:83]
	v_mfma_f32_16x16x32_bf16 v[132:135], v[60:63], v[184:187], v[132:135]
	v_mfma_f32_16x16x32_bf16 v[128:131], v[160:163], v[184:187], v[128:131]
	v_mfma_f32_16x16x32_bf16 v[116:119], v[60:63], v[192:195], v[116:119]
	v_mfma_f32_16x16x32_bf16 v[112:115], v[160:163], v[192:195], v[112:115]
	v_mfma_f32_16x16x32_bf16 v[100:103], v[60:63], v[200:203], v[100:103]
	v_mfma_f32_16x16x32_bf16 v[96:99], v[160:163], v[200:203], v[96:99]
	v_mfma_f32_16x16x32_bf16 v[84:87], v[60:63], v[208:211], v[84:87]
	v_mfma_f32_16x16x32_bf16 v[80:83], v[160:163], v[208:211], v[80:83]
	v_mfma_f32_16x16x32_bf16 v[124:127], v[164:167], v[180:183], v[124:127]
	v_mfma_f32_16x16x32_bf16 v[120:123], v[172:175], v[180:183], v[120:123]
	v_mfma_f32_16x16x32_bf16 v[108:111], v[164:167], v[188:191], v[108:111]
	v_mfma_f32_16x16x32_bf16 v[104:107], v[172:175], v[188:191], v[104:107]
	v_mfma_f32_16x16x32_bf16 v[92:95], v[164:167], v[196:199], v[92:95]
	v_mfma_f32_16x16x32_bf16 v[88:91], v[172:175], v[196:199], v[88:91]
	v_mfma_f32_16x16x32_bf16 v[76:79], v[164:167], v[204:207], v[76:79]
	v_mfma_f32_16x16x32_bf16 v[72:75], v[172:175], v[204:207], v[72:75]
	v_mfma_f32_16x16x32_bf16 v[124:127], v[168:171], v[184:187], v[124:127]
	v_mfma_f32_16x16x32_bf16 v[120:123], v[176:179], v[184:187], v[120:123]
	v_mfma_f32_16x16x32_bf16 v[108:111], v[168:171], v[192:195], v[108:111]
	v_mfma_f32_16x16x32_bf16 v[104:107], v[176:179], v[192:195], v[104:107]
	v_mfma_f32_16x16x32_bf16 v[92:95], v[168:171], v[200:203], v[92:95]
	v_mfma_f32_16x16x32_bf16 v[88:91], v[176:179], v[200:203], v[88:91]
	v_mfma_f32_16x16x32_bf16 v[76:79], v[168:171], v[208:211], v[76:79]
	v_mfma_f32_16x16x32_bf16 v[72:75], v[176:179], v[208:211], v[72:75]
	s_barrier
; #define PG8_STAGE(bufoff, gbase, voff) do { _Pragma("unroll") for (int _i = 0; _i < 2; ++_i) \
;         __builtin_amdgcn_global_load_lds((const unsigned*)((const char*)(gbase) + (voff)[_i]), (LAS unsigned*)(lds + (bufoff) + ldsw + _i * 8192), 16, 0, 0); } while (0)
; #define PG8_LDA(dst, b, h) do { _Pragma("unroll") for (int m = 0; m < 4; ++m) _Pragma("unroll") for (int k = 0; k < 2; ++k) dst[m][k] = *(const LAS bf16x8*)(lds + PG8_SA(b, h) + aoff + m * 2048 + k * 1024); } while (0)
; #define PG8_LDB(dst, b, h) do { _Pragma("unroll") for (int n = 0; n < 2; ++n) _Pragma("unroll") for (int k = 0; k < 2; ++k) dst[n][k] = *(const LAS bf16x8*)(lds + PG8_SB(b, h) + boff + n * 2048 + k * 1024); } while (0)
; #define PG8_MMA(ai, bj, At, Bt) do { __builtin_amdgcn_s_setprio(1); _Pragma("unroll") for (int m = 0; m < 4; ++m) _Pragma("unroll") for (int n = 0; n < 2; ++n) _Pragma("unroll") for (int k = 0; k < 2; ++k) \
;         acc[ai][bj][m][n] = __builtin_amdgcn_mfma_f32_16x16x32_bf16(Bt[n][k], At[m][k], acc[ai][bj][m][n], 0, 0, 0); __builtin_amdgcn_s_setprio(0); } while (0)
; #define PG8_WAIT_V(n) asm volatile("s_waitcnt vmcnt(" #n ")" ::: "memory")
; #define PG8_WAIT_L(n) asm volatile("s_waitcnt lgkmcnt(" #n ")" ::: "memory")
; #define PG8_BAR __builtin_amdgcn_s_barrier()
; #define PG8_SCHED __builtin_amdgcn_sched_barrier(0)
; template <class Epi, class Sched, bool ALIGN_EPI>
; __device__ __forceinline__ void gemm_phase(LAS unsigned char* lds, const Gemm g, const Sched& S, const Epi& E, const int wid) {
;     ...
;             PG8_LDB(B0, 1, 0); PG8_LDB(B1, 1, 1); PG8_SCHED; PG8_LDA(At, 1, 0); PG8_STAGE(PG8_SA(0, 1), a2 + hstepA, voffA);
;             PG8_WAIT_V(8); PG8_WAIT_L(0); PG8_BAR; PG8_MMA(0, 0, At, B0); PG8_MMA(0, 1, At, B1); PG8_BAR; PG8_SCHED;
;             PG8_LDA(At, 1, 1); PG8_STAGE(PG8_SB(1, 0), b3, voffB); PG8_STAGE(PG8_SB(1, 1), b3 + hstepB, voffB); PG8_STAGE(PG8_SA(1, 0), a3, voffA);
;             PG8_WAIT_V(8); PG8_WAIT_L(0); PG8_BAR; PG8_MMA(1, 0, At, B0); PG8_MMA(1, 1, At, B1); PG8_BAR; PG8_SCHED;
;         }
;         if constexpr (ALIGN_EPI) { if (wr == 0) PG8_BAR; }
	s_setprio 0
	s_add_i32 s22, s38, s3
	v_lshl_add_u64 v[212:213], v[212:213], 0, s[16:17]
	s_mov_b32 m0, s22
	ds_read_b128 v[180:183], v155 offset:49152
	ds_read_b128 v[184:187], v155 offset:50176
	ds_read_b128 v[188:191], v155 offset:51200
	ds_read_b128 v[192:195], v155 offset:52224
	ds_read_b128 v[196:199], v155 offset:53248
	ds_read_b128 v[200:203], v155 offset:54272
	ds_read_b128 v[204:207], v155 offset:55296
	ds_read_b128 v[208:211], v155 offset:56320
	global_load_lds_dwordx4 v[212:213], off
	s_add_i32 m0, s22, 0x2000
	s_add_u32 s22, s26, 0x6080
	v_lshl_add_u64 v[212:213], v[214:215], 0, s[16:17]
	s_addc_u32 s23, s27, 0
	s_add_i32 s26, s39, s3
	global_load_lds_dwordx4 v[212:213], off
	s_mov_b32 m0, s26
	s_nop 0
	global_load_lds_dwordx4 v140, s[22:23]
	s_add_i32 m0, s26, 0x2000
	s_nop 0
	global_load_lds_dwordx4 v136, s[22:23]
	v_lshl_add_u64 v[212:213], v[216:217], 0, s[16:17]
	s_mov_b32 m0, s30
	s_nop 0
	global_load_lds_dwordx4 v[212:213], off
	v_lshl_add_u64 v[212:213], v[218:219], 0, s[16:17]
	s_mov_b32 m0, s31
	s_nop 0
	global_load_lds_dwordx4 v[212:213], off
	s_waitcnt vmcnt(8)
	s_waitcnt lgkmcnt(0)
	s_setprio 1
	s_barrier
	v_mfma_f32_16x16x32_bf16 v[68:71], v[56:59], v[180:183], v[68:71]
	v_mfma_f32_16x16x32_bf16 v[64:67], v[156:159], v[180:183], v[64:67]
	v_mfma_f32_16x16x32_bf16 v[52:55], v[56:59], v[188:191], v[52:55]
	v_mfma_f32_16x16x32_bf16 v[48:51], v[156:159], v[188:191], v[48:51]
	v_mfma_f32_16x16x32_bf16 v[28:31], v[56:59], v[196:199], v[28:31]
	v_mfma_f32_16x16x32_bf16 v[24:27], v[156:159], v[196:199], v[24:27]
	v_mfma_f32_16x16x32_bf16 v[12:15], v[56:59], v[204:207], v[12:15]
	v_mfma_f32_16x16x32_bf16 v[8:11], v[156:159], v[204:207], v[8:11]
	v_mfma_f32_16x16x32_bf16 v[68:71], v[60:63], v[184:187], v[68:71]
	v_mfma_f32_16x16x32_bf16 v[64:67], v[160:163], v[184:187], v[64:67]
	v_mfma_f32_16x16x32_bf16 v[52:55], v[60:63], v[192:195], v[52:55]
	v_mfma_f32_16x16x32_bf16 v[48:51], v[160:163], v[192:195], v[48:51]
	v_mfma_f32_16x16x32_bf16 v[28:31], v[60:63], v[200:203], v[28:31]
	v_mfma_f32_16x16x32_bf16 v[24:27], v[160:163], v[200:203], v[24:27]
	v_mfma_f32_16x16x32_bf16 v[12:15], v[60:63], v[208:211], v[12:15]
	v_mfma_f32_16x16x32_bf16 v[8:11], v[160:163], v[208:211], v[8:11]
	v_mfma_f32_16x16x32_bf16 v[40:43], v[164:167], v[180:183], v[40:43]
	v_mfma_f32_16x16x32_bf16 v[60:63], v[168:171], v[184:187], v[40:43]
	v_mfma_f32_16x16x32_bf16 v[40:43], v[172:175], v[180:183], v[44:47]
	v_mfma_f32_16x16x32_bf16 v[36:39], v[164:167], v[188:191], v[36:39]
	v_mfma_f32_16x16x32_bf16 v[32:35], v[172:175], v[188:191], v[32:35]
	v_mfma_f32_16x16x32_bf16 v[20:23], v[164:167], v[196:199], v[20:23]
	v_mfma_f32_16x16x32_bf16 v[16:19], v[172:175], v[196:199], v[16:19]
	v_mfma_f32_16x16x32_bf16 v[4:7], v[164:167], v[204:207], v[4:7]
	v_mfma_f32_16x16x32_bf16 v[0:3], v[172:175], v[204:207], v[0:3]
	v_mfma_f32_16x16x32_bf16 v[56:59], v[176:179], v[184:187], v[40:43]
	v_mfma_f32_16x16x32_bf16 v[36:39], v[168:171], v[192:195], v[36:39]
	v_mfma_f32_16x16x32_bf16 v[32:35], v[176:179], v[192:195], v[32:35]
	v_mfma_f32_16x16x32_bf16 v[20:23], v[168:171], v[200:203], v[20:23]
	v_mfma_f32_16x16x32_bf16 v[16:19], v[176:179], v[200:203], v[16:19]
	v_mfma_f32_16x16x32_bf16 v[4:7], v[168:171], v[208:211], v[4:7]
	v_mfma_f32_16x16x32_bf16 v[0:3], v[176:179], v[208:211], v[0:3]
	s_barrier
	s_setprio 0
	s_add_i32 s68, s68, 2
	s_add_u32 s13, s13, 0x100
	s_addc_u32 s67, s67, 0
	s_cmp_gt_u32 s68, 3
	s_mov_b64 s[22:23], s[24:25]
	s_cbranch_scc0 .LBB0_282
	s_and_b64 vcc, exec, s[28:29]
	s_cbranch_vccz .LBB0_285
	s_barrier

; #define PG8_STAGE(bufoff, gbase, voff) do { _Pragma("unroll") for (int _i = 0; _i < 2; ++_i) \
;         __builtin_amdgcn_global_load_lds((const unsigned*)((const char*)(gbase) + (voff)[_i]), (LAS unsigned*)(lds + (bufoff) + ldsw + _i * 8192), 16, 0, 0); } while (0)
; #define PG8_LDA(dst, b, h) do { _Pragma("unroll") for (int m = 0; m < 4; ++m) _Pragma("unroll") for (int k = 0; k < 2; ++k) dst[m][k] = *(const LAS bf16x8*)(lds + PG8_SA(b, h) + aoff + m * 2048 + k * 1024); } while (0)
; #define PG8_LDB(dst, b, h) do { _Pragma("unroll") for (int n = 0; n < 2; ++n) _Pragma("unroll") for (int k = 0; k < 2; ++k) dst[n][k] = *(const LAS bf16x8*)(lds + PG8_SB(b, h) + boff + n * 2048 + k * 1024); } while (0)
; #define PG8_MMA(ai, bj, At, Bt) do { __builtin_amdgcn_s_setprio(1); _Pragma("unroll") for (int m = 0; m < 4; ++m) _Pragma("unroll") for (int n = 0; n < 2; ++n) _Pragma("unroll") for (int k = 0; k < 2; ++k) \
;         acc[ai][bj][m][n] = __builtin_amdgcn_mfma_f32_16x16x32_bf16(Bt[n][k], At[m][k], acc[ai][bj][m][n], 0, 0, 0); __builtin_amdgcn_s_setprio(0); } while (0)
; #define PG8_WAIT_V(n) asm volatile("s_waitcnt vmcnt(" #n ")" ::: "memory")
; #define PG8_WAIT_L(n) asm volatile("s_waitcnt lgkmcnt(" #n ")" ::: "memory")
; #define PG8_BAR __builtin_amdgcn_s_barrier()
; #define PG8_SCHED __builtin_amdgcn_sched_barrier(0)
; template <class Epi, class Sched, bool ALIGN_EPI>
; __device__ __forceinline__ void gemm_phase(LAS unsigned char* lds, const Gemm g, const Sched& S, const Epi& E, const int wid) {
;     ...
;             PG8_LDB(B0, 0, 0); PG8_LDB(B1, 0, 1); PG8_SCHED; PG8_LDA(At, 0, 0); PG8_STAGE(PG8_SA(1, 1), a1 + hstepA, voffA);
;             PG8_WAIT_V(8); PG8_WAIT_L(0); PG8_BAR; PG8_MMA(0, 0, At, B0); PG8_MMA(0, 1, At, B1); PG8_BAR; PG8_SCHED;
;             PG8_LDA(At, 0, 1); PG8_STAGE(PG8_SB(0, 0), b2, voffB); PG8_STAGE(PG8_SB(0, 1), b2 + hstepB, voffB); PG8_STAGE(PG8_SA(0, 0), a2, voffA);
;             PG8_WAIT_V(8); PG8_WAIT_L(0); PG8_BAR; PG8_MMA(1, 0, At, B0); PG8_MMA(1, 1, At, B1); PG8_BAR; PG8_SCHED;
;             PG8_LDB(B0, 1, 0); PG8_LDB(B1, 1, 1); PG8_SCHED; PG8_LDA(At, 1, 0); PG8_STAGE(PG8_SA(0, 1), a2 + hstepA, voffA);
;             PG8_WAIT_V(8); PG8_WAIT_L(0); PG8_BAR; PG8_MMA(0, 0, At, B0); PG8_MMA(0, 1, At, B1); PG8_BAR; PG8_SCHED;
.LBB0_499:
	ds_read_b128 v[150:153], v147
	ds_read_b128 v[154:157], v147 offset:1024
	ds_read_b128 v[158:161], v147 offset:2048
	ds_read_b128 v[162:165], v147 offset:3072
	ds_read_b128 v[166:169], v148
	ds_read_b128 v[170:173], v148 offset:1024
	ds_read_b128 v[174:177], v148 offset:2048
	ds_read_b128 v[178:181], v148 offset:3072
	s_add_u32 s38, s24, 0xfff80080
	s_addc_u32 s39, s25, -1
	s_cmp_eq_u32 s67, 28
	s_cselect_b32 s57, s19, s39
	s_cselect_b32 s56, s27, s38
	s_cselect_b32 s55, s17, s66
	s_cselect_b32 s54, s64, s65
	s_add_i32 m0, s46, 0xc000
	ds_read_b128 v[182:185], v149
	ds_read_b128 v[186:189], v149 offset:1024
	ds_read_b128 v[190:193], v149 offset:2048
	ds_read_b128 v[194:197], v149 offset:3072
	ds_read_b128 v[198:201], v149 offset:4096
	ds_read_b128 v[202:205], v149 offset:5120
	ds_read_b128 v[206:209], v149 offset:6144
	ds_read_b128 v[210:213], v149 offset:7168
	global_load_lds_dwordx4 v136, s[24:25]
	s_add_i32 m0, s46, 0xe000
	s_nop 0
	global_load_lds_dwordx4 v138, s[24:25]
	s_waitcnt vmcnt(8)
	s_waitcnt lgkmcnt(0)
	s_setprio 1
	s_barrier
	v_mfma_f32_16x16x32_bf16 v[124:127], v[150:153], v[182:185], v[124:127]
	v_mfma_f32_16x16x32_bf16 v[120:123], v[158:161], v[182:185], v[120:123]
	v_mfma_f32_16x16x32_bf16 v[108:111], v[150:153], v[190:193], v[108:111]
	v_mfma_f32_16x16x32_bf16 v[104:107], v[158:161], v[190:193], v[104:107]
	v_mfma_f32_16x16x32_bf16 v[92:95], v[150:153], v[198:201], v[92:95]
	v_mfma_f32_16x16x32_bf16 v[88:91], v[158:161], v[198:201], v[88:91]
	v_mfma_f32_16x16x32_bf16 v[76:79], v[150:153], v[206:209], v[76:79]
	v_mfma_f32_16x16x32_bf16 v[72:75], v[158:161], v[206:209], v[72:75]
	v_mfma_f32_16x16x32_bf16 v[124:127], v[154:157], v[186:189], v[124:127]
	v_mfma_f32_16x16x32_bf16 v[120:123], v[162:165], v[186:189], v[120:123]
	v_mfma_f32_16x16x32_bf16 v[108:111], v[154:157], v[194:197], v[108:111]
	v_mfma_f32_16x16x32_bf16 v[104:107], v[162:165], v[194:197], v[104:107]
	v_mfma_f32_16x16x32_bf16 v[92:95], v[154:157], v[202:205], v[92:95]
	v_mfma_f32_16x16x32_bf16 v[88:91], v[162:165], v[202:205], v[88:91]
	v_mfma_f32_16x16x32_bf16 v[76:79], v[154:157], v[210:213], v[76:79]
	v_mfma_f32_16x16x32_bf16 v[72:75], v[162:165], v[210:213], v[72:75]
	v_mfma_f32_16x16x32_bf16 v[116:119], v[166:169], v[182:185], v[116:119]
	v_mfma_f32_16x16x32_bf16 v[112:115], v[174:177], v[182:185], v[112:115]
	v_mfma_f32_16x16x32_bf16 v[100:103], v[166:169], v[190:193], v[100:103]
	v_mfma_f32_16x16x32_bf16 v[96:99], v[174:177], v[190:193], v[96:99]
	v_mfma_f32_16x16x32_bf16 v[84:87], v[166:169], v[198:201], v[84:87]
	v_mfma_f32_16x16x32_bf16 v[80:83], v[174:177], v[198:201], v[80:83]
	v_mfma_f32_16x16x32_bf16 v[68:71], v[166:169], v[206:209], v[68:71]
	v_mfma_f32_16x16x32_bf16 v[64:67], v[174:177], v[206:209], v[64:67]
	v_mfma_f32_16x16x32_bf16 v[116:119], v[170:173], v[186:189], v[116:119]
	v_mfma_f32_16x16x32_bf16 v[112:115], v[178:181], v[186:189], v[112:115]
	v_mfma_f32_16x16x32_bf16 v[100:103], v[170:173], v[194:197], v[100:103]
	v_mfma_f32_16x16x32_bf16 v[96:99], v[178:181], v[194:197], v[96:99]
	v_mfma_f32_16x16x32_bf16 v[84:87], v[170:173], v[202:205], v[84:87]
	v_mfma_f32_16x16x32_bf16 v[80:83], v[178:181], v[202:205], v[80:83]
	v_mfma_f32_16x16x32_bf16 v[68:71], v[170:173], v[210:213], v[68:71]
	v_mfma_f32_16x16x32_bf16 v[64:67], v[178:181], v[210:213], v[64:67]
	s_barrier
	s_setprio 0
	s_add_i32 s38, s43, s3
	s_mov_b32 m0, s38
	ds_read_b128 v[182:185], v149 offset:16384
	ds_read_b128 v[186:189], v149 offset:17408
	ds_read_b128 v[190:193], v149 offset:18432
	ds_read_b128 v[194:197], v149 offset:19456
	ds_read_b128 v[198:201], v149 offset:20480
	ds_read_b128 v[202:205], v149 offset:21504
	ds_read_b128 v[206:209], v149 offset:22528
	ds_read_b128 v[210:213], v149 offset:23552
	global_load_lds_dwordx4 v132, s[54:55]
	s_add_i32 m0, s38, 0x2000
	s_add_u32 s68, s54, 0x1000
	s_addc_u32 s69, s55, 0
	s_add_i32 s38, s63, s3
	global_load_lds_dwordx4 v128, s[54:55]
	s_mov_b32 m0, s38
	v_lshl_add_u64 v[216:217], s[56:57], 0, v[130:131]
	global_load_lds_dwordx4 v132, s[68:69]
	s_add_i32 m0, s38, 0x2000
	s_nop 0
	global_load_lds_dwordx4 v128, s[68:69]
	v_lshl_add_u64 v[214:215], s[56:57], 0, v[134:135]
	s_mov_b32 m0, s46
	s_nop 0
	global_load_lds_dwordx4 v[214:215], off
	s_mov_b32 m0, s47
	s_nop 0
	global_load_lds_dwordx4 v[216:217], off
	s_waitcnt vmcnt(8)
	s_waitcnt lgkmcnt(0)
	s_setprio 1
	s_barrier
	v_mfma_f32_16x16x32_bf16 v[60:63], v[150:153], v[182:185], v[60:63]
	v_mfma_f32_16x16x32_bf16 v[56:59], v[158:161], v[182:185], v[56:59]
	v_mfma_f32_16x16x32_bf16 v[44:47], v[150:153], v[190:193], v[44:47]
	v_mfma_f32_16x16x32_bf16 v[40:43], v[158:161], v[190:193], v[40:43]
	v_mfma_f32_16x16x32_bf16 v[28:31], v[150:153], v[198:201], v[28:31]
	v_mfma_f32_16x16x32_bf16 v[24:27], v[158:161], v[198:201], v[24:27]
	v_mfma_f32_16x16x32_bf16 v[12:15], v[150:153], v[206:209], v[12:15]
	v_mfma_f32_16x16x32_bf16 v[8:11], v[158:161], v[206:209], v[8:11]
	v_mfma_f32_16x16x32_bf16 v[60:63], v[154:157], v[186:189], v[60:63]
	v_mfma_f32_16x16x32_bf16 v[56:59], v[162:165], v[186:189], v[56:59]
	v_mfma_f32_16x16x32_bf16 v[44:47], v[154:157], v[194:197], v[44:47]
	v_mfma_f32_16x16x32_bf16 v[40:43], v[162:165], v[194:197], v[40:43]
	v_mfma_f32_16x16x32_bf16 v[28:31], v[154:157], v[202:205], v[28:31]
	v_mfma_f32_16x16x32_bf16 v[24:27], v[162:165], v[202:205], v[24:27]
	v_mfma_f32_16x16x32_bf16 v[12:15], v[154:157], v[210:213], v[12:15]
	v_mfma_f32_16x16x32_bf16 v[8:11], v[162:165], v[210:213], v[8:11]
	v_mfma_f32_16x16x32_bf16 v[52:55], v[166:169], v[182:185], v[52:55]
	v_mfma_f32_16x16x32_bf16 v[48:51], v[174:177], v[182:185], v[48:51]
	v_mfma_f32_16x16x32_bf16 v[36:39], v[166:169], v[190:193], v[36:39]
	v_mfma_f32_16x16x32_bf16 v[32:35], v[174:177], v[190:193], v[32:35]
	v_mfma_f32_16x16x32_bf16 v[20:23], v[166:169], v[198:201], v[20:23]
	v_mfma_f32_16x16x32_bf16 v[16:19], v[174:177], v[198:201], v[16:19]
	v_mfma_f32_16x16x32_bf16 v[4:7], v[166:169], v[206:209], v[4:7]
	v_mfma_f32_16x16x32_bf16 v[0:3], v[174:177], v[206:209], v[0:3]
	v_mfma_f32_16x16x32_bf16 v[52:55], v[170:173], v[186:189], v[52:55]
	v_mfma_f32_16x16x32_bf16 v[48:51], v[178:181], v[186:189], v[48:51]
	v_mfma_f32_16x16x32_bf16 v[36:39], v[170:173], v[194:197], v[36:39]
	v_mfma_f32_16x16x32_bf16 v[32:35], v[178:181], v[194:197], v[32:35]
	v_mfma_f32_16x16x32_bf16 v[20:23], v[170:173], v[202:205], v[20:23]
	v_mfma_f32_16x16x32_bf16 v[16:19], v[178:181], v[202:205], v[16:19]
	v_mfma_f32_16x16x32_bf16 v[4:7], v[170:173], v[210:213], v[4:7]
	v_mfma_f32_16x16x32_bf16 v[0:3], v[178:181], v[210:213], v[0:3]
	s_barrier
; #define PG8_STAGE(bufoff, gbase, voff) do { _Pragma("unroll") for (int _i = 0; _i < 2; ++_i) \
;         __builtin_amdgcn_global_load_lds((const unsigned*)((const char*)(gbase) + (voff)[_i]), (LAS unsigned*)(lds + (bufoff) + ldsw + _i * 8192), 16, 0, 0); } while (0)
; #define PG8_LDA(dst, b, h) do { _Pragma("unroll") for (int m = 0; m < 4; ++m) _Pragma("unroll") for (int k = 0; k < 2; ++k) dst[m][k] = *(const LAS bf16x8*)(lds + PG8_SA(b, h) + aoff + m * 2048 + k * 1024); } while (0)
; #define PG8_LDB(dst, b, h) do { _Pragma("unroll") for (int n = 0; n < 2; ++n) _Pragma("unroll") for (int k = 0; k < 2; ++k) dst[n][k] = *(const LAS bf16x8*)(lds + PG8_SB(b, h) + boff + n * 2048 + k * 1024); } while (0)
; #define PG8_MMA(ai, bj, At, Bt) do { __builtin_amdgcn_s_setprio(1); _Pragma("unroll") for (int m = 0; m < 4; ++m) _Pragma("unroll") for (int n = 0; n < 2; ++n) _Pragma("unroll") for (int k = 0; k < 2; ++k) \
;         acc[ai][bj][m][n] = __builtin_amdgcn_mfma_f32_16x16x32_bf16(Bt[n][k], At[m][k], acc[ai][bj][m][n], 0, 0, 0); __builtin_amdgcn_s_setprio(0); } while (0)
; #define PG8_WAIT_V(n) asm volatile("s_waitcnt vmcnt(" #n ")" ::: "memory")
; #define PG8_WAIT_L(n) asm volatile("s_waitcnt lgkmcnt(" #n ")" ::: "memory")
; #define PG8_BAR __builtin_amdgcn_s_barrier()
; #define PG8_SCHED __builtin_amdgcn_sched_barrier(0)
; template <class Epi, class Sched, bool ALIGN_EPI>
; __device__ __forceinline__ void gemm_phase(LAS unsigned char* lds, const Gemm g, const Sched& S, const Epi& E, const int wid) {
;     ...
;             PG8_LDB(B0, 1, 0); PG8_LDB(B1, 1, 1); PG8_SCHED; PG8_LDA(At, 1, 0); PG8_STAGE(PG8_SA(0, 1), a2 + hstepA, voffA);
;             PG8_WAIT_V(8); PG8_WAIT_L(0); PG8_BAR; PG8_MMA(0, 0, At, B0); PG8_MMA(0, 1, At, B1); PG8_BAR; PG8_SCHED;
;             PG8_LDA(At, 1, 1); PG8_STAGE(PG8_SB(1, 0), b3, voffB); PG8_STAGE(PG8_SB(1, 1), b3 + hstepB, voffB); PG8_STAGE(PG8_SA(1, 0), a3, voffA);
;             PG8_WAIT_V(8); PG8_WAIT_L(0); PG8_BAR; PG8_MMA(1, 0, At, B0); PG8_MMA(1, 1, At, B1); PG8_BAR; PG8_SCHED;
;         }
	s_setprio 0
	s_add_i32 s38, 0, 0x18000
	s_add_i32 s39, 0, 0x1c000
	v_add_u32_e32 v162, s38, v144
	v_add_u32_e32 v178, s39, v144
	ds_read_b128 v[150:153], v162
	ds_read_b128 v[154:157], v162 offset:1024
	ds_read_b128 v[158:161], v162 offset:2048
	ds_read_b128 v[162:165], v162 offset:3072
	ds_read_b128 v[166:169], v178
	ds_read_b128 v[170:173], v178 offset:1024
	ds_read_b128 v[174:177], v178 offset:2048
	ds_read_b128 v[178:181], v178 offset:3072
	s_add_u32 s56, s56, 0x80000
	s_addc_u32 s57, s57, 0
	s_mov_b32 m0, s52
	ds_read_b128 v[182:185], v149 offset:32768
	ds_read_b128 v[186:189], v149 offset:33792
	ds_read_b128 v[190:193], v149 offset:34816
	ds_read_b128 v[194:197], v149 offset:35840
	ds_read_b128 v[198:201], v149 offset:36864
	ds_read_b128 v[202:205], v149 offset:37888
	ds_read_b128 v[206:209], v149 offset:38912
	ds_read_b128 v[210:213], v149 offset:39936
	global_load_lds_dwordx4 v134, s[56:57]
	s_mov_b32 m0, s53
	s_nop 0
	global_load_lds_dwordx4 v130, s[56:57]
	s_waitcnt vmcnt(8)
	s_waitcnt lgkmcnt(0)
	s_setprio 1
	s_barrier
	v_mfma_f32_16x16x32_bf16 v[124:127], v[150:153], v[182:185], v[124:127]
	v_mfma_f32_16x16x32_bf16 v[120:123], v[158:161], v[182:185], v[120:123]
	v_mfma_f32_16x16x32_bf16 v[108:111], v[150:153], v[190:193], v[108:111]
	v_mfma_f32_16x16x32_bf16 v[104:107], v[158:161], v[190:193], v[104:107]
	v_mfma_f32_16x16x32_bf16 v[92:95], v[150:153], v[198:201], v[92:95]
	v_mfma_f32_16x16x32_bf16 v[88:91], v[158:161], v[198:201], v[88:91]
	v_mfma_f32_16x16x32_bf16 v[76:79], v[150:153], v[206:209], v[76:79]
	v_mfma_f32_16x16x32_bf16 v[72:75], v[158:161], v[206:209], v[72:75]
	v_mfma_f32_16x16x32_bf16 v[124:127], v[154:157], v[186:189], v[124:127]
	v_mfma_f32_16x16x32_bf16 v[120:123], v[162:165], v[186:189], v[120:123]
	v_mfma_f32_16x16x32_bf16 v[108:111], v[154:157], v[194:197], v[108:111]
	v_mfma_f32_16x16x32_bf16 v[104:107], v[162:165], v[194:197], v[104:107]
	v_mfma_f32_16x16x32_bf16 v[92:95], v[154:157], v[202:205], v[92:95]
	v_mfma_f32_16x16x32_bf16 v[88:91], v[162:165], v[202:205], v[88:91]
	v_mfma_f32_16x16x32_bf16 v[76:79], v[154:157], v[210:213], v[76:79]
	v_mfma_f32_16x16x32_bf16 v[72:75], v[162:165], v[210:213], v[72:75]
	v_mfma_f32_16x16x32_bf16 v[116:119], v[166:169], v[182:185], v[116:119]
	v_mfma_f32_16x16x32_bf16 v[112:115], v[174:177], v[182:185], v[112:115]
	v_mfma_f32_16x16x32_bf16 v[100:103], v[166:169], v[190:193], v[100:103]
	v_mfma_f32_16x16x32_bf16 v[96:99], v[174:177], v[190:193], v[96:99]
	v_mfma_f32_16x16x32_bf16 v[84:87], v[166:169], v[198:201], v[84:87]
	v_mfma_f32_16x16x32_bf16 v[80:83], v[174:177], v[198:201], v[80:83]
	v_mfma_f32_16x16x32_bf16 v[68:71], v[166:169], v[206:209], v[68:71]
	v_mfma_f32_16x16x32_bf16 v[64:67], v[174:177], v[206:209], v[64:67]
	v_mfma_f32_16x16x32_bf16 v[116:119], v[170:173], v[186:189], v[116:119]
	v_mfma_f32_16x16x32_bf16 v[112:115], v[178:181], v[186:189], v[112:115]
	v_mfma_f32_16x16x32_bf16 v[100:103], v[170:173], v[194:197], v[100:103]
	v_mfma_f32_16x16x32_bf16 v[96:99], v[178:181], v[194:197], v[96:99]
	v_mfma_f32_16x16x32_bf16 v[84:87], v[170:173], v[202:205], v[84:87]
	v_mfma_f32_16x16x32_bf16 v[80:83], v[178:181], v[202:205], v[80:83]
	v_mfma_f32_16x16x32_bf16 v[68:71], v[170:173], v[210:213], v[68:71]
	v_mfma_f32_16x16x32_bf16 v[64:67], v[178:181], v[210:213], v[64:67]
	s_barrier
	s_setprio 0
	s_add_u32 s56, s54, 0x8000
	s_addc_u32 s57, s55, 0
	s_add_i32 s38, s38, s3
	s_mov_b32 m0, s38
	ds_read_b128 v[182:185], v149 offset:49152
	ds_read_b128 v[186:189], v149 offset:50176
	ds_read_b128 v[190:193], v149 offset:51200
	ds_read_b128 v[194:197], v149 offset:52224
	ds_read_b128 v[198:201], v149 offset:53248
	ds_read_b128 v[202:205], v149 offset:54272
	ds_read_b128 v[206:209], v149 offset:55296
	ds_read_b128 v[210:213], v149 offset:56320
	global_load_lds_dwordx4 v132, s[56:57]
	s_add_i32 m0, s38, 0x2000
	s_add_u32 s54, s54, 0x9000
	s_addc_u32 s55, s55, 0
	s_add_i32 s38, s39, s3
	global_load_lds_dwordx4 v128, s[56:57]
	s_mov_b32 m0, s38
	v_lshl_add_u64 v[214:215], v[214:215], 0, s[12:13]
	global_load_lds_dwordx4 v132, s[54:55]
	s_add_i32 m0, s38, 0x2000
	s_nop 0
	global_load_lds_dwordx4 v128, s[54:55]
	s_mov_b32 m0, s61
	s_nop 0
	global_load_lds_dwordx4 v[214:215], off
	v_lshl_add_u64 v[214:215], v[216:217], 0, s[12:13]
	s_mov_b32 m0, s62
	s_nop 0
	global_load_lds_dwordx4 v[214:215], off
	s_waitcnt vmcnt(8)
	s_waitcnt lgkmcnt(0)
	s_setprio 1
	s_barrier
	v_mfma_f32_16x16x32_bf16 v[60:63], v[150:153], v[182:185], v[60:63]
	v_mfma_f32_16x16x32_bf16 v[56:59], v[158:161], v[182:185], v[56:59]
	v_mfma_f32_16x16x32_bf16 v[44:47], v[150:153], v[190:193], v[44:47]
	v_mfma_f32_16x16x32_bf16 v[40:43], v[158:161], v[190:193], v[40:43]
	v_mfma_f32_16x16x32_bf16 v[28:31], v[150:153], v[198:201], v[28:31]
	v_mfma_f32_16x16x32_bf16 v[24:27], v[158:161], v[198:201], v[24:27]
	v_mfma_f32_16x16x32_bf16 v[12:15], v[150:153], v[206:209], v[12:15]
	v_mfma_f32_16x16x32_bf16 v[8:11], v[158:161], v[206:209], v[8:11]
	v_mfma_f32_16x16x32_bf16 v[60:63], v[154:157], v[186:189], v[60:63]
	v_mfma_f32_16x16x32_bf16 v[56:59], v[162:165], v[186:189], v[56:59]
	v_mfma_f32_16x16x32_bf16 v[44:47], v[154:157], v[194:197], v[44:47]
	v_mfma_f32_16x16x32_bf16 v[40:43], v[162:165], v[194:197], v[40:43]
	v_mfma_f32_16x16x32_bf16 v[28:31], v[154:157], v[202:205], v[28:31]
	v_mfma_f32_16x16x32_bf16 v[24:27], v[162:165], v[202:205], v[24:27]
	v_mfma_f32_16x16x32_bf16 v[12:15], v[154:157], v[210:213], v[12:15]
	v_mfma_f32_16x16x32_bf16 v[8:11], v[162:165], v[210:213], v[8:11]
	v_mfma_f32_16x16x32_bf16 v[52:55], v[166:169], v[182:185], v[52:55]
	v_mfma_f32_16x16x32_bf16 v[48:51], v[174:177], v[182:185], v[48:51]
	v_mfma_f32_16x16x32_bf16 v[36:39], v[166:169], v[190:193], v[36:39]
	v_mfma_f32_16x16x32_bf16 v[32:35], v[174:177], v[190:193], v[32:35]
	v_mfma_f32_16x16x32_bf16 v[20:23], v[166:169], v[198:201], v[20:23]
	v_mfma_f32_16x16x32_bf16 v[16:19], v[174:177], v[198:201], v[16:19]
	v_mfma_f32_16x16x32_bf16 v[4:7], v[166:169], v[206:209], v[4:7]
	v_mfma_f32_16x16x32_bf16 v[0:3], v[174:177], v[206:209], v[0:3]
	v_mfma_f32_16x16x32_bf16 v[52:55], v[170:173], v[186:189], v[52:55]
	v_mfma_f32_16x16x32_bf16 v[48:51], v[178:181], v[186:189], v[48:51]
	v_mfma_f32_16x16x32_bf16 v[36:39], v[170:173], v[194:197], v[36:39]
	v_mfma_f32_16x16x32_bf16 v[32:35], v[178:181], v[194:197], v[32:35]
	v_mfma_f32_16x16x32_bf16 v[20:23], v[170:173], v[202:205], v[20:23]
	v_mfma_f32_16x16x32_bf16 v[16:19], v[178:181], v[202:205], v[16:19]
	v_mfma_f32_16x16x32_bf16 v[4:7], v[170:173], v[210:213], v[4:7]
	v_mfma_f32_16x16x32_bf16 v[0:3], v[178:181], v[210:213], v[0:3]
	s_barrier
	s_setprio 0
	s_add_i32 s67, s67, 2
	s_add_u32 s65, s65, 0x10000
	s_addc_u32 s66, s66, 0
	s_add_u32 s24, s24, 0x100
	s_addc_u32 s25, s25, 0
	s_cmp_gt_u32 s67, 29
	s_cbranch_scc0 .LBB0_499
	s_and_b64 vcc, exec, s[28:29]
	s_cbranch_vccz .LBB0_502
	s_barrier

; #define PG8_STAGE(bufoff, gbase, voff) do { _Pragma("unroll") for (int _i = 0; _i < 2; ++_i) \
;         __builtin_amdgcn_global_load_lds((const unsigned*)((const char*)(gbase) + (voff)[_i]), (LAS unsigned*)(lds + (bufoff) + ldsw + _i * 8192), 16, 0, 0); } while (0)
; #define PG8_LDA(dst, b, h) do { _Pragma("unroll") for (int m = 0; m < 4; ++m) _Pragma("unroll") for (int k = 0; k < 2; ++k) dst[m][k] = *(const LAS bf16x8*)(lds + PG8_SA(b, h) + aoff + m * 2048 + k * 1024); } while (0)
; #define PG8_LDB(dst, b, h) do { _Pragma("unroll") for (int n = 0; n < 2; ++n) _Pragma("unroll") for (int k = 0; k < 2; ++k) dst[n][k] = *(const LAS bf16x8*)(lds + PG8_SB(b, h) + boff + n * 2048 + k * 1024); } while (0)
; #define PG8_MMA(ai, bj, At, Bt) do { __builtin_amdgcn_s_setprio(1); _Pragma("unroll") for (int m = 0; m < 4; ++m) _Pragma("unroll") for (int n = 0; n < 2; ++n) _Pragma("unroll") for (int k = 0; k < 2; ++k) \
;         acc[ai][bj][m][n] = __builtin_amdgcn_mfma_f32_16x16x32_bf16(Bt[n][k], At[m][k], acc[ai][bj][m][n], 0, 0, 0); __builtin_amdgcn_s_setprio(0); } while (0)
; #define PG8_WAIT_V(n) asm volatile("s_waitcnt vmcnt(" #n ")" ::: "memory")
; #define PG8_WAIT_L(n) asm volatile("s_waitcnt lgkmcnt(" #n ")" ::: "memory")
; #define PG8_BAR __builtin_amdgcn_s_barrier()
; #define PG8_SCHED __builtin_amdgcn_sched_barrier(0)
; template <class Epi, class Sched, bool ALIGN_EPI>
; __device__ __forceinline__ void gemm_phase(LAS unsigned char* lds, const Gemm g, const Sched& S, const Epi& E, const int wid) {
;     ...
;             PG8_LDB(B0, 0, 0); PG8_LDB(B1, 0, 1); PG8_SCHED; PG8_LDA(At, 0, 0); PG8_STAGE(PG8_SA(1, 1), a1 + hstepA, voffA);
;             PG8_WAIT_V(8); PG8_WAIT_L(0); PG8_BAR; PG8_MMA(0, 0, At, B0); PG8_MMA(0, 1, At, B1); PG8_BAR; PG8_SCHED;
;             PG8_LDA(At, 0, 1); PG8_STAGE(PG8_SB(0, 0), b2, voffB); PG8_STAGE(PG8_SB(0, 1), b2 + hstepB, voffB); PG8_STAGE(PG8_SA(0, 0), a2, voffA);
;             PG8_WAIT_V(8); PG8_WAIT_L(0); PG8_BAR; PG8_MMA(1, 0, At, B0); PG8_MMA(1, 1, At, B1); PG8_BAR; PG8_SCHED;
;             PG8_LDB(B0, 1, 0); PG8_LDB(B1, 1, 1); PG8_SCHED; PG8_LDA(At, 1, 0); PG8_STAGE(PG8_SA(0, 1), a2 + hstepA, voffA);
;             PG8_WAIT_V(8); PG8_WAIT_L(0); PG8_BAR; PG8_MMA(0, 0, At, B0); PG8_MMA(0, 1, At, B1); PG8_BAR; PG8_SCHED;
.LBB0_579:
	ds_read_b128 v[120:123], v184
	ds_read_b128 v[132:135], v184 offset:1024
	ds_read_b128 v[136:139], v184 offset:2048
	ds_read_b128 v[140:143], v184 offset:3072
	ds_read_b128 v[144:147], v185
	ds_read_b128 v[148:151], v185 offset:1024
	ds_read_b128 v[152:155], v185 offset:2048
	ds_read_b128 v[176:179], v185 offset:3072
	s_add_u32 s38, s58, 0xfff00080
	s_addc_u32 s39, s59, -1
	s_cmp_eq_u32 s57, 60
	s_cselect_b32 s63, s23, s39
	s_cselect_b32 s62, s35, s38
	s_cselect_b32 s61, s21, s55
	s_cselect_b32 s60, s52, s53
	s_add_i32 m0, s4, 0xc000
	ds_read_b128 v[188:191], v186
	ds_read_b128 v[192:195], v186 offset:1024
	ds_read_b128 v[196:199], v186 offset:2048
	ds_read_b128 v[200:203], v186 offset:3072
	ds_read_b128 v[204:207], v186 offset:4096
	ds_read_b128 v[208:211], v186 offset:5120
	ds_read_b128 v[212:215], v186 offset:6144
	ds_read_b128 v[216:219], v186 offset:7168
	global_load_lds_dwordx4 v168, s[58:59]
	s_add_i32 m0, s4, 0xe000
	s_nop 0
	global_load_lds_dwordx4 v170, s[58:59]
	s_waitcnt vmcnt(8)
	s_waitcnt lgkmcnt(0)
	s_setprio 1
	s_barrier
	v_mfma_f32_16x16x32_bf16 v[128:131], v[120:123], v[188:191], v[128:131]
	v_mfma_f32_16x16x32_bf16 v[124:127], v[136:139], v[188:191], v[124:127]
	v_mfma_f32_16x16x32_bf16 v[108:111], v[120:123], v[196:199], v[108:111]
	v_mfma_f32_16x16x32_bf16 v[104:107], v[136:139], v[196:199], v[104:107]
	v_mfma_f32_16x16x32_bf16 v[92:95], v[120:123], v[204:207], v[92:95]
	v_mfma_f32_16x16x32_bf16 v[88:91], v[136:139], v[204:207], v[88:91]
	v_mfma_f32_16x16x32_bf16 v[76:79], v[120:123], v[212:215], v[76:79]
	v_mfma_f32_16x16x32_bf16 v[72:75], v[136:139], v[212:215], v[72:75]
	v_mfma_f32_16x16x32_bf16 v[128:131], v[132:135], v[192:195], v[128:131]
	v_mfma_f32_16x16x32_bf16 v[124:127], v[140:143], v[192:195], v[124:127]
	v_mfma_f32_16x16x32_bf16 v[108:111], v[132:135], v[200:203], v[108:111]
	v_mfma_f32_16x16x32_bf16 v[104:107], v[140:143], v[200:203], v[104:107]
	v_mfma_f32_16x16x32_bf16 v[92:95], v[132:135], v[208:211], v[92:95]
	v_mfma_f32_16x16x32_bf16 v[88:91], v[140:143], v[208:211], v[88:91]
	v_mfma_f32_16x16x32_bf16 v[76:79], v[132:135], v[216:219], v[76:79]
	v_mfma_f32_16x16x32_bf16 v[72:75], v[140:143], v[216:219], v[72:75]
	v_mfma_f32_16x16x32_bf16 v[116:119], v[144:147], v[188:191], v[116:119]
	v_mfma_f32_16x16x32_bf16 v[112:115], v[152:155], v[188:191], v[112:115]
	v_mfma_f32_16x16x32_bf16 v[100:103], v[144:147], v[196:199], v[100:103]
	v_mfma_f32_16x16x32_bf16 v[96:99], v[152:155], v[196:199], v[96:99]
	v_mfma_f32_16x16x32_bf16 v[84:87], v[144:147], v[204:207], v[84:87]
	v_mfma_f32_16x16x32_bf16 v[80:83], v[152:155], v[204:207], v[80:83]
	v_mfma_f32_16x16x32_bf16 v[68:71], v[144:147], v[212:215], v[68:71]
	v_mfma_f32_16x16x32_bf16 v[64:67], v[152:155], v[212:215], v[64:67]
	v_mfma_f32_16x16x32_bf16 v[116:119], v[148:151], v[192:195], v[116:119]
	v_mfma_f32_16x16x32_bf16 v[112:115], v[176:179], v[192:195], v[112:115]
	v_mfma_f32_16x16x32_bf16 v[100:103], v[148:151], v[200:203], v[100:103]
	v_mfma_f32_16x16x32_bf16 v[96:99], v[176:179], v[200:203], v[96:99]
	v_mfma_f32_16x16x32_bf16 v[84:87], v[148:151], v[208:211], v[84:87]
	v_mfma_f32_16x16x32_bf16 v[80:83], v[176:179], v[208:211], v[80:83]
	v_mfma_f32_16x16x32_bf16 v[68:71], v[148:151], v[216:219], v[68:71]
	v_mfma_f32_16x16x32_bf16 v[64:67], v[176:179], v[216:219], v[64:67]
	s_barrier
	s_setprio 0
	s_add_i32 s38, s66, s3
	s_mov_b32 m0, s38
	ds_read_b128 v[188:191], v186 offset:16384
	ds_read_b128 v[192:195], v186 offset:17408
	ds_read_b128 v[196:199], v186 offset:18432
	ds_read_b128 v[200:203], v186 offset:19456
	ds_read_b128 v[204:207], v186 offset:20480
	ds_read_b128 v[208:211], v186 offset:21504
	ds_read_b128 v[212:215], v186 offset:22528
	ds_read_b128 v[216:219], v186 offset:23552
	global_load_lds_dwordx4 v158, s[60:61]
	s_add_i32 m0, s38, 0x2000
	s_add_u32 s70, s60, 0x1000
	s_addc_u32 s71, s61, 0
	s_add_i32 s38, s67, s3
	global_load_lds_dwordx4 v162, s[60:61]
	s_mov_b32 m0, s38
	v_lshl_add_u64 v[220:221], s[62:63], 0, v[160:161]
	global_load_lds_dwordx4 v158, s[70:71]
	s_add_i32 m0, s38, 0x2000
	s_nop 0
	global_load_lds_dwordx4 v162, s[70:71]
	v_lshl_add_u64 v[180:181], s[62:63], 0, v[156:157]
	s_mov_b32 m0, s4
	s_nop 0
	global_load_lds_dwordx4 v[180:181], off
	s_mov_b32 m0, s5
	s_nop 0
	global_load_lds_dwordx4 v[220:221], off
	s_waitcnt vmcnt(8)
	s_waitcnt lgkmcnt(0)
	s_setprio 1
	s_barrier
	v_mfma_f32_16x16x32_bf16 v[60:63], v[120:123], v[188:191], v[60:63]
	v_mfma_f32_16x16x32_bf16 v[56:59], v[136:139], v[188:191], v[56:59]
	v_mfma_f32_16x16x32_bf16 v[44:47], v[120:123], v[196:199], v[44:47]
	v_mfma_f32_16x16x32_bf16 v[40:43], v[136:139], v[196:199], v[40:43]
	v_mfma_f32_16x16x32_bf16 v[28:31], v[120:123], v[204:207], v[28:31]
	v_mfma_f32_16x16x32_bf16 v[24:27], v[136:139], v[204:207], v[24:27]
	v_mfma_f32_16x16x32_bf16 v[12:15], v[120:123], v[212:215], v[12:15]
	v_mfma_f32_16x16x32_bf16 v[8:11], v[136:139], v[212:215], v[8:11]
	v_mfma_f32_16x16x32_bf16 v[60:63], v[132:135], v[192:195], v[60:63]
	v_mfma_f32_16x16x32_bf16 v[56:59], v[140:143], v[192:195], v[56:59]
	v_mfma_f32_16x16x32_bf16 v[44:47], v[132:135], v[200:203], v[44:47]
	v_mfma_f32_16x16x32_bf16 v[40:43], v[140:143], v[200:203], v[40:43]
	v_mfma_f32_16x16x32_bf16 v[28:31], v[132:135], v[208:211], v[28:31]
	v_mfma_f32_16x16x32_bf16 v[24:27], v[140:143], v[208:211], v[24:27]
	v_mfma_f32_16x16x32_bf16 v[12:15], v[132:135], v[216:219], v[12:15]
	v_mfma_f32_16x16x32_bf16 v[8:11], v[140:143], v[216:219], v[8:11]
	v_mfma_f32_16x16x32_bf16 v[52:55], v[144:147], v[188:191], v[52:55]
	v_mfma_f32_16x16x32_bf16 v[48:51], v[152:155], v[188:191], v[48:51]
	v_mfma_f32_16x16x32_bf16 v[36:39], v[144:147], v[196:199], v[36:39]
	v_mfma_f32_16x16x32_bf16 v[32:35], v[152:155], v[196:199], v[32:35]
	v_mfma_f32_16x16x32_bf16 v[20:23], v[144:147], v[204:207], v[20:23]
	v_mfma_f32_16x16x32_bf16 v[16:19], v[152:155], v[204:207], v[16:19]
	v_mfma_f32_16x16x32_bf16 v[4:7], v[144:147], v[212:215], v[4:7]
	v_mfma_f32_16x16x32_bf16 v[0:3], v[152:155], v[212:215], v[0:3]
	v_mfma_f32_16x16x32_bf16 v[52:55], v[148:151], v[192:195], v[52:55]
	v_mfma_f32_16x16x32_bf16 v[48:51], v[176:179], v[192:195], v[48:51]
	v_mfma_f32_16x16x32_bf16 v[36:39], v[148:151], v[200:203], v[36:39]
	v_mfma_f32_16x16x32_bf16 v[32:35], v[176:179], v[200:203], v[32:35]
	v_mfma_f32_16x16x32_bf16 v[20:23], v[148:151], v[208:211], v[20:23]
	v_mfma_f32_16x16x32_bf16 v[16:19], v[176:179], v[208:211], v[16:19]
	v_mfma_f32_16x16x32_bf16 v[4:7], v[148:151], v[216:219], v[4:7]
	v_mfma_f32_16x16x32_bf16 v[0:3], v[176:179], v[216:219], v[0:3]
	s_barrier
; #define PG8_STAGE(bufoff, gbase, voff) do { _Pragma("unroll") for (int _i = 0; _i < 2; ++_i) \
;         __builtin_amdgcn_global_load_lds((const unsigned*)((const char*)(gbase) + (voff)[_i]), (LAS unsigned*)(lds + (bufoff) + ldsw + _i * 8192), 16, 0, 0); } while (0)
; #define PG8_LDA(dst, b, h) do { _Pragma("unroll") for (int m = 0; m < 4; ++m) _Pragma("unroll") for (int k = 0; k < 2; ++k) dst[m][k] = *(const LAS bf16x8*)(lds + PG8_SA(b, h) + aoff + m * 2048 + k * 1024); } while (0)
; #define PG8_LDB(dst, b, h) do { _Pragma("unroll") for (int n = 0; n < 2; ++n) _Pragma("unroll") for (int k = 0; k < 2; ++k) dst[n][k] = *(const LAS bf16x8*)(lds + PG8_SB(b, h) + boff + n * 2048 + k * 1024); } while (0)
; #define PG8_MMA(ai, bj, At, Bt) do { __builtin_amdgcn_s_setprio(1); _Pragma("unroll") for (int m = 0; m < 4; ++m) _Pragma("unroll") for (int n = 0; n < 2; ++n) _Pragma("unroll") for (int k = 0; k < 2; ++k) \
;         acc[ai][bj][m][n] = __builtin_amdgcn_mfma_f32_16x16x32_bf16(Bt[n][k], At[m][k], acc[ai][bj][m][n], 0, 0, 0); __builtin_amdgcn_s_setprio(0); } while (0)
; #define PG8_WAIT_V(n) asm volatile("s_waitcnt vmcnt(" #n ")" ::: "memory")
; #define PG8_WAIT_L(n) asm volatile("s_waitcnt lgkmcnt(" #n ")" ::: "memory")
; #define PG8_BAR __builtin_amdgcn_s_barrier()
; #define PG8_SCHED __builtin_amdgcn_sched_barrier(0)
; template <class Epi, class Sched, bool ALIGN_EPI>
; __device__ __forceinline__ void gemm_phase(LAS unsigned char* lds, const Gemm g, const Sched& S, const Epi& E, const int wid) {
;     ...
;             PG8_LDB(B0, 1, 0); PG8_LDB(B1, 1, 1); PG8_SCHED; PG8_LDA(At, 1, 0); PG8_STAGE(PG8_SA(0, 1), a2 + hstepA, voffA);
;             PG8_WAIT_V(8); PG8_WAIT_L(0); PG8_BAR; PG8_MMA(0, 0, At, B0); PG8_MMA(0, 1, At, B1); PG8_BAR; PG8_SCHED;
;             PG8_LDA(At, 1, 1); PG8_STAGE(PG8_SB(1, 0), b3, voffB); PG8_STAGE(PG8_SB(1, 1), b3 + hstepB, voffB); PG8_STAGE(PG8_SA(1, 0), a3, voffA);
;             PG8_WAIT_V(8); PG8_WAIT_L(0); PG8_BAR; PG8_MMA(1, 0, At, B0); PG8_MMA(1, 1, At, B1); PG8_BAR; PG8_SCHED;
;         }
	s_setprio 0
	s_add_i32 s38, 0, 0x18000
	s_add_i32 s39, 0, 0x1c000
	v_add_u32_e32 v140, s38, v182
	v_add_u32_e32 v164, s39, v182
	ds_read_b128 v[120:123], v140
	ds_read_b128 v[132:135], v140 offset:1024
	ds_read_b128 v[136:139], v140 offset:2048
	ds_read_b128 v[140:143], v140 offset:3072
	ds_read_b128 v[144:147], v164
	ds_read_b128 v[148:151], v164 offset:1024
	ds_read_b128 v[152:155], v164 offset:2048
	ds_read_b128 v[176:179], v164 offset:3072
	s_add_u32 s62, s62, 0x100000
	s_addc_u32 s63, s63, 0
	s_mov_b32 m0, s44
	ds_read_b128 v[188:191], v186 offset:32768
	ds_read_b128 v[192:195], v186 offset:33792
	ds_read_b128 v[196:199], v186 offset:34816
	ds_read_b128 v[200:203], v186 offset:35840
	ds_read_b128 v[204:207], v186 offset:36864
	ds_read_b128 v[208:211], v186 offset:37888
	ds_read_b128 v[212:215], v186 offset:38912
	ds_read_b128 v[216:219], v186 offset:39936
	global_load_lds_dwordx4 v156, s[62:63]
	s_mov_b32 m0, s45
	s_nop 0
	global_load_lds_dwordx4 v160, s[62:63]
	s_waitcnt vmcnt(8)
	s_waitcnt lgkmcnt(0)
	s_setprio 1
	s_barrier
	v_mfma_f32_16x16x32_bf16 v[128:131], v[120:123], v[188:191], v[128:131]
	v_mfma_f32_16x16x32_bf16 v[124:127], v[136:139], v[188:191], v[124:127]
	v_mfma_f32_16x16x32_bf16 v[108:111], v[120:123], v[196:199], v[108:111]
	v_mfma_f32_16x16x32_bf16 v[104:107], v[136:139], v[196:199], v[104:107]
	v_mfma_f32_16x16x32_bf16 v[92:95], v[120:123], v[204:207], v[92:95]
	v_mfma_f32_16x16x32_bf16 v[88:91], v[136:139], v[204:207], v[88:91]
	v_mfma_f32_16x16x32_bf16 v[76:79], v[120:123], v[212:215], v[76:79]
	v_mfma_f32_16x16x32_bf16 v[72:75], v[136:139], v[212:215], v[72:75]
	v_mfma_f32_16x16x32_bf16 v[128:131], v[132:135], v[192:195], v[128:131]
	v_mfma_f32_16x16x32_bf16 v[124:127], v[140:143], v[192:195], v[124:127]
	v_mfma_f32_16x16x32_bf16 v[108:111], v[132:135], v[200:203], v[108:111]
	v_mfma_f32_16x16x32_bf16 v[104:107], v[140:143], v[200:203], v[104:107]
	v_mfma_f32_16x16x32_bf16 v[92:95], v[132:135], v[208:211], v[92:95]
	v_mfma_f32_16x16x32_bf16 v[88:91], v[140:143], v[208:211], v[88:91]
	v_mfma_f32_16x16x32_bf16 v[76:79], v[132:135], v[216:219], v[76:79]
	v_mfma_f32_16x16x32_bf16 v[72:75], v[140:143], v[216:219], v[72:75]
	v_mfma_f32_16x16x32_bf16 v[116:119], v[144:147], v[188:191], v[116:119]
	v_mfma_f32_16x16x32_bf16 v[112:115], v[152:155], v[188:191], v[112:115]
	v_mfma_f32_16x16x32_bf16 v[100:103], v[144:147], v[196:199], v[100:103]
	v_mfma_f32_16x16x32_bf16 v[96:99], v[152:155], v[196:199], v[96:99]
	v_mfma_f32_16x16x32_bf16 v[84:87], v[144:147], v[204:207], v[84:87]
	v_mfma_f32_16x16x32_bf16 v[80:83], v[152:155], v[204:207], v[80:83]
	v_mfma_f32_16x16x32_bf16 v[68:71], v[144:147], v[212:215], v[68:71]
	v_mfma_f32_16x16x32_bf16 v[64:67], v[152:155], v[212:215], v[64:67]
	v_mfma_f32_16x16x32_bf16 v[116:119], v[148:151], v[192:195], v[116:119]
	v_mfma_f32_16x16x32_bf16 v[112:115], v[176:179], v[192:195], v[112:115]
	v_mfma_f32_16x16x32_bf16 v[100:103], v[148:151], v[200:203], v[100:103]
	v_mfma_f32_16x16x32_bf16 v[96:99], v[176:179], v[200:203], v[96:99]
	v_mfma_f32_16x16x32_bf16 v[84:87], v[148:151], v[208:211], v[84:87]
	v_mfma_f32_16x16x32_bf16 v[80:83], v[176:179], v[208:211], v[80:83]
	v_mfma_f32_16x16x32_bf16 v[68:71], v[148:151], v[216:219], v[68:71]
	v_mfma_f32_16x16x32_bf16 v[64:67], v[176:179], v[216:219], v[64:67]
	s_barrier
	s_setprio 0
	s_add_u32 s62, s60, 0x8000
	s_addc_u32 s63, s61, 0
	s_add_i32 s38, s38, s3
	s_mov_b32 m0, s38
	ds_read_b128 v[188:191], v186 offset:49152
	ds_read_b128 v[192:195], v186 offset:50176
	ds_read_b128 v[196:199], v186 offset:51200
	ds_read_b128 v[200:203], v186 offset:52224
	ds_read_b128 v[204:207], v186 offset:53248
	ds_read_b128 v[208:211], v186 offset:54272
	ds_read_b128 v[212:215], v186 offset:55296
	ds_read_b128 v[216:219], v186 offset:56320
	global_load_lds_dwordx4 v158, s[62:63]
	s_add_i32 m0, s38, 0x2000
	s_add_u32 s60, s60, 0x9000
	s_addc_u32 s61, s61, 0
	s_add_i32 s38, s39, s3
	global_load_lds_dwordx4 v162, s[62:63]
	s_mov_b32 m0, s38
	v_lshl_add_u64 v[180:181], v[180:181], 0, s[16:17]
	global_load_lds_dwordx4 v158, s[60:61]
	s_add_i32 m0, s38, 0x2000
	s_nop 0
	global_load_lds_dwordx4 v162, s[60:61]
	s_mov_b32 m0, s64
	s_nop 0
	global_load_lds_dwordx4 v[180:181], off
	v_lshl_add_u64 v[180:181], v[220:221], 0, s[16:17]
	s_mov_b32 m0, s65
	s_nop 0
	global_load_lds_dwordx4 v[180:181], off
	s_waitcnt vmcnt(8)
	s_waitcnt lgkmcnt(0)
	s_setprio 1
	s_barrier
	v_mfma_f32_16x16x32_bf16 v[60:63], v[120:123], v[188:191], v[60:63]
	v_mfma_f32_16x16x32_bf16 v[56:59], v[136:139], v[188:191], v[56:59]
	v_mfma_f32_16x16x32_bf16 v[44:47], v[120:123], v[196:199], v[44:47]
	v_mfma_f32_16x16x32_bf16 v[40:43], v[136:139], v[196:199], v[40:43]
	v_mfma_f32_16x16x32_bf16 v[28:31], v[120:123], v[204:207], v[28:31]
	v_mfma_f32_16x16x32_bf16 v[24:27], v[136:139], v[204:207], v[24:27]
	v_mfma_f32_16x16x32_bf16 v[12:15], v[120:123], v[212:215], v[12:15]
	v_mfma_f32_16x16x32_bf16 v[8:11], v[136:139], v[212:215], v[8:11]
	v_mfma_f32_16x16x32_bf16 v[60:63], v[132:135], v[192:195], v[60:63]
	v_mfma_f32_16x16x32_bf16 v[56:59], v[140:143], v[192:195], v[56:59]
	v_mfma_f32_16x16x32_bf16 v[44:47], v[132:135], v[200:203], v[44:47]
	v_mfma_f32_16x16x32_bf16 v[40:43], v[140:143], v[200:203], v[40:43]
	v_mfma_f32_16x16x32_bf16 v[28:31], v[132:135], v[208:211], v[28:31]
	v_mfma_f32_16x16x32_bf16 v[24:27], v[140:143], v[208:211], v[24:27]
	v_mfma_f32_16x16x32_bf16 v[12:15], v[132:135], v[216:219], v[12:15]
	v_mfma_f32_16x16x32_bf16 v[8:11], v[140:143], v[216:219], v[8:11]
	v_mfma_f32_16x16x32_bf16 v[52:55], v[144:147], v[188:191], v[52:55]
	v_mfma_f32_16x16x32_bf16 v[48:51], v[152:155], v[188:191], v[48:51]
	v_mfma_f32_16x16x32_bf16 v[36:39], v[144:147], v[196:199], v[36:39]
	v_mfma_f32_16x16x32_bf16 v[32:35], v[152:155], v[196:199], v[32:35]
	v_mfma_f32_16x16x32_bf16 v[20:23], v[144:147], v[204:207], v[20:23]
	v_mfma_f32_16x16x32_bf16 v[16:19], v[152:155], v[204:207], v[16:19]
	v_mfma_f32_16x16x32_bf16 v[4:7], v[144:147], v[212:215], v[4:7]
	v_mfma_f32_16x16x32_bf16 v[0:3], v[152:155], v[212:215], v[0:3]
	v_mfma_f32_16x16x32_bf16 v[52:55], v[148:151], v[192:195], v[52:55]
	v_mfma_f32_16x16x32_bf16 v[48:51], v[176:179], v[192:195], v[48:51]
	v_mfma_f32_16x16x32_bf16 v[36:39], v[148:151], v[200:203], v[36:39]
	v_mfma_f32_16x16x32_bf16 v[32:35], v[176:179], v[200:203], v[32:35]
	v_mfma_f32_16x16x32_bf16 v[20:23], v[148:151], v[208:211], v[20:23]
	v_mfma_f32_16x16x32_bf16 v[16:19], v[176:179], v[208:211], v[16:19]
	v_mfma_f32_16x16x32_bf16 v[4:7], v[148:151], v[216:219], v[4:7]
	v_mfma_f32_16x16x32_bf16 v[0:3], v[176:179], v[216:219], v[0:3]
	s_barrier
	s_setprio 0
	s_add_i32 s57, s57, 2
	s_add_u32 s53, s53, 0x10000
	s_addc_u32 s55, s55, 0
	s_add_u32 s58, s58, 0x100
	s_addc_u32 s59, s59, 0
	s_cmp_gt_u32 s57, 61
	s_cbranch_scc0 .LBB0_579
	s_and_b64 vcc, exec, s[28:29]
	s_cbranch_vccz .LBB0_582
	s_barrier

; #define PG8_STAGE(bufoff, gbase, voff) do { _Pragma("unroll") for (int _i = 0; _i < 2; ++_i) \
;         __builtin_amdgcn_global_load_lds((const unsigned*)((const char*)(gbase) + (voff)[_i]), (LAS unsigned*)(lds + (bufoff) + ldsw + _i * 8192), 16, 0, 0); } while (0)
; #define PG8_LDA(dst, b, h) do { _Pragma("unroll") for (int m = 0; m < 4; ++m) _Pragma("unroll") for (int k = 0; k < 2; ++k) dst[m][k] = *(const LAS bf16x8*)(lds + PG8_SA(b, h) + aoff + m * 2048 + k * 1024); } while (0)
; #define PG8_LDB(dst, b, h) do { _Pragma("unroll") for (int n = 0; n < 2; ++n) _Pragma("unroll") for (int k = 0; k < 2; ++k) dst[n][k] = *(const LAS bf16x8*)(lds + PG8_SB(b, h) + boff + n * 2048 + k * 1024); } while (0)
; #define PG8_MMA(ai, bj, At, Bt) do { __builtin_amdgcn_s_setprio(1); _Pragma("unroll") for (int m = 0; m < 4; ++m) _Pragma("unroll") for (int n = 0; n < 2; ++n) _Pragma("unroll") for (int k = 0; k < 2; ++k) \
;         acc[ai][bj][m][n] = __builtin_amdgcn_mfma_f32_16x16x32_bf16(Bt[n][k], At[m][k], acc[ai][bj][m][n], 0, 0, 0); __builtin_amdgcn_s_setprio(0); } while (0)
; #define PG8_WAIT_V(n) asm volatile("s_waitcnt vmcnt(" #n ")" ::: "memory")
; #define PG8_WAIT_L(n) asm volatile("s_waitcnt lgkmcnt(" #n ")" ::: "memory")
; #define PG8_BAR __builtin_amdgcn_s_barrier()
; #define PG8_SCHED __builtin_amdgcn_sched_barrier(0)
; template <class Epi, class Sched, bool ALIGN_EPI>
; __device__ __forceinline__ void gemm_phase(LAS unsigned char* lds, const Gemm g, const Sched& S, const Epi& E, const int wid) {
;     ...
;             PG8_LDB(B0, 0, 0); PG8_LDB(B1, 0, 1); PG8_SCHED; PG8_LDA(At, 0, 0); PG8_STAGE(PG8_SA(1, 1), a1 + hstepA, voffA);
;             PG8_WAIT_V(8); PG8_WAIT_L(0); PG8_BAR; PG8_MMA(0, 0, At, B0); PG8_MMA(0, 1, At, B1); PG8_BAR; PG8_SCHED;
;             PG8_LDA(At, 0, 1); PG8_STAGE(PG8_SB(0, 0), b2, voffB); PG8_STAGE(PG8_SB(0, 1), b2 + hstepB, voffB); PG8_STAGE(PG8_SA(0, 0), a2, voffA);
;             PG8_WAIT_V(8); PG8_WAIT_L(0); PG8_BAR; PG8_MMA(1, 0, At, B0); PG8_MMA(1, 1, At, B1); PG8_BAR; PG8_SCHED;
;             PG8_LDB(B0, 1, 0); PG8_LDB(B1, 1, 1); PG8_SCHED; PG8_LDA(At, 1, 0); PG8_STAGE(PG8_SA(0, 1), a2 + hstepA, voffA);
;             PG8_WAIT_V(8); PG8_WAIT_L(0); PG8_BAR; PG8_MMA(0, 0, At, B0); PG8_MMA(0, 1, At, B1); PG8_BAR; PG8_SCHED;
.LBB0_687:
	s_add_u32 s38, s18, 0x4000
	s_addc_u32 s39, s19, 0
	s_and_b64 s[62:63], s[64:65], exec
	s_cselect_b32 s66, s35, s38
	s_cselect_b32 s67, s27, s39
	s_add_u32 s62, s66, 0x8000
	s_addc_u32 s63, s67, 0
	s_add_i32 s38, 0, 0x10000
	v_add_u32_e32 v138, s38, v160
	ds_read_b128 v[130:133], v138
	ds_read_b128 v[134:137], v138 offset:1024
	ds_read_b128 v[170:173], v138 offset:2048
	ds_read_b128 v[174:177], v138 offset:3072
	v_add_u32_e32 v138, s53, v160
	ds_read_b128 v[178:181], v138
	ds_read_b128 v[182:185], v138 offset:1024
	ds_read_b128 v[186:189], v138 offset:2048
	ds_read_b128 v[190:193], v138 offset:3072
	s_and_b64 s[64:65], s[64:65], exec
	s_cselect_b32 s65, s25, s70
	s_cselect_b32 s64, s61, s69
	s_add_i32 m0, s23, 0xc000
	ds_read_b128 v[194:197], v166
	ds_read_b128 v[198:201], v166 offset:1024
	ds_read_b128 v[202:205], v166 offset:2048
	ds_read_b128 v[206:209], v166 offset:3072
	ds_read_b128 v[210:213], v166 offset:4096
	ds_read_b128 v[214:217], v166 offset:5120
	ds_read_b128 v[218:221], v166 offset:6144
	ds_read_b128 v[222:225], v166 offset:7168
	global_load_lds_dwordx4 v150, s[18:19]
	s_add_i32 m0, s23, 0xe000
	s_nop 0
	global_load_lds_dwordx4 v152, s[18:19]
	s_waitcnt vmcnt(8)
	s_waitcnt lgkmcnt(0)
	s_setprio 1
	s_barrier
	v_mfma_f32_16x16x32_bf16 v[124:127], v[130:133], v[194:197], v[124:127]
	v_mfma_f32_16x16x32_bf16 v[120:123], v[170:173], v[194:197], v[120:123]
	v_mfma_f32_16x16x32_bf16 v[108:111], v[130:133], v[202:205], v[108:111]
	v_mfma_f32_16x16x32_bf16 v[104:107], v[170:173], v[202:205], v[104:107]
	v_mfma_f32_16x16x32_bf16 v[92:95], v[130:133], v[210:213], v[92:95]
	v_mfma_f32_16x16x32_bf16 v[88:91], v[170:173], v[210:213], v[88:91]
	v_mfma_f32_16x16x32_bf16 v[76:79], v[130:133], v[218:221], v[76:79]
	v_mfma_f32_16x16x32_bf16 v[72:75], v[170:173], v[218:221], v[72:75]
	v_mfma_f32_16x16x32_bf16 v[124:127], v[134:137], v[198:201], v[124:127]
	v_mfma_f32_16x16x32_bf16 v[120:123], v[174:177], v[198:201], v[120:123]
	v_mfma_f32_16x16x32_bf16 v[108:111], v[134:137], v[206:209], v[108:111]
	v_mfma_f32_16x16x32_bf16 v[104:107], v[174:177], v[206:209], v[104:107]
	v_mfma_f32_16x16x32_bf16 v[92:95], v[134:137], v[214:217], v[92:95]
	v_mfma_f32_16x16x32_bf16 v[88:91], v[174:177], v[214:217], v[88:91]
	v_mfma_f32_16x16x32_bf16 v[76:79], v[134:137], v[222:225], v[76:79]
	v_mfma_f32_16x16x32_bf16 v[72:75], v[174:177], v[222:225], v[72:75]
	v_mfma_f32_16x16x32_bf16 v[116:119], v[178:181], v[194:197], v[116:119]
	v_mfma_f32_16x16x32_bf16 v[112:115], v[186:189], v[194:197], v[112:115]
	v_mfma_f32_16x16x32_bf16 v[100:103], v[178:181], v[202:205], v[100:103]
	v_mfma_f32_16x16x32_bf16 v[96:99], v[186:189], v[202:205], v[96:99]
	v_mfma_f32_16x16x32_bf16 v[84:87], v[178:181], v[210:213], v[84:87]
	v_mfma_f32_16x16x32_bf16 v[80:83], v[186:189], v[210:213], v[80:83]
	v_mfma_f32_16x16x32_bf16 v[68:71], v[178:181], v[218:221], v[68:71]
	v_mfma_f32_16x16x32_bf16 v[64:67], v[186:189], v[218:221], v[64:67]
	v_mfma_f32_16x16x32_bf16 v[116:119], v[182:185], v[198:201], v[116:119]
	v_mfma_f32_16x16x32_bf16 v[112:115], v[190:193], v[198:201], v[112:115]
	v_mfma_f32_16x16x32_bf16 v[100:103], v[182:185], v[206:209], v[100:103]
	v_mfma_f32_16x16x32_bf16 v[96:99], v[190:193], v[206:209], v[96:99]
	v_mfma_f32_16x16x32_bf16 v[84:87], v[182:185], v[214:217], v[84:87]
	v_mfma_f32_16x16x32_bf16 v[80:83], v[190:193], v[214:217], v[80:83]
	v_mfma_f32_16x16x32_bf16 v[68:71], v[182:185], v[222:225], v[68:71]
	v_mfma_f32_16x16x32_bf16 v[64:67], v[190:193], v[222:225], v[64:67]
	s_barrier
	s_setprio 0
	s_add_i32 s38, s38, s3
	s_mov_b32 m0, s38
	ds_read_b128 v[194:197], v166 offset:16384
	ds_read_b128 v[198:201], v166 offset:17408
	ds_read_b128 v[202:205], v166 offset:18432
	ds_read_b128 v[206:209], v166 offset:19456
	ds_read_b128 v[210:213], v166 offset:20480
	ds_read_b128 v[214:217], v166 offset:21504
	ds_read_b128 v[218:221], v166 offset:22528
	ds_read_b128 v[222:225], v166 offset:23552
	global_load_lds_dwordx4 v144, s[64:65]
	s_add_i32 m0, s38, 0x2000
	s_add_u32 s72, s64, 0x1000
	s_addc_u32 s73, s65, 0
	s_add_i32 s38, s53, s3
	global_load_lds_dwordx4 v140, s[64:65]
	s_mov_b32 m0, s38
	s_nop 0
	global_load_lds_dwordx4 v144, s[72:73]
	s_add_i32 m0, s38, 0x2000
	s_nop 0
	global_load_lds_dwordx4 v140, s[72:73]
	s_mov_b32 m0, s23
	s_nop 0
	global_load_lds_dwordx4 v146, s[66:67]
	s_mov_b32 m0, s30
	s_nop 0
	global_load_lds_dwordx4 v142, s[66:67]
	s_waitcnt vmcnt(8)
	s_waitcnt lgkmcnt(0)
	s_setprio 1
	s_barrier
	v_mfma_f32_16x16x32_bf16 v[60:63], v[130:133], v[194:197], v[60:63]
	v_mfma_f32_16x16x32_bf16 v[56:59], v[170:173], v[194:197], v[56:59]
	v_mfma_f32_16x16x32_bf16 v[44:47], v[130:133], v[202:205], v[44:47]
	v_mfma_f32_16x16x32_bf16 v[40:43], v[170:173], v[202:205], v[40:43]
	v_mfma_f32_16x16x32_bf16 v[28:31], v[130:133], v[210:213], v[28:31]
	v_mfma_f32_16x16x32_bf16 v[24:27], v[170:173], v[210:213], v[24:27]
	v_mfma_f32_16x16x32_bf16 v[12:15], v[130:133], v[218:221], v[12:15]
	v_mfma_f32_16x16x32_bf16 v[8:11], v[170:173], v[218:221], v[8:11]
	v_mfma_f32_16x16x32_bf16 v[60:63], v[134:137], v[198:201], v[60:63]
	v_mfma_f32_16x16x32_bf16 v[56:59], v[174:177], v[198:201], v[56:59]
	v_mfma_f32_16x16x32_bf16 v[44:47], v[134:137], v[206:209], v[44:47]
	v_mfma_f32_16x16x32_bf16 v[40:43], v[174:177], v[206:209], v[40:43]
	v_mfma_f32_16x16x32_bf16 v[28:31], v[134:137], v[214:217], v[28:31]
	v_mfma_f32_16x16x32_bf16 v[24:27], v[174:177], v[214:217], v[24:27]
	v_mfma_f32_16x16x32_bf16 v[12:15], v[134:137], v[222:225], v[12:15]
	v_mfma_f32_16x16x32_bf16 v[8:11], v[174:177], v[222:225], v[8:11]
	v_mfma_f32_16x16x32_bf16 v[52:55], v[178:181], v[194:197], v[52:55]
	v_mfma_f32_16x16x32_bf16 v[48:51], v[186:189], v[194:197], v[48:51]
	v_mfma_f32_16x16x32_bf16 v[36:39], v[178:181], v[202:205], v[36:39]
	v_mfma_f32_16x16x32_bf16 v[32:35], v[186:189], v[202:205], v[32:35]
	v_mfma_f32_16x16x32_bf16 v[20:23], v[178:181], v[210:213], v[20:23]
	v_mfma_f32_16x16x32_bf16 v[16:19], v[186:189], v[210:213], v[16:19]
	v_mfma_f32_16x16x32_bf16 v[4:7], v[178:181], v[218:221], v[4:7]
	v_mfma_f32_16x16x32_bf16 v[0:3], v[186:189], v[218:221], v[0:3]
	v_mfma_f32_16x16x32_bf16 v[52:55], v[182:185], v[198:201], v[52:55]
	v_mfma_f32_16x16x32_bf16 v[48:51], v[190:193], v[198:201], v[48:51]
	v_mfma_f32_16x16x32_bf16 v[36:39], v[182:185], v[206:209], v[36:39]
	v_mfma_f32_16x16x32_bf16 v[32:35], v[190:193], v[206:209], v[32:35]
	v_mfma_f32_16x16x32_bf16 v[20:23], v[182:185], v[214:217], v[20:23]
	v_mfma_f32_16x16x32_bf16 v[16:19], v[190:193], v[214:217], v[16:19]
	v_mfma_f32_16x16x32_bf16 v[4:7], v[182:185], v[222:225], v[4:7]
	v_mfma_f32_16x16x32_bf16 v[0:3], v[190:193], v[222:225], v[0:3]
	s_barrier
; #define PG8_STAGE(bufoff, gbase, voff) do { _Pragma("unroll") for (int _i = 0; _i < 2; ++_i) \
;         __builtin_amdgcn_global_load_lds((const unsigned*)((const char*)(gbase) + (voff)[_i]), (LAS unsigned*)(lds + (bufoff) + ldsw + _i * 8192), 16, 0, 0); } while (0)
; #define PG8_LDA(dst, b, h) do { _Pragma("unroll") for (int m = 0; m < 4; ++m) _Pragma("unroll") for (int k = 0; k < 2; ++k) dst[m][k] = *(const LAS bf16x8*)(lds + PG8_SA(b, h) + aoff + m * 2048 + k * 1024); } while (0)
; #define PG8_LDB(dst, b, h) do { _Pragma("unroll") for (int n = 0; n < 2; ++n) _Pragma("unroll") for (int k = 0; k < 2; ++k) dst[n][k] = *(const LAS bf16x8*)(lds + PG8_SB(b, h) + boff + n * 2048 + k * 1024); } while (0)
; #define PG8_MMA(ai, bj, At, Bt) do { __builtin_amdgcn_s_setprio(1); _Pragma("unroll") for (int m = 0; m < 4; ++m) _Pragma("unroll") for (int n = 0; n < 2; ++n) _Pragma("unroll") for (int k = 0; k < 2; ++k) \
;         acc[ai][bj][m][n] = __builtin_amdgcn_mfma_f32_16x16x32_bf16(Bt[n][k], At[m][k], acc[ai][bj][m][n], 0, 0, 0); __builtin_amdgcn_s_setprio(0); } while (0)
; #define PG8_WAIT_V(n) asm volatile("s_waitcnt vmcnt(" #n ")" ::: "memory")
; #define PG8_WAIT_L(n) asm volatile("s_waitcnt lgkmcnt(" #n ")" ::: "memory")
; #define PG8_BAR __builtin_amdgcn_s_barrier()
; #define PG8_SCHED __builtin_amdgcn_sched_barrier(0)
; template <class Epi, class Sched, bool ALIGN_EPI>
; __device__ __forceinline__ void gemm_phase(LAS unsigned char* lds, const Gemm g, const Sched& S, const Epi& E, const int wid) {
;     ...
;             PG8_LDB(B0, 1, 0); PG8_LDB(B1, 1, 1); PG8_SCHED; PG8_LDA(At, 1, 0); PG8_STAGE(PG8_SA(0, 1), a2 + hstepA, voffA);
;             PG8_WAIT_V(8); PG8_WAIT_L(0); PG8_BAR; PG8_MMA(0, 0, At, B0); PG8_MMA(0, 1, At, B1); PG8_BAR; PG8_SCHED;
;             PG8_LDA(At, 1, 1); PG8_STAGE(PG8_SB(1, 0), b3, voffB); PG8_STAGE(PG8_SB(1, 1), b3 + hstepB, voffB); PG8_STAGE(PG8_SA(1, 0), a3, voffA);
;             PG8_WAIT_V(8); PG8_WAIT_L(0); PG8_BAR; PG8_MMA(1, 0, At, B0); PG8_MMA(1, 1, At, B1); PG8_BAR; PG8_SCHED;
;         }
	s_setprio 0
	s_add_i32 s38, 0, 0x18000
	v_add_u32_e32 v138, s38, v160
	s_add_i32 s39, 0, 0x1c000
	ds_read_b128 v[130:133], v138
	ds_read_b128 v[134:137], v138 offset:1024
	ds_read_b128 v[170:173], v138 offset:2048
	ds_read_b128 v[174:177], v138 offset:3072
	v_add_u32_e32 v138, s39, v160
	ds_read_b128 v[178:181], v138
	ds_read_b128 v[182:185], v138 offset:1024
	ds_read_b128 v[186:189], v138 offset:2048
	ds_read_b128 v[190:193], v138 offset:3072
	s_add_u32 s66, s66, 0x4000
	s_addc_u32 s67, s67, 0
	s_mov_b32 m0, s31
	ds_read_b128 v[194:197], v166 offset:32768
	ds_read_b128 v[198:201], v166 offset:33792
	ds_read_b128 v[202:205], v166 offset:34816
	ds_read_b128 v[206:209], v166 offset:35840
	ds_read_b128 v[210:213], v166 offset:36864
	ds_read_b128 v[214:217], v166 offset:37888
	ds_read_b128 v[218:221], v166 offset:38912
	ds_read_b128 v[222:225], v166 offset:39936
	global_load_lds_dwordx4 v146, s[66:67]
	s_mov_b32 m0, s43
	s_nop 0
	global_load_lds_dwordx4 v142, s[66:67]
	s_waitcnt vmcnt(8)
	s_waitcnt lgkmcnt(0)
	s_setprio 1
	s_barrier
	v_mfma_f32_16x16x32_bf16 v[124:127], v[130:133], v[194:197], v[124:127]
	v_mfma_f32_16x16x32_bf16 v[120:123], v[170:173], v[194:197], v[120:123]
	v_mfma_f32_16x16x32_bf16 v[108:111], v[130:133], v[202:205], v[108:111]
	v_mfma_f32_16x16x32_bf16 v[104:107], v[170:173], v[202:205], v[104:107]
	v_mfma_f32_16x16x32_bf16 v[92:95], v[130:133], v[210:213], v[92:95]
	v_mfma_f32_16x16x32_bf16 v[88:91], v[170:173], v[210:213], v[88:91]
	v_mfma_f32_16x16x32_bf16 v[76:79], v[130:133], v[218:221], v[76:79]
	v_mfma_f32_16x16x32_bf16 v[72:75], v[170:173], v[218:221], v[72:75]
	v_mfma_f32_16x16x32_bf16 v[124:127], v[134:137], v[198:201], v[124:127]
	v_mfma_f32_16x16x32_bf16 v[120:123], v[174:177], v[198:201], v[120:123]
	v_mfma_f32_16x16x32_bf16 v[108:111], v[134:137], v[206:209], v[108:111]
	v_mfma_f32_16x16x32_bf16 v[104:107], v[174:177], v[206:209], v[104:107]
	v_mfma_f32_16x16x32_bf16 v[92:95], v[134:137], v[214:217], v[92:95]
	v_mfma_f32_16x16x32_bf16 v[88:91], v[174:177], v[214:217], v[88:91]
	v_mfma_f32_16x16x32_bf16 v[76:79], v[134:137], v[222:225], v[76:79]
	v_mfma_f32_16x16x32_bf16 v[72:75], v[174:177], v[222:225], v[72:75]
	v_mfma_f32_16x16x32_bf16 v[116:119], v[178:181], v[194:197], v[116:119]
	v_mfma_f32_16x16x32_bf16 v[112:115], v[186:189], v[194:197], v[112:115]
	v_mfma_f32_16x16x32_bf16 v[100:103], v[178:181], v[202:205], v[100:103]
	v_mfma_f32_16x16x32_bf16 v[96:99], v[186:189], v[202:205], v[96:99]
	v_mfma_f32_16x16x32_bf16 v[84:87], v[178:181], v[210:213], v[84:87]
	v_mfma_f32_16x16x32_bf16 v[80:83], v[186:189], v[210:213], v[80:83]
	v_mfma_f32_16x16x32_bf16 v[68:71], v[178:181], v[218:221], v[68:71]
	v_mfma_f32_16x16x32_bf16 v[64:67], v[186:189], v[218:221], v[64:67]
	v_mfma_f32_16x16x32_bf16 v[116:119], v[182:185], v[198:201], v[116:119]
	v_mfma_f32_16x16x32_bf16 v[112:115], v[190:193], v[198:201], v[112:115]
	v_mfma_f32_16x16x32_bf16 v[100:103], v[182:185], v[206:209], v[100:103]
	v_mfma_f32_16x16x32_bf16 v[96:99], v[190:193], v[206:209], v[96:99]
	v_mfma_f32_16x16x32_bf16 v[84:87], v[182:185], v[214:217], v[84:87]
	v_mfma_f32_16x16x32_bf16 v[80:83], v[190:193], v[214:217], v[80:83]
	v_mfma_f32_16x16x32_bf16 v[68:71], v[182:185], v[222:225], v[68:71]
	v_mfma_f32_16x16x32_bf16 v[64:67], v[190:193], v[222:225], v[64:67]
	s_barrier
	s_setprio 0
	s_add_u32 s66, s64, 0x8000
	s_addc_u32 s67, s65, 0
	s_add_i32 s38, s38, s3
	s_mov_b32 m0, s38
	ds_read_b128 v[194:197], v166 offset:49152
	ds_read_b128 v[198:201], v166 offset:50176
	ds_read_b128 v[202:205], v166 offset:51200
	ds_read_b128 v[206:209], v166 offset:52224
	ds_read_b128 v[210:213], v166 offset:53248
	ds_read_b128 v[214:217], v166 offset:54272
	ds_read_b128 v[218:221], v166 offset:55296
	ds_read_b128 v[222:225], v166 offset:56320
	global_load_lds_dwordx4 v144, s[66:67]
	s_add_i32 m0, s38, 0x2000
	s_add_u32 s64, s64, 0x9000
	s_addc_u32 s65, s65, 0
	s_add_i32 s38, s39, s3
	global_load_lds_dwordx4 v140, s[66:67]
	s_mov_b32 m0, s38
	s_nop 0
	global_load_lds_dwordx4 v144, s[64:65]
	s_add_i32 m0, s38, 0x2000
	s_nop 0
	global_load_lds_dwordx4 v140, s[64:65]
	s_mov_b32 m0, s47
	s_nop 0
	global_load_lds_dwordx4 v146, s[62:63]
	s_mov_b32 m0, s49
	s_nop 0
	global_load_lds_dwordx4 v142, s[62:63]
	s_waitcnt vmcnt(8)
	s_waitcnt lgkmcnt(0)
	s_setprio 1
	s_barrier
	v_mfma_f32_16x16x32_bf16 v[60:63], v[130:133], v[194:197], v[60:63]
	v_mfma_f32_16x16x32_bf16 v[56:59], v[170:173], v[194:197], v[56:59]
	v_mfma_f32_16x16x32_bf16 v[44:47], v[130:133], v[202:205], v[44:47]
	v_mfma_f32_16x16x32_bf16 v[40:43], v[170:173], v[202:205], v[40:43]
	v_mfma_f32_16x16x32_bf16 v[28:31], v[130:133], v[210:213], v[28:31]
	v_mfma_f32_16x16x32_bf16 v[24:27], v[170:173], v[210:213], v[24:27]
	v_mfma_f32_16x16x32_bf16 v[12:15], v[130:133], v[218:221], v[12:15]
	v_mfma_f32_16x16x32_bf16 v[8:11], v[170:173], v[218:221], v[8:11]
	v_mfma_f32_16x16x32_bf16 v[60:63], v[134:137], v[198:201], v[60:63]
	v_mfma_f32_16x16x32_bf16 v[56:59], v[174:177], v[198:201], v[56:59]
	v_mfma_f32_16x16x32_bf16 v[44:47], v[134:137], v[206:209], v[44:47]
	v_mfma_f32_16x16x32_bf16 v[40:43], v[174:177], v[206:209], v[40:43]
	v_mfma_f32_16x16x32_bf16 v[28:31], v[134:137], v[214:217], v[28:31]
	v_mfma_f32_16x16x32_bf16 v[24:27], v[174:177], v[214:217], v[24:27]
	v_mfma_f32_16x16x32_bf16 v[12:15], v[134:137], v[222:225], v[12:15]
	v_mfma_f32_16x16x32_bf16 v[8:11], v[174:177], v[222:225], v[8:11]
	v_mfma_f32_16x16x32_bf16 v[52:55], v[178:181], v[194:197], v[52:55]
	v_mfma_f32_16x16x32_bf16 v[48:51], v[186:189], v[194:197], v[48:51]
	v_mfma_f32_16x16x32_bf16 v[36:39], v[178:181], v[202:205], v[36:39]
	v_mfma_f32_16x16x32_bf16 v[32:35], v[186:189], v[202:205], v[32:35]
	v_mfma_f32_16x16x32_bf16 v[20:23], v[178:181], v[210:213], v[20:23]
	v_mfma_f32_16x16x32_bf16 v[16:19], v[186:189], v[210:213], v[16:19]
	v_mfma_f32_16x16x32_bf16 v[4:7], v[178:181], v[218:221], v[4:7]
	v_mfma_f32_16x16x32_bf16 v[0:3], v[186:189], v[218:221], v[0:3]
	v_mfma_f32_16x16x32_bf16 v[52:55], v[182:185], v[198:201], v[52:55]
	v_mfma_f32_16x16x32_bf16 v[48:51], v[190:193], v[198:201], v[48:51]
	v_mfma_f32_16x16x32_bf16 v[36:39], v[182:185], v[206:209], v[36:39]
	v_mfma_f32_16x16x32_bf16 v[32:35], v[190:193], v[206:209], v[32:35]
	v_mfma_f32_16x16x32_bf16 v[20:23], v[182:185], v[214:217], v[20:23]
	v_mfma_f32_16x16x32_bf16 v[16:19], v[190:193], v[214:217], v[16:19]
	v_mfma_f32_16x16x32_bf16 v[4:7], v[182:185], v[222:225], v[4:7]
	v_mfma_f32_16x16x32_bf16 v[0:3], v[190:193], v[222:225], v[0:3]
	s_barrier
	s_setprio 0
	s_add_i32 s71, s71, 2
	s_add_u32 s18, s18, 0x10000
	s_addc_u32 s19, s19, 0
	s_add_u32 s69, s69, 0x10000
	s_addc_u32 s70, s70, 0
	s_cmp_gt_u32 s71, 61
	s_cbranch_scc1 .LBB0_690

; #define PG8_STAGE(bufoff, gbase, voff) do { _Pragma("unroll") for (int _i = 0; _i < 2; ++_i) \
;         __builtin_amdgcn_global_load_lds((const unsigned*)((const char*)(gbase) + (voff)[_i]), (LAS unsigned*)(lds + (bufoff) + ldsw + _i * 8192), 16, 0, 0); } while (0)
; #define PG8_LDA(dst, b, h) do { _Pragma("unroll") for (int m = 0; m < 4; ++m) _Pragma("unroll") for (int k = 0; k < 2; ++k) dst[m][k] = *(const LAS bf16x8*)(lds + PG8_SA(b, h) + aoff + m * 2048 + k * 1024); } while (0)
; #define PG8_LDB(dst, b, h) do { _Pragma("unroll") for (int n = 0; n < 2; ++n) _Pragma("unroll") for (int k = 0; k < 2; ++k) dst[n][k] = *(const LAS bf16x8*)(lds + PG8_SB(b, h) + boff + n * 2048 + k * 1024); } while (0)
; #define PG8_MMA(ai, bj, At, Bt) do { __builtin_amdgcn_s_setprio(1); _Pragma("unroll") for (int m = 0; m < 4; ++m) _Pragma("unroll") for (int n = 0; n < 2; ++n) _Pragma("unroll") for (int k = 0; k < 2; ++k) \
;         acc[ai][bj][m][n] = __builtin_amdgcn_mfma_f32_16x16x32_bf16(Bt[n][k], At[m][k], acc[ai][bj][m][n], 0, 0, 0); __builtin_amdgcn_s_setprio(0); } while (0)
; #define PG8_WAIT_V(n) asm volatile("s_waitcnt vmcnt(" #n ")" ::: "memory")
; #define PG8_WAIT_L(n) asm volatile("s_waitcnt lgkmcnt(" #n ")" ::: "memory")
; #define PG8_BAR __builtin_amdgcn_s_barrier()
; #define PG8_SCHED __builtin_amdgcn_sched_barrier(0)
; template <class Epi, class Sched, bool ALIGN_EPI>
; __device__ __forceinline__ void gemm_phase(LAS unsigned char* lds, const Gemm g, const Sched& S, const Epi& E, const int wid) {
;     ...
;             PG8_LDB(B0, 0, 0); PG8_LDB(B1, 0, 1); PG8_SCHED; PG8_LDA(At, 0, 0); PG8_STAGE(PG8_SA(1, 1), a1 + hstepA, voffA);
;             PG8_WAIT_V(8); PG8_WAIT_L(0); PG8_BAR; PG8_MMA(0, 0, At, B0); PG8_MMA(0, 1, At, B1); PG8_BAR; PG8_SCHED;
;             PG8_LDA(At, 0, 1); PG8_STAGE(PG8_SB(0, 0), b2, voffB); PG8_STAGE(PG8_SB(0, 1), b2 + hstepB, voffB); PG8_STAGE(PG8_SA(0, 0), a2, voffA);
;             PG8_WAIT_V(8); PG8_WAIT_L(0); PG8_BAR; PG8_MMA(1, 0, At, B0); PG8_MMA(1, 1, At, B1); PG8_BAR; PG8_SCHED;
;             PG8_LDB(B0, 1, 0); PG8_LDB(B1, 1, 1); PG8_SCHED; PG8_LDA(At, 1, 0); PG8_STAGE(PG8_SA(0, 1), a2 + hstepA, voffA);
;             PG8_WAIT_V(8); PG8_WAIT_L(0); PG8_BAR; PG8_MMA(0, 0, At, B0); PG8_MMA(0, 1, At, B1); PG8_BAR; PG8_SCHED;
.LBB0_791:
	ds_read_b128 v[72:75], v202
	ds_read_b128 v[76:79], v202 offset:1024
	ds_read_b128 v[136:139], v202 offset:2048
	ds_read_b128 v[140:143], v202 offset:3072
	ds_read_b128 v[144:147], v203
	ds_read_b128 v[148:151], v203 offset:1024
	ds_read_b128 v[152:155], v203 offset:2048
	ds_read_b128 v[178:181], v203 offset:3072
	s_add_u32 s38, s20, 0x4000
	s_addc_u32 s39, s21, 0
	s_cmpk_eq_i32 s53, 0xfc
	s_cselect_b32 s76, s5, s38
	s_cselect_b32 s77, s4, s39
	s_cselect_b32 s74, s31, s35
	s_cselect_b32 s75, s30, s52
	s_add_u32 s72, s76, 0x8000
	s_addc_u32 s73, s77, 0
	s_add_i32 m0, s45, 0xc000
	ds_read_b128 v[182:185], v204
	ds_read_b128 v[186:189], v204 offset:1024
	ds_read_b128 v[190:193], v204 offset:2048
	ds_read_b128 v[194:197], v204 offset:3072
	ds_read_b128 v[208:211], v204 offset:4096
	ds_read_b128 v[212:215], v204 offset:5120
	ds_read_b128 v[216:219], v204 offset:6144
	ds_read_b128 v[220:223], v204 offset:7168
	global_load_lds_dwordx4 v168, s[20:21]
	s_add_i32 m0, s45, 0xe000
	s_nop 0
	global_load_lds_dwordx4 v170, s[20:21]
	s_waitcnt vmcnt(8)
	s_waitcnt lgkmcnt(0)
	s_setprio 1
	s_barrier
	v_mfma_f32_16x16x32_bf16 v[132:135], v[72:75], v[182:185], v[132:135]
	v_mfma_f32_16x16x32_bf16 v[128:131], v[136:139], v[182:185], v[128:131]
	v_mfma_f32_16x16x32_bf16 v[116:119], v[72:75], v[190:193], v[116:119]
	v_mfma_f32_16x16x32_bf16 v[112:115], v[136:139], v[190:193], v[112:115]
	v_mfma_f32_16x16x32_bf16 v[100:103], v[72:75], v[208:211], v[100:103]
	v_mfma_f32_16x16x32_bf16 v[96:99], v[136:139], v[208:211], v[96:99]
	v_mfma_f32_16x16x32_bf16 v[84:87], v[72:75], v[216:219], v[84:87]
	v_mfma_f32_16x16x32_bf16 v[80:83], v[136:139], v[216:219], v[80:83]
	v_mfma_f32_16x16x32_bf16 v[132:135], v[76:79], v[186:189], v[132:135]
	v_mfma_f32_16x16x32_bf16 v[128:131], v[140:143], v[186:189], v[128:131]
	v_mfma_f32_16x16x32_bf16 v[116:119], v[76:79], v[194:197], v[116:119]
	v_mfma_f32_16x16x32_bf16 v[112:115], v[140:143], v[194:197], v[112:115]
	v_mfma_f32_16x16x32_bf16 v[100:103], v[76:79], v[212:215], v[100:103]
	v_mfma_f32_16x16x32_bf16 v[96:99], v[140:143], v[212:215], v[96:99]
	v_mfma_f32_16x16x32_bf16 v[84:87], v[76:79], v[220:223], v[84:87]
	v_mfma_f32_16x16x32_bf16 v[80:83], v[140:143], v[220:223], v[80:83]
	v_mfma_f32_16x16x32_bf16 v[124:127], v[144:147], v[182:185], v[124:127]
	v_mfma_f32_16x16x32_bf16 v[120:123], v[152:155], v[182:185], v[120:123]
	v_mfma_f32_16x16x32_bf16 v[108:111], v[144:147], v[190:193], v[108:111]
	v_mfma_f32_16x16x32_bf16 v[104:107], v[152:155], v[190:193], v[104:107]
	v_mfma_f32_16x16x32_bf16 v[92:95], v[144:147], v[208:211], v[92:95]
	v_mfma_f32_16x16x32_bf16 v[88:91], v[152:155], v[208:211], v[88:91]
	v_mfma_f32_16x16x32_bf16 v[68:71], v[144:147], v[216:219], v[68:71]
	v_mfma_f32_16x16x32_bf16 v[64:67], v[152:155], v[216:219], v[64:67]
	v_mfma_f32_16x16x32_bf16 v[124:127], v[148:151], v[186:189], v[124:127]
	v_mfma_f32_16x16x32_bf16 v[120:123], v[178:181], v[186:189], v[120:123]
	v_mfma_f32_16x16x32_bf16 v[108:111], v[148:151], v[194:197], v[108:111]
	v_mfma_f32_16x16x32_bf16 v[104:107], v[178:181], v[194:197], v[104:107]
	v_mfma_f32_16x16x32_bf16 v[92:95], v[148:151], v[212:215], v[92:95]
	v_mfma_f32_16x16x32_bf16 v[88:91], v[178:181], v[212:215], v[88:91]
	v_mfma_f32_16x16x32_bf16 v[68:71], v[148:151], v[220:223], v[68:71]
	v_mfma_f32_16x16x32_bf16 v[64:67], v[178:181], v[220:223], v[64:67]
	s_barrier
	s_setprio 0
	s_add_i32 s38, s81, s3
	s_mov_b32 m0, s38
	ds_read_b128 v[182:185], v204 offset:16384
	ds_read_b128 v[186:189], v204 offset:17408
	ds_read_b128 v[190:193], v204 offset:18432
	ds_read_b128 v[194:197], v204 offset:19456
	ds_read_b128 v[208:211], v204 offset:20480
	ds_read_b128 v[212:215], v204 offset:21504
	ds_read_b128 v[216:219], v204 offset:22528
	ds_read_b128 v[220:223], v204 offset:23552
	global_load_lds_dwordx4 v158, s[74:75]
	s_add_i32 m0, s38, 0x2000
	s_add_u32 s54, s74, 0x1000
	s_addc_u32 s55, s75, 0
	s_add_i32 s38, s85, s3
	global_load_lds_dwordx4 v162, s[74:75]
	s_mov_b32 m0, s38
	s_nop 0
	global_load_lds_dwordx4 v158, s[54:55]
	s_add_i32 m0, s38, 0x2000
	s_nop 0
	global_load_lds_dwordx4 v162, s[54:55]
	s_mov_b32 m0, s45
	s_nop 0
	global_load_lds_dwordx4 v156, s[76:77]
	s_mov_b32 m0, s46
	s_nop 0
	global_load_lds_dwordx4 v160, s[76:77]
	s_waitcnt vmcnt(8)
	s_waitcnt lgkmcnt(0)
	s_setprio 1
	s_barrier
	v_mfma_f32_16x16x32_bf16 v[60:63], v[72:75], v[182:185], v[60:63]
	v_mfma_f32_16x16x32_bf16 v[56:59], v[136:139], v[182:185], v[56:59]
	v_mfma_f32_16x16x32_bf16 v[44:47], v[72:75], v[190:193], v[44:47]
	v_mfma_f32_16x16x32_bf16 v[40:43], v[136:139], v[190:193], v[40:43]
	v_mfma_f32_16x16x32_bf16 v[28:31], v[72:75], v[208:211], v[28:31]
	v_mfma_f32_16x16x32_bf16 v[24:27], v[136:139], v[208:211], v[24:27]
	v_mfma_f32_16x16x32_bf16 v[12:15], v[72:75], v[216:219], v[12:15]
	v_mfma_f32_16x16x32_bf16 v[8:11], v[136:139], v[216:219], v[8:11]
	v_mfma_f32_16x16x32_bf16 v[60:63], v[76:79], v[186:189], v[60:63]
	v_mfma_f32_16x16x32_bf16 v[56:59], v[140:143], v[186:189], v[56:59]
	v_mfma_f32_16x16x32_bf16 v[44:47], v[76:79], v[194:197], v[44:47]
	v_mfma_f32_16x16x32_bf16 v[40:43], v[140:143], v[194:197], v[40:43]
	v_mfma_f32_16x16x32_bf16 v[28:31], v[76:79], v[212:215], v[28:31]
	v_mfma_f32_16x16x32_bf16 v[24:27], v[140:143], v[212:215], v[24:27]
	v_mfma_f32_16x16x32_bf16 v[12:15], v[76:79], v[220:223], v[12:15]
	v_mfma_f32_16x16x32_bf16 v[8:11], v[140:143], v[220:223], v[8:11]
	v_mfma_f32_16x16x32_bf16 v[52:55], v[144:147], v[182:185], v[52:55]
	v_mfma_f32_16x16x32_bf16 v[48:51], v[152:155], v[182:185], v[48:51]
	v_mfma_f32_16x16x32_bf16 v[36:39], v[144:147], v[190:193], v[36:39]
	v_mfma_f32_16x16x32_bf16 v[32:35], v[152:155], v[190:193], v[32:35]
	v_mfma_f32_16x16x32_bf16 v[20:23], v[144:147], v[208:211], v[20:23]
	v_mfma_f32_16x16x32_bf16 v[16:19], v[152:155], v[208:211], v[16:19]
	v_mfma_f32_16x16x32_bf16 v[4:7], v[144:147], v[216:219], v[4:7]
	v_mfma_f32_16x16x32_bf16 v[0:3], v[152:155], v[216:219], v[0:3]
	v_mfma_f32_16x16x32_bf16 v[52:55], v[148:151], v[186:189], v[52:55]
	v_mfma_f32_16x16x32_bf16 v[48:51], v[178:181], v[186:189], v[48:51]
	v_mfma_f32_16x16x32_bf16 v[36:39], v[148:151], v[194:197], v[36:39]
	v_mfma_f32_16x16x32_bf16 v[32:35], v[178:181], v[194:197], v[32:35]
	v_mfma_f32_16x16x32_bf16 v[20:23], v[148:151], v[212:215], v[20:23]
	v_mfma_f32_16x16x32_bf16 v[16:19], v[178:181], v[212:215], v[16:19]
	v_mfma_f32_16x16x32_bf16 v[4:7], v[148:151], v[220:223], v[4:7]
	v_mfma_f32_16x16x32_bf16 v[0:3], v[178:181], v[220:223], v[0:3]
	s_barrier
; #define PG8_STAGE(bufoff, gbase, voff) do { _Pragma("unroll") for (int _i = 0; _i < 2; ++_i) \
;         __builtin_amdgcn_global_load_lds((const unsigned*)((const char*)(gbase) + (voff)[_i]), (LAS unsigned*)(lds + (bufoff) + ldsw + _i * 8192), 16, 0, 0); } while (0)
; #define PG8_LDA(dst, b, h) do { _Pragma("unroll") for (int m = 0; m < 4; ++m) _Pragma("unroll") for (int k = 0; k < 2; ++k) dst[m][k] = *(const LAS bf16x8*)(lds + PG8_SA(b, h) + aoff + m * 2048 + k * 1024); } while (0)
; #define PG8_LDB(dst, b, h) do { _Pragma("unroll") for (int n = 0; n < 2; ++n) _Pragma("unroll") for (int k = 0; k < 2; ++k) dst[n][k] = *(const LAS bf16x8*)(lds + PG8_SB(b, h) + boff + n * 2048 + k * 1024); } while (0)
; #define PG8_MMA(ai, bj, At, Bt) do { __builtin_amdgcn_s_setprio(1); _Pragma("unroll") for (int m = 0; m < 4; ++m) _Pragma("unroll") for (int n = 0; n < 2; ++n) _Pragma("unroll") for (int k = 0; k < 2; ++k) \
;         acc[ai][bj][m][n] = __builtin_amdgcn_mfma_f32_16x16x32_bf16(Bt[n][k], At[m][k], acc[ai][bj][m][n], 0, 0, 0); __builtin_amdgcn_s_setprio(0); } while (0)
; #define PG8_WAIT_V(n) asm volatile("s_waitcnt vmcnt(" #n ")" ::: "memory")
; #define PG8_WAIT_L(n) asm volatile("s_waitcnt lgkmcnt(" #n ")" ::: "memory")
; #define PG8_BAR __builtin_amdgcn_s_barrier()
; #define PG8_SCHED __builtin_amdgcn_sched_barrier(0)
; template <class Epi, class Sched, bool ALIGN_EPI>
; __device__ __forceinline__ void gemm_phase(LAS unsigned char* lds, const Gemm g, const Sched& S, const Epi& E, const int wid) {
;     ...
;             PG8_LDB(B0, 1, 0); PG8_LDB(B1, 1, 1); PG8_SCHED; PG8_LDA(At, 1, 0); PG8_STAGE(PG8_SA(0, 1), a2 + hstepA, voffA);
;             PG8_WAIT_V(8); PG8_WAIT_L(0); PG8_BAR; PG8_MMA(0, 0, At, B0); PG8_MMA(0, 1, At, B1); PG8_BAR; PG8_SCHED;
;             PG8_LDA(At, 1, 1); PG8_STAGE(PG8_SB(1, 0), b3, voffB); PG8_STAGE(PG8_SB(1, 1), b3 + hstepB, voffB); PG8_STAGE(PG8_SA(1, 0), a3, voffA);
;             PG8_WAIT_V(8); PG8_WAIT_L(0); PG8_BAR; PG8_MMA(1, 0, At, B0); PG8_MMA(1, 1, At, B1); PG8_BAR; PG8_SCHED;
;         }
	s_setprio 0
	s_add_i32 s38, 0, 0x18000
	s_add_i32 s39, 0, 0x1c000
	v_add_u32_e32 v140, s38, v198
	v_add_u32_e32 v164, s39, v198
	ds_read_b128 v[72:75], v140
	ds_read_b128 v[76:79], v140 offset:1024
	ds_read_b128 v[136:139], v140 offset:2048
	ds_read_b128 v[140:143], v140 offset:3072
	ds_read_b128 v[144:147], v164
	ds_read_b128 v[148:151], v164 offset:1024
	ds_read_b128 v[152:155], v164 offset:2048
	ds_read_b128 v[178:181], v164 offset:3072
	s_add_u32 s54, s76, 0x4000
	s_addc_u32 s55, s77, 0
	s_mov_b32 m0, s47
	ds_read_b128 v[182:185], v204 offset:32768
	ds_read_b128 v[186:189], v204 offset:33792
	ds_read_b128 v[190:193], v204 offset:34816
	ds_read_b128 v[194:197], v204 offset:35840
	ds_read_b128 v[208:211], v204 offset:36864
	ds_read_b128 v[212:215], v204 offset:37888
	ds_read_b128 v[216:219], v204 offset:38912
	ds_read_b128 v[220:223], v204 offset:39936
	global_load_lds_dwordx4 v156, s[54:55]
	s_mov_b32 m0, s49
	s_nop 0
	global_load_lds_dwordx4 v160, s[54:55]
	s_waitcnt vmcnt(8)
	s_waitcnt lgkmcnt(0)
	s_setprio 1
	s_barrier
	v_mfma_f32_16x16x32_bf16 v[132:135], v[72:75], v[182:185], v[132:135]
	v_mfma_f32_16x16x32_bf16 v[128:131], v[136:139], v[182:185], v[128:131]
	v_mfma_f32_16x16x32_bf16 v[116:119], v[72:75], v[190:193], v[116:119]
	v_mfma_f32_16x16x32_bf16 v[112:115], v[136:139], v[190:193], v[112:115]
	v_mfma_f32_16x16x32_bf16 v[100:103], v[72:75], v[208:211], v[100:103]
	v_mfma_f32_16x16x32_bf16 v[96:99], v[136:139], v[208:211], v[96:99]
	v_mfma_f32_16x16x32_bf16 v[84:87], v[72:75], v[216:219], v[84:87]
	v_mfma_f32_16x16x32_bf16 v[80:83], v[136:139], v[216:219], v[80:83]
	v_mfma_f32_16x16x32_bf16 v[132:135], v[76:79], v[186:189], v[132:135]
	v_mfma_f32_16x16x32_bf16 v[128:131], v[140:143], v[186:189], v[128:131]
	v_mfma_f32_16x16x32_bf16 v[116:119], v[76:79], v[194:197], v[116:119]
	v_mfma_f32_16x16x32_bf16 v[112:115], v[140:143], v[194:197], v[112:115]
	v_mfma_f32_16x16x32_bf16 v[100:103], v[76:79], v[212:215], v[100:103]
	v_mfma_f32_16x16x32_bf16 v[96:99], v[140:143], v[212:215], v[96:99]
	v_mfma_f32_16x16x32_bf16 v[84:87], v[76:79], v[220:223], v[84:87]
	v_mfma_f32_16x16x32_bf16 v[80:83], v[140:143], v[220:223], v[80:83]
	v_mfma_f32_16x16x32_bf16 v[124:127], v[144:147], v[182:185], v[124:127]
	v_mfma_f32_16x16x32_bf16 v[120:123], v[152:155], v[182:185], v[120:123]
	v_mfma_f32_16x16x32_bf16 v[108:111], v[144:147], v[190:193], v[108:111]
	v_mfma_f32_16x16x32_bf16 v[104:107], v[152:155], v[190:193], v[104:107]
	v_mfma_f32_16x16x32_bf16 v[92:95], v[144:147], v[208:211], v[92:95]
	v_mfma_f32_16x16x32_bf16 v[88:91], v[152:155], v[208:211], v[88:91]
	v_mfma_f32_16x16x32_bf16 v[68:71], v[144:147], v[216:219], v[68:71]
	v_mfma_f32_16x16x32_bf16 v[64:67], v[152:155], v[216:219], v[64:67]
	v_mfma_f32_16x16x32_bf16 v[124:127], v[148:151], v[186:189], v[124:127]
	v_mfma_f32_16x16x32_bf16 v[120:123], v[178:181], v[186:189], v[120:123]
	v_mfma_f32_16x16x32_bf16 v[108:111], v[148:151], v[194:197], v[108:111]
	v_mfma_f32_16x16x32_bf16 v[104:107], v[178:181], v[194:197], v[104:107]
	v_mfma_f32_16x16x32_bf16 v[92:95], v[148:151], v[212:215], v[92:95]
	v_mfma_f32_16x16x32_bf16 v[88:91], v[178:181], v[212:215], v[88:91]
	v_mfma_f32_16x16x32_bf16 v[68:71], v[148:151], v[220:223], v[68:71]
	v_mfma_f32_16x16x32_bf16 v[64:67], v[178:181], v[220:223], v[64:67]
	s_barrier
	s_setprio 0
	s_add_u32 s54, s74, 0x8000
	s_addc_u32 s55, s75, 0
	s_add_i32 s38, s38, s3
	s_mov_b32 m0, s38
	ds_read_b128 v[182:185], v204 offset:49152
	ds_read_b128 v[186:189], v204 offset:50176
	ds_read_b128 v[190:193], v204 offset:51200
	ds_read_b128 v[194:197], v204 offset:52224
	ds_read_b128 v[208:211], v204 offset:53248
	ds_read_b128 v[212:215], v204 offset:54272
	ds_read_b128 v[216:219], v204 offset:55296
	ds_read_b128 v[220:223], v204 offset:56320
	global_load_lds_dwordx4 v158, s[54:55]
	s_add_i32 m0, s38, 0x2000
	s_nop 0
	global_load_lds_dwordx4 v162, s[54:55]
	s_add_u32 s54, s74, 0x9000
	s_addc_u32 s55, s75, 0
	s_add_i32 s38, s39, s3
	s_mov_b32 m0, s38
	s_nop 0
	global_load_lds_dwordx4 v158, s[54:55]
	s_add_i32 m0, s38, 0x2000
	s_nop 0
	global_load_lds_dwordx4 v162, s[54:55]
	s_mov_b32 m0, s78
	s_nop 0
	global_load_lds_dwordx4 v156, s[72:73]
	s_mov_b32 m0, s79
	s_nop 0
	global_load_lds_dwordx4 v160, s[72:73]
	s_waitcnt vmcnt(8)
	s_waitcnt lgkmcnt(0)
	s_setprio 1
	s_barrier
	v_mfma_f32_16x16x32_bf16 v[60:63], v[72:75], v[182:185], v[60:63]
	v_mfma_f32_16x16x32_bf16 v[56:59], v[136:139], v[182:185], v[56:59]
	v_mfma_f32_16x16x32_bf16 v[44:47], v[72:75], v[190:193], v[44:47]
	v_mfma_f32_16x16x32_bf16 v[40:43], v[136:139], v[190:193], v[40:43]
	v_mfma_f32_16x16x32_bf16 v[28:31], v[72:75], v[208:211], v[28:31]
	v_mfma_f32_16x16x32_bf16 v[24:27], v[136:139], v[208:211], v[24:27]
	v_mfma_f32_16x16x32_bf16 v[12:15], v[72:75], v[216:219], v[12:15]
	v_mfma_f32_16x16x32_bf16 v[8:11], v[136:139], v[216:219], v[8:11]
	v_mfma_f32_16x16x32_bf16 v[60:63], v[76:79], v[186:189], v[60:63]
	v_mfma_f32_16x16x32_bf16 v[56:59], v[140:143], v[186:189], v[56:59]
	v_mfma_f32_16x16x32_bf16 v[44:47], v[76:79], v[194:197], v[44:47]
	v_mfma_f32_16x16x32_bf16 v[40:43], v[140:143], v[194:197], v[40:43]
	v_mfma_f32_16x16x32_bf16 v[28:31], v[76:79], v[212:215], v[28:31]
	v_mfma_f32_16x16x32_bf16 v[24:27], v[140:143], v[212:215], v[24:27]
	v_mfma_f32_16x16x32_bf16 v[12:15], v[76:79], v[220:223], v[12:15]
	v_mfma_f32_16x16x32_bf16 v[8:11], v[140:143], v[220:223], v[8:11]
	v_mfma_f32_16x16x32_bf16 v[52:55], v[144:147], v[182:185], v[52:55]
	v_mfma_f32_16x16x32_bf16 v[48:51], v[152:155], v[182:185], v[48:51]
	v_mfma_f32_16x16x32_bf16 v[36:39], v[144:147], v[190:193], v[36:39]
	v_mfma_f32_16x16x32_bf16 v[32:35], v[152:155], v[190:193], v[32:35]
	v_mfma_f32_16x16x32_bf16 v[20:23], v[144:147], v[208:211], v[20:23]
	v_mfma_f32_16x16x32_bf16 v[16:19], v[152:155], v[208:211], v[16:19]
	v_mfma_f32_16x16x32_bf16 v[4:7], v[144:147], v[216:219], v[4:7]
	v_mfma_f32_16x16x32_bf16 v[0:3], v[152:155], v[216:219], v[0:3]
	v_mfma_f32_16x16x32_bf16 v[52:55], v[148:151], v[186:189], v[52:55]
	v_mfma_f32_16x16x32_bf16 v[48:51], v[178:181], v[186:189], v[48:51]
	v_mfma_f32_16x16x32_bf16 v[36:39], v[148:151], v[194:197], v[36:39]
	v_mfma_f32_16x16x32_bf16 v[32:35], v[178:181], v[194:197], v[32:35]
	v_mfma_f32_16x16x32_bf16 v[20:23], v[148:151], v[212:215], v[20:23]
	v_mfma_f32_16x16x32_bf16 v[16:19], v[178:181], v[212:215], v[16:19]
	v_mfma_f32_16x16x32_bf16 v[4:7], v[148:151], v[220:223], v[4:7]
	v_mfma_f32_16x16x32_bf16 v[0:3], v[178:181], v[220:223], v[0:3]
	s_barrier
	s_setprio 0
	s_add_i32 s53, s53, 2
	s_add_u32 s35, s35, 0x10000
	s_addc_u32 s52, s52, 0
	s_add_u32 s20, s20, 0x10000
	s_addc_u32 s21, s21, 0
	s_cmpk_gt_u32 s53, 0xfd
	s_cbranch_scc0 .LBB0_791
	s_and_b64 vcc, exec, s[28:29]
	s_cbranch_vccz .LBB0_794
	s_barrier

; #define PG8_STAGE(bufoff, gbase, voff) do { _Pragma("unroll") for (int _i = 0; _i < 2; ++_i) \
;         __builtin_amdgcn_global_load_lds((const unsigned*)((const char*)(gbase) + (voff)[_i]), (LAS unsigned*)(lds + (bufoff) + ldsw + _i * 8192), 16, 0, 0); } while (0)
; #define PG8_LDA(dst, b, h) do { _Pragma("unroll") for (int m = 0; m < 4; ++m) _Pragma("unroll") for (int k = 0; k < 2; ++k) dst[m][k] = *(const LAS bf16x8*)(lds + PG8_SA(b, h) + aoff + m * 2048 + k * 1024); } while (0)
; #define PG8_LDB(dst, b, h) do { _Pragma("unroll") for (int n = 0; n < 2; ++n) _Pragma("unroll") for (int k = 0; k < 2; ++k) dst[n][k] = *(const LAS bf16x8*)(lds + PG8_SB(b, h) + boff + n * 2048 + k * 1024); } while (0)
; #define PG8_MMA(ai, bj, At, Bt) do { __builtin_amdgcn_s_setprio(1); _Pragma("unroll") for (int m = 0; m < 4; ++m) _Pragma("unroll") for (int n = 0; n < 2; ++n) _Pragma("unroll") for (int k = 0; k < 2; ++k) \
;         acc[ai][bj][m][n] = __builtin_amdgcn_mfma_f32_16x16x32_bf16(Bt[n][k], At[m][k], acc[ai][bj][m][n], 0, 0, 0); __builtin_amdgcn_s_setprio(0); } while (0)
; #define PG8_WAIT_V(n) asm volatile("s_waitcnt vmcnt(" #n ")" ::: "memory")
; #define PG8_WAIT_L(n) asm volatile("s_waitcnt lgkmcnt(" #n ")" ::: "memory")
; #define PG8_BAR __builtin_amdgcn_s_barrier()
; #define PG8_SCHED __builtin_amdgcn_sched_barrier(0)
; template <class Epi, class Sched, bool ALIGN_EPI>
; __device__ __forceinline__ void gemm_phase(LAS unsigned char* lds, const Gemm g, const Sched& S, const Epi& E, const int wid) {
;     ...
;             PG8_LDB(B0, 0, 0); PG8_LDB(B1, 0, 1); PG8_SCHED; PG8_LDA(At, 0, 0); PG8_STAGE(PG8_SA(1, 1), a1 + hstepA, voffA);
;             PG8_WAIT_V(8); PG8_WAIT_L(0); PG8_BAR; PG8_MMA(0, 0, At, B0); PG8_MMA(0, 1, At, B1); PG8_BAR; PG8_SCHED;
;             PG8_LDA(At, 0, 1); PG8_STAGE(PG8_SB(0, 0), b2, voffB); PG8_STAGE(PG8_SB(0, 1), b2 + hstepB, voffB); PG8_STAGE(PG8_SA(0, 0), a2, voffA);
;             PG8_WAIT_V(8); PG8_WAIT_L(0); PG8_BAR; PG8_MMA(1, 0, At, B0); PG8_MMA(1, 1, At, B1); PG8_BAR; PG8_SCHED;
;             PG8_LDB(B0, 1, 0); PG8_LDB(B1, 1, 1); PG8_SCHED; PG8_LDA(At, 1, 0); PG8_STAGE(PG8_SA(0, 1), a2 + hstepA, voffA);
;             PG8_WAIT_V(8); PG8_WAIT_L(0); PG8_BAR; PG8_MMA(0, 0, At, B0); PG8_MMA(0, 1, At, B1); PG8_BAR; PG8_SCHED;
.LBB0_920:
	v_add_u32_e32 v142, s89, v170
	s_waitcnt lgkmcnt(0)
	ds_read_b128 v[130:133], v142
	ds_read_b128 v[134:137], v142 offset:1024
	ds_read_b128 v[138:141], v142 offset:2048
	ds_read_b128 v[182:185], v142 offset:3072
	v_add_u32_e32 v142, s90, v170
	s_add_u32 s38, s68, 0x4000
	ds_read_b128 v[186:189], v142
	ds_read_b128 v[190:193], v142 offset:1024
	ds_read_b128 v[194:197], v142 offset:2048
	ds_read_b128 v[198:201], v142 offset:3072
	s_addc_u32 s39, s69, 0
	s_and_b64 s[70:71], s[72:73], exec
	s_cselect_b32 s74, s5, s38
	s_cselect_b32 s75, s4, s39
	s_add_u32 s70, s74, 0x8000
	s_addc_u32 s71, s75, 0
	s_and_b64 s[72:73], s[72:73], exec
	s_cselect_b32 s73, s19, s35
	s_cselect_b32 s72, s30, s31
	s_add_i32 m0, s44, 0xc000
	ds_read_b128 v[202:205], v177
	ds_read_b128 v[206:209], v177 offset:1024
	ds_read_b128 v[210:213], v177 offset:2048
	ds_read_b128 v[214:217], v177 offset:3072
	ds_read_b128 v[218:221], v177 offset:4096
	ds_read_b128 v[222:225], v177 offset:5120
	ds_read_b128 v[226:229], v177 offset:6144
	ds_read_b128 v[230:233], v177 offset:7168
	global_load_lds_dwordx4 v158, s[68:69]
	s_add_i32 m0, s44, 0xe000
	s_nop 0
	global_load_lds_dwordx4 v160, s[68:69]
	s_waitcnt vmcnt(8)
	s_waitcnt lgkmcnt(0)
	s_setprio 1
	s_barrier
	v_mfma_f32_16x16x32_bf16 v[124:127], v[130:133], v[202:205], v[124:127]
	v_mfma_f32_16x16x32_bf16 v[120:123], v[138:141], v[202:205], v[120:123]
	v_mfma_f32_16x16x32_bf16 v[108:111], v[130:133], v[210:213], v[108:111]
	v_mfma_f32_16x16x32_bf16 v[104:107], v[138:141], v[210:213], v[104:107]
	v_mfma_f32_16x16x32_bf16 v[92:95], v[130:133], v[218:221], v[92:95]
	v_mfma_f32_16x16x32_bf16 v[88:91], v[138:141], v[218:221], v[88:91]
	v_mfma_f32_16x16x32_bf16 v[76:79], v[130:133], v[226:229], v[76:79]
	v_mfma_f32_16x16x32_bf16 v[72:75], v[138:141], v[226:229], v[72:75]
	v_mfma_f32_16x16x32_bf16 v[124:127], v[134:137], v[206:209], v[124:127]
	v_mfma_f32_16x16x32_bf16 v[120:123], v[182:185], v[206:209], v[120:123]
	v_mfma_f32_16x16x32_bf16 v[108:111], v[134:137], v[214:217], v[108:111]
	v_mfma_f32_16x16x32_bf16 v[104:107], v[182:185], v[214:217], v[104:107]
	v_mfma_f32_16x16x32_bf16 v[92:95], v[134:137], v[222:225], v[92:95]
	v_mfma_f32_16x16x32_bf16 v[88:91], v[182:185], v[222:225], v[88:91]
	v_mfma_f32_16x16x32_bf16 v[76:79], v[134:137], v[230:233], v[76:79]
	v_mfma_f32_16x16x32_bf16 v[72:75], v[182:185], v[230:233], v[72:75]
	v_mfma_f32_16x16x32_bf16 v[116:119], v[186:189], v[202:205], v[116:119]
	v_mfma_f32_16x16x32_bf16 v[112:115], v[194:197], v[202:205], v[112:115]
	v_mfma_f32_16x16x32_bf16 v[100:103], v[186:189], v[210:213], v[100:103]
	v_mfma_f32_16x16x32_bf16 v[96:99], v[194:197], v[210:213], v[96:99]
	v_mfma_f32_16x16x32_bf16 v[84:87], v[186:189], v[218:221], v[84:87]
	v_mfma_f32_16x16x32_bf16 v[80:83], v[194:197], v[218:221], v[80:83]
	v_mfma_f32_16x16x32_bf16 v[68:71], v[186:189], v[226:229], v[68:71]
	v_mfma_f32_16x16x32_bf16 v[64:67], v[194:197], v[226:229], v[64:67]
	v_mfma_f32_16x16x32_bf16 v[116:119], v[190:193], v[206:209], v[116:119]
	v_mfma_f32_16x16x32_bf16 v[112:115], v[198:201], v[206:209], v[112:115]
	v_mfma_f32_16x16x32_bf16 v[100:103], v[190:193], v[214:217], v[100:103]
	v_mfma_f32_16x16x32_bf16 v[96:99], v[198:201], v[214:217], v[96:99]
	v_mfma_f32_16x16x32_bf16 v[84:87], v[190:193], v[222:225], v[84:87]
	v_mfma_f32_16x16x32_bf16 v[80:83], v[198:201], v[222:225], v[80:83]
	v_mfma_f32_16x16x32_bf16 v[68:71], v[190:193], v[230:233], v[68:71]
	v_mfma_f32_16x16x32_bf16 v[64:67], v[198:201], v[230:233], v[64:67]
	s_barrier
	s_setprio 0
	s_add_i32 s38, s89, s3
	s_mov_b32 m0, s38
	ds_read_b128 v[202:205], v177 offset:16384
	ds_read_b128 v[206:209], v177 offset:17408
	ds_read_b128 v[210:213], v177 offset:18432
	ds_read_b128 v[214:217], v177 offset:19456
	ds_read_b128 v[218:221], v177 offset:20480
	ds_read_b128 v[222:225], v177 offset:21504
	ds_read_b128 v[226:229], v177 offset:22528
	ds_read_b128 v[230:233], v177 offset:23552
	global_load_lds_dwordx4 v146, s[72:73]
	s_add_i32 m0, s38, 0x2000
	s_add_u32 s94, s72, 0x1000
	s_addc_u32 s95, s73, 0
	s_add_i32 s38, s90, s3
	global_load_lds_dwordx4 v150, s[72:73]
	s_mov_b32 m0, s38
	s_nop 0
	global_load_lds_dwordx4 v146, s[94:95]
	s_add_i32 m0, s38, 0x2000
	s_nop 0
	global_load_lds_dwordx4 v150, s[94:95]
	s_mov_b32 m0, s44
	s_nop 0
	global_load_lds_dwordx4 v144, s[74:75]
	s_mov_b32 m0, s45
	s_nop 0
	global_load_lds_dwordx4 v148, s[74:75]
	s_waitcnt vmcnt(8)
	s_waitcnt lgkmcnt(0)
	s_setprio 1
	s_barrier
	v_mfma_f32_16x16x32_bf16 v[60:63], v[130:133], v[202:205], v[60:63]
	v_mfma_f32_16x16x32_bf16 v[56:59], v[138:141], v[202:205], v[56:59]
	v_mfma_f32_16x16x32_bf16 v[44:47], v[130:133], v[210:213], v[44:47]
	v_mfma_f32_16x16x32_bf16 v[40:43], v[138:141], v[210:213], v[40:43]
	v_mfma_f32_16x16x32_bf16 v[28:31], v[130:133], v[218:221], v[28:31]
	v_mfma_f32_16x16x32_bf16 v[24:27], v[138:141], v[218:221], v[24:27]
	v_mfma_f32_16x16x32_bf16 v[12:15], v[130:133], v[226:229], v[12:15]
	v_mfma_f32_16x16x32_bf16 v[8:11], v[138:141], v[226:229], v[8:11]
	v_mfma_f32_16x16x32_bf16 v[60:63], v[134:137], v[206:209], v[60:63]
	v_mfma_f32_16x16x32_bf16 v[56:59], v[182:185], v[206:209], v[56:59]
	v_mfma_f32_16x16x32_bf16 v[44:47], v[134:137], v[214:217], v[44:47]
	v_mfma_f32_16x16x32_bf16 v[40:43], v[182:185], v[214:217], v[40:43]
	v_mfma_f32_16x16x32_bf16 v[28:31], v[134:137], v[222:225], v[28:31]
	v_mfma_f32_16x16x32_bf16 v[24:27], v[182:185], v[222:225], v[24:27]
	v_mfma_f32_16x16x32_bf16 v[12:15], v[134:137], v[230:233], v[12:15]
	v_mfma_f32_16x16x32_bf16 v[8:11], v[182:185], v[230:233], v[8:11]
	v_mfma_f32_16x16x32_bf16 v[52:55], v[186:189], v[202:205], v[52:55]
	v_mfma_f32_16x16x32_bf16 v[48:51], v[194:197], v[202:205], v[48:51]
	v_mfma_f32_16x16x32_bf16 v[36:39], v[186:189], v[210:213], v[36:39]
	v_mfma_f32_16x16x32_bf16 v[32:35], v[194:197], v[210:213], v[32:35]
	v_mfma_f32_16x16x32_bf16 v[20:23], v[186:189], v[218:221], v[20:23]
	v_mfma_f32_16x16x32_bf16 v[16:19], v[194:197], v[218:221], v[16:19]
	v_mfma_f32_16x16x32_bf16 v[4:7], v[186:189], v[226:229], v[4:7]
	v_mfma_f32_16x16x32_bf16 v[0:3], v[194:197], v[226:229], v[0:3]
	v_mfma_f32_16x16x32_bf16 v[52:55], v[190:193], v[206:209], v[52:55]
	v_mfma_f32_16x16x32_bf16 v[48:51], v[198:201], v[206:209], v[48:51]
	v_mfma_f32_16x16x32_bf16 v[36:39], v[190:193], v[214:217], v[36:39]
	v_mfma_f32_16x16x32_bf16 v[32:35], v[198:201], v[214:217], v[32:35]
	v_mfma_f32_16x16x32_bf16 v[20:23], v[190:193], v[222:225], v[20:23]
	v_mfma_f32_16x16x32_bf16 v[16:19], v[198:201], v[222:225], v[16:19]
	v_mfma_f32_16x16x32_bf16 v[4:7], v[190:193], v[230:233], v[4:7]
	v_mfma_f32_16x16x32_bf16 v[0:3], v[198:201], v[230:233], v[0:3]
	s_barrier
; #define PG8_STAGE(bufoff, gbase, voff) do { _Pragma("unroll") for (int _i = 0; _i < 2; ++_i) \
;         __builtin_amdgcn_global_load_lds((const unsigned*)((const char*)(gbase) + (voff)[_i]), (LAS unsigned*)(lds + (bufoff) + ldsw + _i * 8192), 16, 0, 0); } while (0)
; #define PG8_LDA(dst, b, h) do { _Pragma("unroll") for (int m = 0; m < 4; ++m) _Pragma("unroll") for (int k = 0; k < 2; ++k) dst[m][k] = *(const LAS bf16x8*)(lds + PG8_SA(b, h) + aoff + m * 2048 + k * 1024); } while (0)
; #define PG8_LDB(dst, b, h) do { _Pragma("unroll") for (int n = 0; n < 2; ++n) _Pragma("unroll") for (int k = 0; k < 2; ++k) dst[n][k] = *(const LAS bf16x8*)(lds + PG8_SB(b, h) + boff + n * 2048 + k * 1024); } while (0)
; #define PG8_MMA(ai, bj, At, Bt) do { __builtin_amdgcn_s_setprio(1); _Pragma("unroll") for (int m = 0; m < 4; ++m) _Pragma("unroll") for (int n = 0; n < 2; ++n) _Pragma("unroll") for (int k = 0; k < 2; ++k) \
;         acc[ai][bj][m][n] = __builtin_amdgcn_mfma_f32_16x16x32_bf16(Bt[n][k], At[m][k], acc[ai][bj][m][n], 0, 0, 0); __builtin_amdgcn_s_setprio(0); } while (0)
; #define PG8_WAIT_V(n) asm volatile("s_waitcnt vmcnt(" #n ")" ::: "memory")
; #define PG8_WAIT_L(n) asm volatile("s_waitcnt lgkmcnt(" #n ")" ::: "memory")
; #define PG8_BAR __builtin_amdgcn_s_barrier()
; #define PG8_SCHED __builtin_amdgcn_sched_barrier(0)
; template <class Epi, class Sched, bool ALIGN_EPI>
; __device__ __forceinline__ void gemm_phase(LAS unsigned char* lds, const Gemm g, const Sched& S, const Epi& E, const int wid) {
;     ...
;             PG8_LDB(B0, 1, 0); PG8_LDB(B1, 1, 1); PG8_SCHED; PG8_LDA(At, 1, 0); PG8_STAGE(PG8_SA(0, 1), a2 + hstepA, voffA);
;             PG8_WAIT_V(8); PG8_WAIT_L(0); PG8_BAR; PG8_MMA(0, 0, At, B0); PG8_MMA(0, 1, At, B1); PG8_BAR; PG8_SCHED;
;             PG8_LDA(At, 1, 1); PG8_STAGE(PG8_SB(1, 0), b3, voffB); PG8_STAGE(PG8_SB(1, 1), b3 + hstepB, voffB); PG8_STAGE(PG8_SA(1, 0), a3, voffA);
;             PG8_WAIT_V(8); PG8_WAIT_L(0); PG8_BAR; PG8_MMA(1, 0, At, B0); PG8_MMA(1, 1, At, B1); PG8_BAR; PG8_SCHED;
;         }
	s_setprio 0
	s_add_i32 s38, 0, 0x18000
	v_add_u32_e32 v142, s38, v170
	s_add_i32 s39, 0, 0x1c000
	ds_read_b128 v[130:133], v142
	ds_read_b128 v[134:137], v142 offset:1024
	ds_read_b128 v[138:141], v142 offset:2048
	ds_read_b128 v[182:185], v142 offset:3072
	v_add_u32_e32 v142, s39, v170
	ds_read_b128 v[186:189], v142
	ds_read_b128 v[190:193], v142 offset:1024
	ds_read_b128 v[194:197], v142 offset:2048
	ds_read_b128 v[198:201], v142 offset:3072
	s_add_u32 s74, s74, 0x4000
	s_addc_u32 s75, s75, 0
	s_mov_b32 m0, s46
	ds_read_b128 v[202:205], v177 offset:32768
	ds_read_b128 v[206:209], v177 offset:33792
	ds_read_b128 v[210:213], v177 offset:34816
	ds_read_b128 v[214:217], v177 offset:35840
	ds_read_b128 v[218:221], v177 offset:36864
	ds_read_b128 v[222:225], v177 offset:37888
	ds_read_b128 v[226:229], v177 offset:38912
	ds_read_b128 v[230:233], v177 offset:39936
	global_load_lds_dwordx4 v144, s[74:75]
	s_mov_b32 m0, s47
	s_nop 0
	global_load_lds_dwordx4 v148, s[74:75]
	s_waitcnt vmcnt(8)
	s_waitcnt lgkmcnt(0)
	s_setprio 1
	s_barrier
	v_mfma_f32_16x16x32_bf16 v[124:127], v[130:133], v[202:205], v[124:127]
	v_mfma_f32_16x16x32_bf16 v[120:123], v[138:141], v[202:205], v[120:123]
	v_mfma_f32_16x16x32_bf16 v[108:111], v[130:133], v[210:213], v[108:111]
	v_mfma_f32_16x16x32_bf16 v[104:107], v[138:141], v[210:213], v[104:107]
	v_mfma_f32_16x16x32_bf16 v[92:95], v[130:133], v[218:221], v[92:95]
	v_mfma_f32_16x16x32_bf16 v[88:91], v[138:141], v[218:221], v[88:91]
	v_mfma_f32_16x16x32_bf16 v[76:79], v[130:133], v[226:229], v[76:79]
	v_mfma_f32_16x16x32_bf16 v[72:75], v[138:141], v[226:229], v[72:75]
	v_mfma_f32_16x16x32_bf16 v[124:127], v[134:137], v[206:209], v[124:127]
	v_mfma_f32_16x16x32_bf16 v[120:123], v[182:185], v[206:209], v[120:123]
	v_mfma_f32_16x16x32_bf16 v[108:111], v[134:137], v[214:217], v[108:111]
	v_mfma_f32_16x16x32_bf16 v[104:107], v[182:185], v[214:217], v[104:107]
	v_mfma_f32_16x16x32_bf16 v[92:95], v[134:137], v[222:225], v[92:95]
	v_mfma_f32_16x16x32_bf16 v[88:91], v[182:185], v[222:225], v[88:91]
	v_mfma_f32_16x16x32_bf16 v[76:79], v[134:137], v[230:233], v[76:79]
	v_mfma_f32_16x16x32_bf16 v[72:75], v[182:185], v[230:233], v[72:75]
	v_mfma_f32_16x16x32_bf16 v[116:119], v[186:189], v[202:205], v[116:119]
	v_mfma_f32_16x16x32_bf16 v[112:115], v[194:197], v[202:205], v[112:115]
	v_mfma_f32_16x16x32_bf16 v[100:103], v[186:189], v[210:213], v[100:103]
	v_mfma_f32_16x16x32_bf16 v[96:99], v[194:197], v[210:213], v[96:99]
	v_mfma_f32_16x16x32_bf16 v[84:87], v[186:189], v[218:221], v[84:87]
	v_mfma_f32_16x16x32_bf16 v[80:83], v[194:197], v[218:221], v[80:83]
	v_mfma_f32_16x16x32_bf16 v[68:71], v[186:189], v[226:229], v[68:71]
	v_mfma_f32_16x16x32_bf16 v[64:67], v[194:197], v[226:229], v[64:67]
	v_mfma_f32_16x16x32_bf16 v[116:119], v[190:193], v[206:209], v[116:119]
	v_mfma_f32_16x16x32_bf16 v[112:115], v[198:201], v[206:209], v[112:115]
	v_mfma_f32_16x16x32_bf16 v[100:103], v[190:193], v[214:217], v[100:103]
	v_mfma_f32_16x16x32_bf16 v[96:99], v[198:201], v[214:217], v[96:99]
	v_mfma_f32_16x16x32_bf16 v[84:87], v[190:193], v[222:225], v[84:87]
	v_mfma_f32_16x16x32_bf16 v[80:83], v[198:201], v[222:225], v[80:83]
	v_mfma_f32_16x16x32_bf16 v[68:71], v[190:193], v[230:233], v[68:71]
	v_mfma_f32_16x16x32_bf16 v[64:67], v[198:201], v[230:233], v[64:67]
	s_barrier
	s_setprio 0
	s_add_u32 s74, s72, 0x8000
	s_addc_u32 s75, s73, 0
	s_add_i32 s38, s38, s3
	s_mov_b32 m0, s38
	ds_read_b128 v[202:205], v177 offset:49152
	ds_read_b128 v[206:209], v177 offset:50176
	ds_read_b128 v[210:213], v177 offset:51200
	ds_read_b128 v[214:217], v177 offset:52224
	ds_read_b128 v[218:221], v177 offset:53248
	ds_read_b128 v[222:225], v177 offset:54272
	ds_read_b128 v[226:229], v177 offset:55296
	ds_read_b128 v[230:233], v177 offset:56320
	global_load_lds_dwordx4 v146, s[74:75]
	s_add_i32 m0, s38, 0x2000
	s_add_u32 s72, s72, 0x9000
	s_addc_u32 s73, s73, 0
	s_add_i32 s38, s39, s3
	global_load_lds_dwordx4 v150, s[74:75]
	s_mov_b32 m0, s38
	s_nop 0
	global_load_lds_dwordx4 v146, s[72:73]
	s_add_i32 m0, s38, 0x2000
	s_nop 0
	global_load_lds_dwordx4 v150, s[72:73]
	s_mov_b32 m0, s79
	s_nop 0
	global_load_lds_dwordx4 v144, s[70:71]
	s_mov_b32 m0, s80
	s_nop 0
	global_load_lds_dwordx4 v148, s[70:71]
	s_waitcnt vmcnt(8)
	s_waitcnt lgkmcnt(0)
	s_setprio 1
	s_barrier
	v_mfma_f32_16x16x32_bf16 v[60:63], v[130:133], v[202:205], v[60:63]
	v_mfma_f32_16x16x32_bf16 v[56:59], v[138:141], v[202:205], v[56:59]
	v_mfma_f32_16x16x32_bf16 v[44:47], v[130:133], v[210:213], v[44:47]
	v_mfma_f32_16x16x32_bf16 v[40:43], v[138:141], v[210:213], v[40:43]
	v_mfma_f32_16x16x32_bf16 v[28:31], v[130:133], v[218:221], v[28:31]
	v_mfma_f32_16x16x32_bf16 v[24:27], v[138:141], v[218:221], v[24:27]
	v_mfma_f32_16x16x32_bf16 v[12:15], v[130:133], v[226:229], v[12:15]
	v_mfma_f32_16x16x32_bf16 v[8:11], v[138:141], v[226:229], v[8:11]
	v_mfma_f32_16x16x32_bf16 v[60:63], v[134:137], v[206:209], v[60:63]
	v_mfma_f32_16x16x32_bf16 v[56:59], v[182:185], v[206:209], v[56:59]
	v_mfma_f32_16x16x32_bf16 v[44:47], v[134:137], v[214:217], v[44:47]
	v_mfma_f32_16x16x32_bf16 v[40:43], v[182:185], v[214:217], v[40:43]
	v_mfma_f32_16x16x32_bf16 v[28:31], v[134:137], v[222:225], v[28:31]
	v_mfma_f32_16x16x32_bf16 v[24:27], v[182:185], v[222:225], v[24:27]
	v_mfma_f32_16x16x32_bf16 v[12:15], v[134:137], v[230:233], v[12:15]
	v_mfma_f32_16x16x32_bf16 v[8:11], v[182:185], v[230:233], v[8:11]
	v_mfma_f32_16x16x32_bf16 v[52:55], v[186:189], v[202:205], v[52:55]
	v_mfma_f32_16x16x32_bf16 v[48:51], v[194:197], v[202:205], v[48:51]
	v_mfma_f32_16x16x32_bf16 v[36:39], v[186:189], v[210:213], v[36:39]
	v_mfma_f32_16x16x32_bf16 v[32:35], v[194:197], v[210:213], v[32:35]
	v_mfma_f32_16x16x32_bf16 v[20:23], v[186:189], v[218:221], v[20:23]
	v_mfma_f32_16x16x32_bf16 v[16:19], v[194:197], v[218:221], v[16:19]
	v_mfma_f32_16x16x32_bf16 v[4:7], v[186:189], v[226:229], v[4:7]
	v_mfma_f32_16x16x32_bf16 v[0:3], v[194:197], v[226:229], v[0:3]
	v_mfma_f32_16x16x32_bf16 v[52:55], v[190:193], v[206:209], v[52:55]
	v_mfma_f32_16x16x32_bf16 v[48:51], v[198:201], v[206:209], v[48:51]
	v_mfma_f32_16x16x32_bf16 v[36:39], v[190:193], v[214:217], v[36:39]
	v_mfma_f32_16x16x32_bf16 v[32:35], v[198:201], v[214:217], v[32:35]
	v_mfma_f32_16x16x32_bf16 v[20:23], v[190:193], v[222:225], v[20:23]
	v_mfma_f32_16x16x32_bf16 v[16:19], v[198:201], v[222:225], v[16:19]
	v_mfma_f32_16x16x32_bf16 v[4:7], v[190:193], v[230:233], v[4:7]
	v_mfma_f32_16x16x32_bf16 v[0:3], v[198:201], v[230:233], v[0:3]
	s_barrier
	s_setprio 0
	s_add_i32 s54, s54, 2
	s_add_u32 s68, s68, 0x10000
	s_addc_u32 s69, s69, 0
	s_add_u32 s31, s31, 0x10000
	s_addc_u32 s35, s35, 0
	s_cmp_gt_u32 s54, 61
	s_cbranch_scc1 .LBB0_923

; #define PG8_STAGE(bufoff, gbase, voff) do { _Pragma("unroll") for (int _i = 0; _i < 2; ++_i) \
;         __builtin_amdgcn_global_load_lds((const unsigned*)((const char*)(gbase) + (voff)[_i]), (LAS unsigned*)(lds + (bufoff) + ldsw + _i * 8192), 16, 0, 0); } while (0)
; #define PG8_LDA(dst, b, h) do { _Pragma("unroll") for (int m = 0; m < 4; ++m) _Pragma("unroll") for (int k = 0; k < 2; ++k) dst[m][k] = *(const LAS bf16x8*)(lds + PG8_SA(b, h) + aoff + m * 2048 + k * 1024); } while (0)
; #define PG8_LDB(dst, b, h) do { _Pragma("unroll") for (int n = 0; n < 2; ++n) _Pragma("unroll") for (int k = 0; k < 2; ++k) dst[n][k] = *(const LAS bf16x8*)(lds + PG8_SB(b, h) + boff + n * 2048 + k * 1024); } while (0)
; #define PG8_MMA(ai, bj, At, Bt) do { __builtin_amdgcn_s_setprio(1); _Pragma("unroll") for (int m = 0; m < 4; ++m) _Pragma("unroll") for (int n = 0; n < 2; ++n) _Pragma("unroll") for (int k = 0; k < 2; ++k) \
;         acc[ai][bj][m][n] = __builtin_amdgcn_mfma_f32_16x16x32_bf16(Bt[n][k], At[m][k], acc[ai][bj][m][n], 0, 0, 0); __builtin_amdgcn_s_setprio(0); } while (0)
; #define PG8_WAIT_V(n) asm volatile("s_waitcnt vmcnt(" #n ")" ::: "memory")
; #define PG8_WAIT_L(n) asm volatile("s_waitcnt lgkmcnt(" #n ")" ::: "memory")
; #define PG8_BAR __builtin_amdgcn_s_barrier()
; #define PG8_SCHED __builtin_amdgcn_sched_barrier(0)
; template <class Epi, class Sched, bool ALIGN_EPI>
; __device__ __forceinline__ void gemm_phase(LAS unsigned char* lds, const Gemm g, const Sched& S, const Epi& E, const int wid) {
;     ...
;             PG8_LDB(B0, 0, 0); PG8_LDB(B1, 0, 1); PG8_SCHED; PG8_LDA(At, 0, 0); PG8_STAGE(PG8_SA(1, 1), a1 + hstepA, voffA);
;             PG8_WAIT_V(8); PG8_WAIT_L(0); PG8_BAR; PG8_MMA(0, 0, At, B0); PG8_MMA(0, 1, At, B1); PG8_BAR; PG8_SCHED;
;             PG8_LDA(At, 0, 1); PG8_STAGE(PG8_SB(0, 0), b2, voffB); PG8_STAGE(PG8_SB(0, 1), b2 + hstepB, voffB); PG8_STAGE(PG8_SA(0, 0), a2, voffA);
;             PG8_WAIT_V(8); PG8_WAIT_L(0); PG8_BAR; PG8_MMA(1, 0, At, B0); PG8_MMA(1, 1, At, B1); PG8_BAR; PG8_SCHED;
;             PG8_LDB(B0, 1, 0); PG8_LDB(B1, 1, 1); PG8_SCHED; PG8_LDA(At, 1, 0); PG8_STAGE(PG8_SA(0, 1), a2 + hstepA, voffA);
;             PG8_WAIT_V(8); PG8_WAIT_L(0); PG8_BAR; PG8_MMA(0, 0, At, B0); PG8_MMA(0, 1, At, B1); PG8_BAR; PG8_SCHED;
.LBB0_1438:
	ds_read_b128 v[72:75], v202
	ds_read_b128 v[76:79], v202 offset:1024
	ds_read_b128 v[136:139], v202 offset:2048
	ds_read_b128 v[140:143], v202 offset:3072
	ds_read_b128 v[144:147], v203
	ds_read_b128 v[148:151], v203 offset:1024
	ds_read_b128 v[152:155], v203 offset:2048
	ds_read_b128 v[178:181], v203 offset:3072
	s_add_u32 s38, s20, 0xfff00080
	s_addc_u32 s39, s21, -1
	s_cmp_eq_u32 s55, 60
	s_cselect_b32 s71, s4, s39
	s_cselect_b32 s70, s5, s38
	s_cselect_b32 s69, s30, s54
	s_cselect_b32 s68, s31, s35
	s_add_i32 m0, s44, 0xc000
	ds_read_b128 v[182:185], v204
	ds_read_b128 v[186:189], v204 offset:1024
	ds_read_b128 v[190:193], v204 offset:2048
	ds_read_b128 v[194:197], v204 offset:3072
	ds_read_b128 v[208:211], v204 offset:4096
	ds_read_b128 v[212:215], v204 offset:5120
	ds_read_b128 v[216:219], v204 offset:6144
	ds_read_b128 v[220:223], v204 offset:7168
	global_load_lds_dwordx4 v168, s[20:21]
	s_add_i32 m0, s44, 0xe000
	s_nop 0
	global_load_lds_dwordx4 v170, s[20:21]
	s_waitcnt vmcnt(8)
	s_waitcnt lgkmcnt(0)
	s_setprio 1
	s_barrier
	v_mfma_f32_16x16x32_bf16 v[132:135], v[72:75], v[182:185], v[132:135]
	v_mfma_f32_16x16x32_bf16 v[128:131], v[136:139], v[182:185], v[128:131]
	v_mfma_f32_16x16x32_bf16 v[116:119], v[72:75], v[190:193], v[116:119]
	v_mfma_f32_16x16x32_bf16 v[112:115], v[136:139], v[190:193], v[112:115]
	v_mfma_f32_16x16x32_bf16 v[100:103], v[72:75], v[208:211], v[100:103]
	v_mfma_f32_16x16x32_bf16 v[96:99], v[136:139], v[208:211], v[96:99]
	v_mfma_f32_16x16x32_bf16 v[84:87], v[72:75], v[216:219], v[84:87]
	v_mfma_f32_16x16x32_bf16 v[80:83], v[136:139], v[216:219], v[80:83]
	v_mfma_f32_16x16x32_bf16 v[132:135], v[76:79], v[186:189], v[132:135]
	v_mfma_f32_16x16x32_bf16 v[128:131], v[140:143], v[186:189], v[128:131]
	v_mfma_f32_16x16x32_bf16 v[116:119], v[76:79], v[194:197], v[116:119]
	v_mfma_f32_16x16x32_bf16 v[112:115], v[140:143], v[194:197], v[112:115]
	v_mfma_f32_16x16x32_bf16 v[100:103], v[76:79], v[212:215], v[100:103]
	v_mfma_f32_16x16x32_bf16 v[96:99], v[140:143], v[212:215], v[96:99]
	v_mfma_f32_16x16x32_bf16 v[84:87], v[76:79], v[220:223], v[84:87]
	v_mfma_f32_16x16x32_bf16 v[80:83], v[140:143], v[220:223], v[80:83]
	v_mfma_f32_16x16x32_bf16 v[124:127], v[144:147], v[182:185], v[124:127]
	v_mfma_f32_16x16x32_bf16 v[120:123], v[152:155], v[182:185], v[120:123]
	v_mfma_f32_16x16x32_bf16 v[108:111], v[144:147], v[190:193], v[108:111]
	v_mfma_f32_16x16x32_bf16 v[104:107], v[152:155], v[190:193], v[104:107]
	v_mfma_f32_16x16x32_bf16 v[92:95], v[144:147], v[208:211], v[92:95]
	v_mfma_f32_16x16x32_bf16 v[88:91], v[152:155], v[208:211], v[88:91]
	v_mfma_f32_16x16x32_bf16 v[68:71], v[144:147], v[216:219], v[68:71]
	v_mfma_f32_16x16x32_bf16 v[64:67], v[152:155], v[216:219], v[64:67]
	v_mfma_f32_16x16x32_bf16 v[124:127], v[148:151], v[186:189], v[124:127]
	v_mfma_f32_16x16x32_bf16 v[120:123], v[178:181], v[186:189], v[120:123]
	v_mfma_f32_16x16x32_bf16 v[108:111], v[148:151], v[194:197], v[108:111]
	v_mfma_f32_16x16x32_bf16 v[104:107], v[178:181], v[194:197], v[104:107]
	v_mfma_f32_16x16x32_bf16 v[92:95], v[148:151], v[212:215], v[92:95]
	v_mfma_f32_16x16x32_bf16 v[88:91], v[178:181], v[212:215], v[88:91]
	v_mfma_f32_16x16x32_bf16 v[68:71], v[148:151], v[220:223], v[68:71]
	v_mfma_f32_16x16x32_bf16 v[64:67], v[178:181], v[220:223], v[64:67]
	s_barrier
	s_setprio 0
	s_add_i32 s38, s75, s3
	s_mov_b32 m0, s38
	ds_read_b128 v[182:185], v204 offset:16384
	ds_read_b128 v[186:189], v204 offset:17408
	ds_read_b128 v[190:193], v204 offset:18432
	ds_read_b128 v[194:197], v204 offset:19456
	ds_read_b128 v[208:211], v204 offset:20480
	ds_read_b128 v[212:215], v204 offset:21504
	ds_read_b128 v[216:219], v204 offset:22528
	ds_read_b128 v[220:223], v204 offset:23552
	global_load_lds_dwordx4 v158, s[68:69]
	s_add_i32 m0, s38, 0x2000
	s_add_u32 s38, s68, 0x1000
	s_addc_u32 s39, s69, 0
	s_add_i32 s57, s76, s3
	global_load_lds_dwordx4 v162, s[68:69]
	s_mov_b32 m0, s57
	v_lshl_add_u64 v[226:227], s[70:71], 0, v[160:161]
	global_load_lds_dwordx4 v158, s[38:39]
	s_add_i32 m0, s57, 0x2000
	s_nop 0
	global_load_lds_dwordx4 v162, s[38:39]
	v_lshl_add_u64 v[224:225], s[70:71], 0, v[156:157]
	s_mov_b32 m0, s44
	s_nop 0
	global_load_lds_dwordx4 v[224:225], off
	s_mov_b32 m0, s45
	s_nop 0
	global_load_lds_dwordx4 v[226:227], off
	s_waitcnt vmcnt(8)
	s_waitcnt lgkmcnt(0)
	s_setprio 1
	s_barrier
	v_mfma_f32_16x16x32_bf16 v[60:63], v[72:75], v[182:185], v[60:63]
	v_mfma_f32_16x16x32_bf16 v[56:59], v[136:139], v[182:185], v[56:59]
	v_mfma_f32_16x16x32_bf16 v[44:47], v[72:75], v[190:193], v[44:47]
	v_mfma_f32_16x16x32_bf16 v[40:43], v[136:139], v[190:193], v[40:43]
	v_mfma_f32_16x16x32_bf16 v[28:31], v[72:75], v[208:211], v[28:31]
	v_mfma_f32_16x16x32_bf16 v[24:27], v[136:139], v[208:211], v[24:27]
	v_mfma_f32_16x16x32_bf16 v[12:15], v[72:75], v[216:219], v[12:15]
	v_mfma_f32_16x16x32_bf16 v[8:11], v[136:139], v[216:219], v[8:11]
	v_mfma_f32_16x16x32_bf16 v[60:63], v[76:79], v[186:189], v[60:63]
	v_mfma_f32_16x16x32_bf16 v[56:59], v[140:143], v[186:189], v[56:59]
	v_mfma_f32_16x16x32_bf16 v[44:47], v[76:79], v[194:197], v[44:47]
	v_mfma_f32_16x16x32_bf16 v[40:43], v[140:143], v[194:197], v[40:43]
	v_mfma_f32_16x16x32_bf16 v[28:31], v[76:79], v[212:215], v[28:31]
	v_mfma_f32_16x16x32_bf16 v[24:27], v[140:143], v[212:215], v[24:27]
	v_mfma_f32_16x16x32_bf16 v[12:15], v[76:79], v[220:223], v[12:15]
	v_mfma_f32_16x16x32_bf16 v[8:11], v[140:143], v[220:223], v[8:11]
	v_mfma_f32_16x16x32_bf16 v[52:55], v[144:147], v[182:185], v[52:55]
	v_mfma_f32_16x16x32_bf16 v[48:51], v[152:155], v[182:185], v[48:51]
	v_mfma_f32_16x16x32_bf16 v[36:39], v[144:147], v[190:193], v[36:39]
	v_mfma_f32_16x16x32_bf16 v[32:35], v[152:155], v[190:193], v[32:35]
	v_mfma_f32_16x16x32_bf16 v[20:23], v[144:147], v[208:211], v[20:23]
	v_mfma_f32_16x16x32_bf16 v[16:19], v[152:155], v[208:211], v[16:19]
	v_mfma_f32_16x16x32_bf16 v[4:7], v[144:147], v[216:219], v[4:7]
	v_mfma_f32_16x16x32_bf16 v[0:3], v[152:155], v[216:219], v[0:3]
	v_mfma_f32_16x16x32_bf16 v[52:55], v[148:151], v[186:189], v[52:55]
	v_mfma_f32_16x16x32_bf16 v[48:51], v[178:181], v[186:189], v[48:51]
	v_mfma_f32_16x16x32_bf16 v[36:39], v[148:151], v[194:197], v[36:39]
	v_mfma_f32_16x16x32_bf16 v[32:35], v[178:181], v[194:197], v[32:35]
	v_mfma_f32_16x16x32_bf16 v[20:23], v[148:151], v[212:215], v[20:23]
	v_mfma_f32_16x16x32_bf16 v[16:19], v[178:181], v[212:215], v[16:19]
	v_mfma_f32_16x16x32_bf16 v[4:7], v[148:151], v[220:223], v[4:7]
	v_mfma_f32_16x16x32_bf16 v[0:3], v[178:181], v[220:223], v[0:3]
	s_barrier
; #define PG8_STAGE(bufoff, gbase, voff) do { _Pragma("unroll") for (int _i = 0; _i < 2; ++_i) \
;         __builtin_amdgcn_global_load_lds((const unsigned*)((const char*)(gbase) + (voff)[_i]), (LAS unsigned*)(lds + (bufoff) + ldsw + _i * 8192), 16, 0, 0); } while (0)
; #define PG8_LDA(dst, b, h) do { _Pragma("unroll") for (int m = 0; m < 4; ++m) _Pragma("unroll") for (int k = 0; k < 2; ++k) dst[m][k] = *(const LAS bf16x8*)(lds + PG8_SA(b, h) + aoff + m * 2048 + k * 1024); } while (0)
; #define PG8_LDB(dst, b, h) do { _Pragma("unroll") for (int n = 0; n < 2; ++n) _Pragma("unroll") for (int k = 0; k < 2; ++k) dst[n][k] = *(const LAS bf16x8*)(lds + PG8_SB(b, h) + boff + n * 2048 + k * 1024); } while (0)
; #define PG8_MMA(ai, bj, At, Bt) do { __builtin_amdgcn_s_setprio(1); _Pragma("unroll") for (int m = 0; m < 4; ++m) _Pragma("unroll") for (int n = 0; n < 2; ++n) _Pragma("unroll") for (int k = 0; k < 2; ++k) \
;         acc[ai][bj][m][n] = __builtin_amdgcn_mfma_f32_16x16x32_bf16(Bt[n][k], At[m][k], acc[ai][bj][m][n], 0, 0, 0); __builtin_amdgcn_s_setprio(0); } while (0)
; #define PG8_WAIT_V(n) asm volatile("s_waitcnt vmcnt(" #n ")" ::: "memory")
; #define PG8_WAIT_L(n) asm volatile("s_waitcnt lgkmcnt(" #n ")" ::: "memory")
; #define PG8_BAR __builtin_amdgcn_s_barrier()
; #define PG8_SCHED __builtin_amdgcn_sched_barrier(0)
; template <class Epi, class Sched, bool ALIGN_EPI>
; __device__ __forceinline__ void gemm_phase(LAS unsigned char* lds, const Gemm g, const Sched& S, const Epi& E, const int wid) {
;     ...
;             PG8_LDB(B0, 1, 0); PG8_LDB(B1, 1, 1); PG8_SCHED; PG8_LDA(At, 1, 0); PG8_STAGE(PG8_SA(0, 1), a2 + hstepA, voffA);
;             PG8_WAIT_V(8); PG8_WAIT_L(0); PG8_BAR; PG8_MMA(0, 0, At, B0); PG8_MMA(0, 1, At, B1); PG8_BAR; PG8_SCHED;
;             PG8_LDA(At, 1, 1); PG8_STAGE(PG8_SB(1, 0), b3, voffB); PG8_STAGE(PG8_SB(1, 1), b3 + hstepB, voffB); PG8_STAGE(PG8_SA(1, 0), a3, voffA);
;             PG8_WAIT_V(8); PG8_WAIT_L(0); PG8_BAR; PG8_MMA(1, 0, At, B0); PG8_MMA(1, 1, At, B1); PG8_BAR; PG8_SCHED;
;         }
	s_setprio 0
	s_add_i32 s57, 0, 0x18000
	s_add_i32 s59, 0, 0x1c000
	v_add_u32_e32 v140, s57, v198
	v_add_u32_e32 v164, s59, v198
	ds_read_b128 v[72:75], v140
	ds_read_b128 v[76:79], v140 offset:1024
	ds_read_b128 v[136:139], v140 offset:2048
	ds_read_b128 v[140:143], v140 offset:3072
	ds_read_b128 v[144:147], v164
	ds_read_b128 v[148:151], v164 offset:1024
	ds_read_b128 v[152:155], v164 offset:2048
	ds_read_b128 v[178:181], v164 offset:3072
	s_add_u32 s38, s70, 0x100000
	s_addc_u32 s39, s71, 0
	s_mov_b32 m0, s46
	ds_read_b128 v[182:185], v204 offset:32768
	ds_read_b128 v[186:189], v204 offset:33792
	ds_read_b128 v[190:193], v204 offset:34816
	ds_read_b128 v[194:197], v204 offset:35840
	ds_read_b128 v[208:211], v204 offset:36864
	ds_read_b128 v[212:215], v204 offset:37888
	ds_read_b128 v[216:219], v204 offset:38912
	ds_read_b128 v[220:223], v204 offset:39936
	global_load_lds_dwordx4 v156, s[38:39]
	s_mov_b32 m0, s47
	s_nop 0
	global_load_lds_dwordx4 v160, s[38:39]
	s_waitcnt vmcnt(8)
	s_waitcnt lgkmcnt(0)
	s_setprio 1
	s_barrier
	v_mfma_f32_16x16x32_bf16 v[132:135], v[72:75], v[182:185], v[132:135]
	v_mfma_f32_16x16x32_bf16 v[128:131], v[136:139], v[182:185], v[128:131]
	v_mfma_f32_16x16x32_bf16 v[116:119], v[72:75], v[190:193], v[116:119]
	v_mfma_f32_16x16x32_bf16 v[112:115], v[136:139], v[190:193], v[112:115]
	v_mfma_f32_16x16x32_bf16 v[100:103], v[72:75], v[208:211], v[100:103]
	v_mfma_f32_16x16x32_bf16 v[96:99], v[136:139], v[208:211], v[96:99]
	v_mfma_f32_16x16x32_bf16 v[84:87], v[72:75], v[216:219], v[84:87]
	v_mfma_f32_16x16x32_bf16 v[80:83], v[136:139], v[216:219], v[80:83]
	v_mfma_f32_16x16x32_bf16 v[132:135], v[76:79], v[186:189], v[132:135]
	v_mfma_f32_16x16x32_bf16 v[128:131], v[140:143], v[186:189], v[128:131]
	v_mfma_f32_16x16x32_bf16 v[116:119], v[76:79], v[194:197], v[116:119]
	v_mfma_f32_16x16x32_bf16 v[112:115], v[140:143], v[194:197], v[112:115]
	v_mfma_f32_16x16x32_bf16 v[100:103], v[76:79], v[212:215], v[100:103]
	v_mfma_f32_16x16x32_bf16 v[96:99], v[140:143], v[212:215], v[96:99]
	v_mfma_f32_16x16x32_bf16 v[84:87], v[76:79], v[220:223], v[84:87]
	v_mfma_f32_16x16x32_bf16 v[80:83], v[140:143], v[220:223], v[80:83]
	v_mfma_f32_16x16x32_bf16 v[124:127], v[144:147], v[182:185], v[124:127]
	v_mfma_f32_16x16x32_bf16 v[120:123], v[152:155], v[182:185], v[120:123]
	v_mfma_f32_16x16x32_bf16 v[108:111], v[144:147], v[190:193], v[108:111]
	v_mfma_f32_16x16x32_bf16 v[104:107], v[152:155], v[190:193], v[104:107]
	v_mfma_f32_16x16x32_bf16 v[92:95], v[144:147], v[208:211], v[92:95]
	v_mfma_f32_16x16x32_bf16 v[88:91], v[152:155], v[208:211], v[88:91]
	v_mfma_f32_16x16x32_bf16 v[68:71], v[144:147], v[216:219], v[68:71]
	v_mfma_f32_16x16x32_bf16 v[64:67], v[152:155], v[216:219], v[64:67]
	v_mfma_f32_16x16x32_bf16 v[124:127], v[148:151], v[186:189], v[124:127]
	v_mfma_f32_16x16x32_bf16 v[120:123], v[178:181], v[186:189], v[120:123]
	v_mfma_f32_16x16x32_bf16 v[108:111], v[148:151], v[194:197], v[108:111]
	v_mfma_f32_16x16x32_bf16 v[104:107], v[178:181], v[194:197], v[104:107]
	v_mfma_f32_16x16x32_bf16 v[92:95], v[148:151], v[212:215], v[92:95]
	v_mfma_f32_16x16x32_bf16 v[88:91], v[178:181], v[212:215], v[88:91]
	v_mfma_f32_16x16x32_bf16 v[68:71], v[148:151], v[220:223], v[68:71]
	v_mfma_f32_16x16x32_bf16 v[64:67], v[178:181], v[220:223], v[64:67]
	s_barrier
	s_setprio 0
	s_add_u32 s38, s68, 0x8000
	s_addc_u32 s39, s69, 0
	s_add_i32 s57, s57, s3
	s_mov_b32 m0, s57
	ds_read_b128 v[182:185], v204 offset:49152
	ds_read_b128 v[186:189], v204 offset:50176
	ds_read_b128 v[190:193], v204 offset:51200
	ds_read_b128 v[194:197], v204 offset:52224
	ds_read_b128 v[208:211], v204 offset:53248
	ds_read_b128 v[212:215], v204 offset:54272
	ds_read_b128 v[216:219], v204 offset:55296
	ds_read_b128 v[220:223], v204 offset:56320
	global_load_lds_dwordx4 v158, s[38:39]
	s_add_i32 m0, s57, 0x2000
	s_nop 0
	global_load_lds_dwordx4 v162, s[38:39]
	s_add_u32 s38, s68, 0x9000
	s_addc_u32 s39, s69, 0
	s_add_i32 s57, s59, s3
	s_mov_b32 m0, s57
	v_lshl_add_u64 v[224:225], v[224:225], 0, s[48:49]
	global_load_lds_dwordx4 v158, s[38:39]
	s_add_i32 m0, s57, 0x2000
	s_nop 0
	global_load_lds_dwordx4 v162, s[38:39]
	s_mov_b32 m0, s72
	s_nop 0
	global_load_lds_dwordx4 v[224:225], off
	v_lshl_add_u64 v[224:225], v[226:227], 0, s[48:49]
	s_mov_b32 m0, s73
	s_nop 0
	global_load_lds_dwordx4 v[224:225], off
	s_waitcnt vmcnt(8)
	s_waitcnt lgkmcnt(0)
	s_setprio 1
	s_barrier
	v_mfma_f32_16x16x32_bf16 v[60:63], v[72:75], v[182:185], v[60:63]
	v_mfma_f32_16x16x32_bf16 v[56:59], v[136:139], v[182:185], v[56:59]
	v_mfma_f32_16x16x32_bf16 v[44:47], v[72:75], v[190:193], v[44:47]
	v_mfma_f32_16x16x32_bf16 v[40:43], v[136:139], v[190:193], v[40:43]
	v_mfma_f32_16x16x32_bf16 v[28:31], v[72:75], v[208:211], v[28:31]
	v_mfma_f32_16x16x32_bf16 v[24:27], v[136:139], v[208:211], v[24:27]
	v_mfma_f32_16x16x32_bf16 v[12:15], v[72:75], v[216:219], v[12:15]
	v_mfma_f32_16x16x32_bf16 v[8:11], v[136:139], v[216:219], v[8:11]
	v_mfma_f32_16x16x32_bf16 v[60:63], v[76:79], v[186:189], v[60:63]
	v_mfma_f32_16x16x32_bf16 v[56:59], v[140:143], v[186:189], v[56:59]
	v_mfma_f32_16x16x32_bf16 v[44:47], v[76:79], v[194:197], v[44:47]
	v_mfma_f32_16x16x32_bf16 v[40:43], v[140:143], v[194:197], v[40:43]
	v_mfma_f32_16x16x32_bf16 v[28:31], v[76:79], v[212:215], v[28:31]
	v_mfma_f32_16x16x32_bf16 v[24:27], v[140:143], v[212:215], v[24:27]
	v_mfma_f32_16x16x32_bf16 v[12:15], v[76:79], v[220:223], v[12:15]
	v_mfma_f32_16x16x32_bf16 v[8:11], v[140:143], v[220:223], v[8:11]
	v_mfma_f32_16x16x32_bf16 v[52:55], v[144:147], v[182:185], v[52:55]
	v_mfma_f32_16x16x32_bf16 v[48:51], v[152:155], v[182:185], v[48:51]
	v_mfma_f32_16x16x32_bf16 v[36:39], v[144:147], v[190:193], v[36:39]
	v_mfma_f32_16x16x32_bf16 v[32:35], v[152:155], v[190:193], v[32:35]
	v_mfma_f32_16x16x32_bf16 v[20:23], v[144:147], v[208:211], v[20:23]
	v_mfma_f32_16x16x32_bf16 v[16:19], v[152:155], v[208:211], v[16:19]
	v_mfma_f32_16x16x32_bf16 v[4:7], v[144:147], v[216:219], v[4:7]
	v_mfma_f32_16x16x32_bf16 v[0:3], v[152:155], v[216:219], v[0:3]
	v_mfma_f32_16x16x32_bf16 v[52:55], v[148:151], v[186:189], v[52:55]
	v_mfma_f32_16x16x32_bf16 v[48:51], v[178:181], v[186:189], v[48:51]
	v_mfma_f32_16x16x32_bf16 v[36:39], v[148:151], v[194:197], v[36:39]
	v_mfma_f32_16x16x32_bf16 v[32:35], v[178:181], v[194:197], v[32:35]
	v_mfma_f32_16x16x32_bf16 v[20:23], v[148:151], v[212:215], v[20:23]
	v_mfma_f32_16x16x32_bf16 v[16:19], v[178:181], v[212:215], v[16:19]
	v_mfma_f32_16x16x32_bf16 v[4:7], v[148:151], v[220:223], v[4:7]
	v_mfma_f32_16x16x32_bf16 v[0:3], v[178:181], v[220:223], v[0:3]
	s_barrier
	s_setprio 0
	s_add_i32 s55, s55, 2
	s_add_u32 s20, s20, 0x100
	s_addc_u32 s21, s21, 0
	s_add_u32 s35, s35, 0x10000
	s_addc_u32 s54, s54, 0
	s_cmp_gt_u32 s55, 61
	s_cbranch_scc0 .LBB0_1438
	s_and_b64 vcc, exec, s[28:29]
	s_cbranch_vccz .LBB0_1441
	s_barrier

; #define PG8_STAGE(bufoff, gbase, voff) do { _Pragma("unroll") for (int _i = 0; _i < 2; ++_i) \
;         __builtin_amdgcn_global_load_lds((const unsigned*)((const char*)(gbase) + (voff)[_i]), (LAS unsigned*)(lds + (bufoff) + ldsw + _i * 8192), 16, 0, 0); } while (0)
; #define PG8_LDA(dst, b, h) do { _Pragma("unroll") for (int m = 0; m < 4; ++m) _Pragma("unroll") for (int k = 0; k < 2; ++k) dst[m][k] = *(const LAS bf16x8*)(lds + PG8_SA(b, h) + aoff + m * 2048 + k * 1024); } while (0)
; #define PG8_LDB(dst, b, h) do { _Pragma("unroll") for (int n = 0; n < 2; ++n) _Pragma("unroll") for (int k = 0; k < 2; ++k) dst[n][k] = *(const LAS bf16x8*)(lds + PG8_SB(b, h) + boff + n * 2048 + k * 1024); } while (0)
; #define PG8_MMA(ai, bj, At, Bt) do { __builtin_amdgcn_s_setprio(1); _Pragma("unroll") for (int m = 0; m < 4; ++m) _Pragma("unroll") for (int n = 0; n < 2; ++n) _Pragma("unroll") for (int k = 0; k < 2; ++k) \
;         acc[ai][bj][m][n] = __builtin_amdgcn_mfma_f32_16x16x32_bf16(Bt[n][k], At[m][k], acc[ai][bj][m][n], 0, 0, 0); __builtin_amdgcn_s_setprio(0); } while (0)
; #define PG8_WAIT_V(n) asm volatile("s_waitcnt vmcnt(" #n ")" ::: "memory")
; #define PG8_WAIT_L(n) asm volatile("s_waitcnt lgkmcnt(" #n ")" ::: "memory")
; #define PG8_BAR __builtin_amdgcn_s_barrier()
; #define PG8_SCHED __builtin_amdgcn_sched_barrier(0)
; template <class Epi, class Sched, bool ALIGN_EPI>
; __device__ __forceinline__ void gemm_phase(LAS unsigned char* lds, const Gemm g, const Sched& S, const Epi& E, const int wid) {
;     ...
;             PG8_LDB(B0, 0, 0); PG8_LDB(B1, 0, 1); PG8_SCHED; PG8_LDA(At, 0, 0); PG8_STAGE(PG8_SA(1, 1), a1 + hstepA, voffA);
;             PG8_WAIT_V(8); PG8_WAIT_L(0); PG8_BAR; PG8_MMA(0, 0, At, B0); PG8_MMA(0, 1, At, B1); PG8_BAR; PG8_SCHED;
;             PG8_LDA(At, 0, 1); PG8_STAGE(PG8_SB(0, 0), b2, voffB); PG8_STAGE(PG8_SB(0, 1), b2 + hstepB, voffB); PG8_STAGE(PG8_SA(0, 0), a2, voffA);
;             PG8_WAIT_V(8); PG8_WAIT_L(0); PG8_BAR; PG8_MMA(1, 0, At, B0); PG8_MMA(1, 1, At, B1); PG8_BAR; PG8_SCHED;
;             PG8_LDB(B0, 1, 0); PG8_LDB(B1, 1, 1); PG8_SCHED; PG8_LDA(At, 1, 0); PG8_STAGE(PG8_SA(0, 1), a2 + hstepA, voffA);
;             PG8_WAIT_V(8); PG8_WAIT_L(0); PG8_BAR; PG8_MMA(0, 0, At, B0); PG8_MMA(0, 1, At, B1); PG8_BAR; PG8_SCHED;
.LBB0_1568:
	v_add_u32_e32 v138, s63, v160
	ds_read_b128 v[130:133], v138
	ds_read_b128 v[134:137], v138 offset:1024
	ds_read_b128 v[170:173], v138 offset:2048
	ds_read_b128 v[174:177], v138 offset:3072
	v_add_u32_e32 v138, s64, v160
	s_add_u32 s56, s16, 0x4000
	ds_read_b128 v[178:181], v138
	ds_read_b128 v[182:185], v138 offset:1024
	ds_read_b128 v[186:189], v138 offset:2048
	ds_read_b128 v[190:193], v138 offset:3072
	s_addc_u32 s57, s17, 0
	s_and_b64 s[38:39], s[58:59], exec
	s_cselect_b32 s60, s35, s56
	s_cselect_b32 s61, s27, s57
	s_add_u32 s56, s60, 0x8000
	s_addc_u32 s57, s61, 0
	s_and_b64 s[38:39], s[58:59], exec
	s_cselect_b32 s59, s25, s69
	s_cselect_b32 s58, s53, s68
	s_add_i32 m0, s31, 0xc000
	ds_read_b128 v[194:197], v166
	ds_read_b128 v[198:201], v166 offset:1024
	ds_read_b128 v[202:205], v166 offset:2048
	ds_read_b128 v[206:209], v166 offset:3072
	ds_read_b128 v[210:213], v166 offset:4096
	ds_read_b128 v[214:217], v166 offset:5120
	ds_read_b128 v[218:221], v166 offset:6144
	ds_read_b128 v[222:225], v166 offset:7168
	global_load_lds_dwordx4 v150, s[16:17]
	s_add_i32 m0, s31, 0xe000
	s_nop 0
	global_load_lds_dwordx4 v152, s[16:17]
	s_waitcnt vmcnt(8)
	s_waitcnt lgkmcnt(0)
	s_setprio 1
	s_barrier
	v_mfma_f32_16x16x32_bf16 v[124:127], v[130:133], v[194:197], v[124:127]
	v_mfma_f32_16x16x32_bf16 v[120:123], v[170:173], v[194:197], v[120:123]
	v_mfma_f32_16x16x32_bf16 v[108:111], v[130:133], v[202:205], v[108:111]
	v_mfma_f32_16x16x32_bf16 v[104:107], v[170:173], v[202:205], v[104:107]
	v_mfma_f32_16x16x32_bf16 v[92:95], v[130:133], v[210:213], v[92:95]
	v_mfma_f32_16x16x32_bf16 v[88:91], v[170:173], v[210:213], v[88:91]
	v_mfma_f32_16x16x32_bf16 v[76:79], v[130:133], v[218:221], v[76:79]
	v_mfma_f32_16x16x32_bf16 v[72:75], v[170:173], v[218:221], v[72:75]
	v_mfma_f32_16x16x32_bf16 v[124:127], v[134:137], v[198:201], v[124:127]
	v_mfma_f32_16x16x32_bf16 v[120:123], v[174:177], v[198:201], v[120:123]
	v_mfma_f32_16x16x32_bf16 v[108:111], v[134:137], v[206:209], v[108:111]
	v_mfma_f32_16x16x32_bf16 v[104:107], v[174:177], v[206:209], v[104:107]
	v_mfma_f32_16x16x32_bf16 v[92:95], v[134:137], v[214:217], v[92:95]
	v_mfma_f32_16x16x32_bf16 v[88:91], v[174:177], v[214:217], v[88:91]
	v_mfma_f32_16x16x32_bf16 v[76:79], v[134:137], v[222:225], v[76:79]
	v_mfma_f32_16x16x32_bf16 v[72:75], v[174:177], v[222:225], v[72:75]
	v_mfma_f32_16x16x32_bf16 v[116:119], v[178:181], v[194:197], v[116:119]
	v_mfma_f32_16x16x32_bf16 v[112:115], v[186:189], v[194:197], v[112:115]
	v_mfma_f32_16x16x32_bf16 v[100:103], v[178:181], v[202:205], v[100:103]
	v_mfma_f32_16x16x32_bf16 v[96:99], v[186:189], v[202:205], v[96:99]
	v_mfma_f32_16x16x32_bf16 v[84:87], v[178:181], v[210:213], v[84:87]
	v_mfma_f32_16x16x32_bf16 v[80:83], v[186:189], v[210:213], v[80:83]
	v_mfma_f32_16x16x32_bf16 v[68:71], v[178:181], v[218:221], v[68:71]
	v_mfma_f32_16x16x32_bf16 v[64:67], v[186:189], v[218:221], v[64:67]
	v_mfma_f32_16x16x32_bf16 v[116:119], v[182:185], v[198:201], v[116:119]
	v_mfma_f32_16x16x32_bf16 v[112:115], v[190:193], v[198:201], v[112:115]
	v_mfma_f32_16x16x32_bf16 v[100:103], v[182:185], v[206:209], v[100:103]
	v_mfma_f32_16x16x32_bf16 v[96:99], v[190:193], v[206:209], v[96:99]
	v_mfma_f32_16x16x32_bf16 v[84:87], v[182:185], v[214:217], v[84:87]
	v_mfma_f32_16x16x32_bf16 v[80:83], v[190:193], v[214:217], v[80:83]
	v_mfma_f32_16x16x32_bf16 v[68:71], v[182:185], v[222:225], v[68:71]
	v_mfma_f32_16x16x32_bf16 v[64:67], v[190:193], v[222:225], v[64:67]
	s_barrier
	s_setprio 0
	s_add_i32 s38, s63, s3
	s_mov_b32 m0, s38
	ds_read_b128 v[194:197], v166 offset:16384
	ds_read_b128 v[198:201], v166 offset:17408
	ds_read_b128 v[202:205], v166 offset:18432
	ds_read_b128 v[206:209], v166 offset:19456
	ds_read_b128 v[210:213], v166 offset:20480
	ds_read_b128 v[214:217], v166 offset:21504
	ds_read_b128 v[218:221], v166 offset:22528
	ds_read_b128 v[222:225], v166 offset:23552
	global_load_lds_dwordx4 v144, s[58:59]
	s_add_i32 m0, s38, 0x2000
	s_add_u32 s38, s58, 0x1000
	s_addc_u32 s39, s59, 0
	s_add_i32 s71, s64, s3
	global_load_lds_dwordx4 v140, s[58:59]
	s_mov_b32 m0, s71
	s_nop 0
	global_load_lds_dwordx4 v144, s[38:39]
	s_add_i32 m0, s71, 0x2000
	s_nop 0
	global_load_lds_dwordx4 v140, s[38:39]
	s_mov_b32 m0, s31
	s_nop 0
	global_load_lds_dwordx4 v146, s[60:61]
	s_mov_b32 m0, s42
	s_nop 0
	global_load_lds_dwordx4 v142, s[60:61]
	s_waitcnt vmcnt(8)
	s_waitcnt lgkmcnt(0)
	s_setprio 1
	s_barrier
	v_mfma_f32_16x16x32_bf16 v[60:63], v[130:133], v[194:197], v[60:63]
	v_mfma_f32_16x16x32_bf16 v[56:59], v[170:173], v[194:197], v[56:59]
	v_mfma_f32_16x16x32_bf16 v[44:47], v[130:133], v[202:205], v[44:47]
	v_mfma_f32_16x16x32_bf16 v[40:43], v[170:173], v[202:205], v[40:43]
	v_mfma_f32_16x16x32_bf16 v[28:31], v[130:133], v[210:213], v[28:31]
	v_mfma_f32_16x16x32_bf16 v[24:27], v[170:173], v[210:213], v[24:27]
	v_mfma_f32_16x16x32_bf16 v[12:15], v[130:133], v[218:221], v[12:15]
	v_mfma_f32_16x16x32_bf16 v[8:11], v[170:173], v[218:221], v[8:11]
	v_mfma_f32_16x16x32_bf16 v[60:63], v[134:137], v[198:201], v[60:63]
	v_mfma_f32_16x16x32_bf16 v[56:59], v[174:177], v[198:201], v[56:59]
	v_mfma_f32_16x16x32_bf16 v[44:47], v[134:137], v[206:209], v[44:47]
	v_mfma_f32_16x16x32_bf16 v[40:43], v[174:177], v[206:209], v[40:43]
	v_mfma_f32_16x16x32_bf16 v[28:31], v[134:137], v[214:217], v[28:31]
	v_mfma_f32_16x16x32_bf16 v[24:27], v[174:177], v[214:217], v[24:27]
	v_mfma_f32_16x16x32_bf16 v[12:15], v[134:137], v[222:225], v[12:15]
	v_mfma_f32_16x16x32_bf16 v[8:11], v[174:177], v[222:225], v[8:11]
	v_mfma_f32_16x16x32_bf16 v[52:55], v[178:181], v[194:197], v[52:55]
	v_mfma_f32_16x16x32_bf16 v[48:51], v[186:189], v[194:197], v[48:51]
	v_mfma_f32_16x16x32_bf16 v[36:39], v[178:181], v[202:205], v[36:39]
	v_mfma_f32_16x16x32_bf16 v[32:35], v[186:189], v[202:205], v[32:35]
	v_mfma_f32_16x16x32_bf16 v[20:23], v[178:181], v[210:213], v[20:23]
	v_mfma_f32_16x16x32_bf16 v[16:19], v[186:189], v[210:213], v[16:19]
	v_mfma_f32_16x16x32_bf16 v[4:7], v[178:181], v[218:221], v[4:7]
	v_mfma_f32_16x16x32_bf16 v[0:3], v[186:189], v[218:221], v[0:3]
	v_mfma_f32_16x16x32_bf16 v[52:55], v[182:185], v[198:201], v[52:55]
	v_mfma_f32_16x16x32_bf16 v[48:51], v[190:193], v[198:201], v[48:51]
	v_mfma_f32_16x16x32_bf16 v[36:39], v[182:185], v[206:209], v[36:39]
	v_mfma_f32_16x16x32_bf16 v[32:35], v[190:193], v[206:209], v[32:35]
	v_mfma_f32_16x16x32_bf16 v[20:23], v[182:185], v[214:217], v[20:23]
	v_mfma_f32_16x16x32_bf16 v[16:19], v[190:193], v[214:217], v[16:19]
	v_mfma_f32_16x16x32_bf16 v[4:7], v[182:185], v[222:225], v[4:7]
	v_mfma_f32_16x16x32_bf16 v[0:3], v[190:193], v[222:225], v[0:3]
	s_barrier
; #define PG8_STAGE(bufoff, gbase, voff) do { _Pragma("unroll") for (int _i = 0; _i < 2; ++_i) \
;         __builtin_amdgcn_global_load_lds((const unsigned*)((const char*)(gbase) + (voff)[_i]), (LAS unsigned*)(lds + (bufoff) + ldsw + _i * 8192), 16, 0, 0); } while (0)
; #define PG8_LDA(dst, b, h) do { _Pragma("unroll") for (int m = 0; m < 4; ++m) _Pragma("unroll") for (int k = 0; k < 2; ++k) dst[m][k] = *(const LAS bf16x8*)(lds + PG8_SA(b, h) + aoff + m * 2048 + k * 1024); } while (0)
; #define PG8_LDB(dst, b, h) do { _Pragma("unroll") for (int n = 0; n < 2; ++n) _Pragma("unroll") for (int k = 0; k < 2; ++k) dst[n][k] = *(const LAS bf16x8*)(lds + PG8_SB(b, h) + boff + n * 2048 + k * 1024); } while (0)
; #define PG8_MMA(ai, bj, At, Bt) do { __builtin_amdgcn_s_setprio(1); _Pragma("unroll") for (int m = 0; m < 4; ++m) _Pragma("unroll") for (int n = 0; n < 2; ++n) _Pragma("unroll") for (int k = 0; k < 2; ++k) \
;         acc[ai][bj][m][n] = __builtin_amdgcn_mfma_f32_16x16x32_bf16(Bt[n][k], At[m][k], acc[ai][bj][m][n], 0, 0, 0); __builtin_amdgcn_s_setprio(0); } while (0)
; #define PG8_WAIT_V(n) asm volatile("s_waitcnt vmcnt(" #n ")" ::: "memory")
; #define PG8_WAIT_L(n) asm volatile("s_waitcnt lgkmcnt(" #n ")" ::: "memory")
; #define PG8_BAR __builtin_amdgcn_s_barrier()
; #define PG8_SCHED __builtin_amdgcn_sched_barrier(0)
; template <class Epi, class Sched, bool ALIGN_EPI>
; __device__ __forceinline__ void gemm_phase(LAS unsigned char* lds, const Gemm g, const Sched& S, const Epi& E, const int wid) {
;     ...
;             PG8_LDB(B0, 1, 0); PG8_LDB(B1, 1, 1); PG8_SCHED; PG8_LDA(At, 1, 0); PG8_STAGE(PG8_SA(0, 1), a2 + hstepA, voffA);
;             PG8_WAIT_V(8); PG8_WAIT_L(0); PG8_BAR; PG8_MMA(0, 0, At, B0); PG8_MMA(0, 1, At, B1); PG8_BAR; PG8_SCHED;
;             PG8_LDA(At, 1, 1); PG8_STAGE(PG8_SB(1, 0), b3, voffB); PG8_STAGE(PG8_SB(1, 1), b3 + hstepB, voffB); PG8_STAGE(PG8_SA(1, 0), a3, voffA);
;             PG8_WAIT_V(8); PG8_WAIT_L(0); PG8_BAR; PG8_MMA(1, 0, At, B0); PG8_MMA(1, 1, At, B1); PG8_BAR; PG8_SCHED;
;         }
	s_setprio 0
	s_add_i32 s71, 0, 0x18000
	v_add_u32_e32 v138, s71, v160
	s_add_i32 s72, 0, 0x1c000
	ds_read_b128 v[130:133], v138
	ds_read_b128 v[134:137], v138 offset:1024
	ds_read_b128 v[170:173], v138 offset:2048
	ds_read_b128 v[174:177], v138 offset:3072
	v_add_u32_e32 v138, s72, v160
	ds_read_b128 v[178:181], v138
	ds_read_b128 v[182:185], v138 offset:1024
	ds_read_b128 v[186:189], v138 offset:2048
	ds_read_b128 v[190:193], v138 offset:3072
	s_add_u32 s38, s60, 0x4000
	s_addc_u32 s39, s61, 0
	s_mov_b32 m0, s43
	ds_read_b128 v[194:197], v166 offset:32768
	ds_read_b128 v[198:201], v166 offset:33792
	ds_read_b128 v[202:205], v166 offset:34816
	ds_read_b128 v[206:209], v166 offset:35840
	ds_read_b128 v[210:213], v166 offset:36864
	ds_read_b128 v[214:217], v166 offset:37888
	ds_read_b128 v[218:221], v166 offset:38912
	ds_read_b128 v[222:225], v166 offset:39936
	global_load_lds_dwordx4 v146, s[38:39]
	s_mov_b32 m0, s44
	s_nop 0
	global_load_lds_dwordx4 v142, s[38:39]
	s_waitcnt vmcnt(8)
	s_waitcnt lgkmcnt(0)
	s_setprio 1
	s_barrier
	v_mfma_f32_16x16x32_bf16 v[124:127], v[130:133], v[194:197], v[124:127]
	v_mfma_f32_16x16x32_bf16 v[120:123], v[170:173], v[194:197], v[120:123]
	v_mfma_f32_16x16x32_bf16 v[108:111], v[130:133], v[202:205], v[108:111]
	v_mfma_f32_16x16x32_bf16 v[104:107], v[170:173], v[202:205], v[104:107]
	v_mfma_f32_16x16x32_bf16 v[92:95], v[130:133], v[210:213], v[92:95]
	v_mfma_f32_16x16x32_bf16 v[88:91], v[170:173], v[210:213], v[88:91]
	v_mfma_f32_16x16x32_bf16 v[76:79], v[130:133], v[218:221], v[76:79]
	v_mfma_f32_16x16x32_bf16 v[72:75], v[170:173], v[218:221], v[72:75]
	v_mfma_f32_16x16x32_bf16 v[124:127], v[134:137], v[198:201], v[124:127]
	v_mfma_f32_16x16x32_bf16 v[120:123], v[174:177], v[198:201], v[120:123]
	v_mfma_f32_16x16x32_bf16 v[108:111], v[134:137], v[206:209], v[108:111]
	v_mfma_f32_16x16x32_bf16 v[104:107], v[174:177], v[206:209], v[104:107]
	v_mfma_f32_16x16x32_bf16 v[92:95], v[134:137], v[214:217], v[92:95]
	v_mfma_f32_16x16x32_bf16 v[88:91], v[174:177], v[214:217], v[88:91]
	v_mfma_f32_16x16x32_bf16 v[76:79], v[134:137], v[222:225], v[76:79]
	v_mfma_f32_16x16x32_bf16 v[72:75], v[174:177], v[222:225], v[72:75]
	v_mfma_f32_16x16x32_bf16 v[116:119], v[178:181], v[194:197], v[116:119]
	v_mfma_f32_16x16x32_bf16 v[112:115], v[186:189], v[194:197], v[112:115]
	v_mfma_f32_16x16x32_bf16 v[100:103], v[178:181], v[202:205], v[100:103]
	v_mfma_f32_16x16x32_bf16 v[96:99], v[186:189], v[202:205], v[96:99]
	v_mfma_f32_16x16x32_bf16 v[84:87], v[178:181], v[210:213], v[84:87]
	v_mfma_f32_16x16x32_bf16 v[80:83], v[186:189], v[210:213], v[80:83]
	v_mfma_f32_16x16x32_bf16 v[68:71], v[178:181], v[218:221], v[68:71]
	v_mfma_f32_16x16x32_bf16 v[64:67], v[186:189], v[218:221], v[64:67]
	v_mfma_f32_16x16x32_bf16 v[116:119], v[182:185], v[198:201], v[116:119]
	v_mfma_f32_16x16x32_bf16 v[112:115], v[190:193], v[198:201], v[112:115]
	v_mfma_f32_16x16x32_bf16 v[100:103], v[182:185], v[206:209], v[100:103]
	v_mfma_f32_16x16x32_bf16 v[96:99], v[190:193], v[206:209], v[96:99]
	v_mfma_f32_16x16x32_bf16 v[84:87], v[182:185], v[214:217], v[84:87]
	v_mfma_f32_16x16x32_bf16 v[80:83], v[190:193], v[214:217], v[80:83]
	v_mfma_f32_16x16x32_bf16 v[68:71], v[182:185], v[222:225], v[68:71]
	v_mfma_f32_16x16x32_bf16 v[64:67], v[190:193], v[222:225], v[64:67]
	s_barrier
	s_setprio 0
	s_add_u32 s38, s58, 0x8000
	s_addc_u32 s39, s59, 0
	s_add_i32 s60, s71, s3
	s_mov_b32 m0, s60
	ds_read_b128 v[194:197], v166 offset:49152
	ds_read_b128 v[198:201], v166 offset:50176
	ds_read_b128 v[202:205], v166 offset:51200
	ds_read_b128 v[206:209], v166 offset:52224
	ds_read_b128 v[210:213], v166 offset:53248
	ds_read_b128 v[214:217], v166 offset:54272
	ds_read_b128 v[218:221], v166 offset:55296
	ds_read_b128 v[222:225], v166 offset:56320
	global_load_lds_dwordx4 v144, s[38:39]
	s_add_i32 m0, s60, 0x2000
	s_nop 0
	global_load_lds_dwordx4 v140, s[38:39]
	s_add_u32 s38, s58, 0x9000
	s_addc_u32 s39, s59, 0
	s_add_i32 s58, s72, s3
	s_mov_b32 m0, s58
	s_nop 0
	global_load_lds_dwordx4 v144, s[38:39]
	s_add_i32 m0, s58, 0x2000
	s_nop 0
	global_load_lds_dwordx4 v140, s[38:39]
	s_mov_b32 m0, s54
	s_nop 0
	global_load_lds_dwordx4 v146, s[56:57]
	s_mov_b32 m0, s55
	s_nop 0
	global_load_lds_dwordx4 v142, s[56:57]
	s_waitcnt vmcnt(8)
	s_waitcnt lgkmcnt(0)
	s_setprio 1
	s_barrier
	v_mfma_f32_16x16x32_bf16 v[60:63], v[130:133], v[194:197], v[60:63]
	v_mfma_f32_16x16x32_bf16 v[56:59], v[170:173], v[194:197], v[56:59]
	v_mfma_f32_16x16x32_bf16 v[44:47], v[130:133], v[202:205], v[44:47]
	v_mfma_f32_16x16x32_bf16 v[40:43], v[170:173], v[202:205], v[40:43]
	v_mfma_f32_16x16x32_bf16 v[28:31], v[130:133], v[210:213], v[28:31]
	v_mfma_f32_16x16x32_bf16 v[24:27], v[170:173], v[210:213], v[24:27]
	v_mfma_f32_16x16x32_bf16 v[12:15], v[130:133], v[218:221], v[12:15]
	v_mfma_f32_16x16x32_bf16 v[8:11], v[170:173], v[218:221], v[8:11]
	v_mfma_f32_16x16x32_bf16 v[60:63], v[134:137], v[198:201], v[60:63]
	v_mfma_f32_16x16x32_bf16 v[56:59], v[174:177], v[198:201], v[56:59]
	v_mfma_f32_16x16x32_bf16 v[44:47], v[134:137], v[206:209], v[44:47]
	v_mfma_f32_16x16x32_bf16 v[40:43], v[174:177], v[206:209], v[40:43]
	v_mfma_f32_16x16x32_bf16 v[28:31], v[134:137], v[214:217], v[28:31]
	v_mfma_f32_16x16x32_bf16 v[24:27], v[174:177], v[214:217], v[24:27]
	v_mfma_f32_16x16x32_bf16 v[12:15], v[134:137], v[222:225], v[12:15]
	v_mfma_f32_16x16x32_bf16 v[8:11], v[174:177], v[222:225], v[8:11]
	v_mfma_f32_16x16x32_bf16 v[52:55], v[178:181], v[194:197], v[52:55]
	v_mfma_f32_16x16x32_bf16 v[48:51], v[186:189], v[194:197], v[48:51]
	v_mfma_f32_16x16x32_bf16 v[36:39], v[178:181], v[202:205], v[36:39]
	v_mfma_f32_16x16x32_bf16 v[32:35], v[186:189], v[202:205], v[32:35]
	v_mfma_f32_16x16x32_bf16 v[20:23], v[178:181], v[210:213], v[20:23]
	v_mfma_f32_16x16x32_bf16 v[16:19], v[186:189], v[210:213], v[16:19]
	v_mfma_f32_16x16x32_bf16 v[4:7], v[178:181], v[218:221], v[4:7]
	v_mfma_f32_16x16x32_bf16 v[0:3], v[186:189], v[218:221], v[0:3]
	v_mfma_f32_16x16x32_bf16 v[52:55], v[182:185], v[198:201], v[52:55]
	v_mfma_f32_16x16x32_bf16 v[48:51], v[190:193], v[198:201], v[48:51]
	v_mfma_f32_16x16x32_bf16 v[36:39], v[182:185], v[206:209], v[36:39]
	v_mfma_f32_16x16x32_bf16 v[32:35], v[190:193], v[206:209], v[32:35]
	v_mfma_f32_16x16x32_bf16 v[20:23], v[182:185], v[214:217], v[20:23]
	v_mfma_f32_16x16x32_bf16 v[16:19], v[190:193], v[214:217], v[16:19]
	v_mfma_f32_16x16x32_bf16 v[4:7], v[182:185], v[222:225], v[4:7]
	v_mfma_f32_16x16x32_bf16 v[0:3], v[190:193], v[222:225], v[0:3]
	s_barrier
	s_setprio 0
	s_add_i32 s70, s70, 2
	s_add_u32 s16, s16, 0x10000
	s_addc_u32 s17, s17, 0
	s_add_u32 s68, s68, 0x10000
	s_addc_u32 s69, s69, 0
	s_cmp_gt_u32 s70, 61
	s_cbranch_scc1 .LBB0_1571

; #define PG8_STAGE(bufoff, gbase, voff) do { _Pragma("unroll") for (int _i = 0; _i < 2; ++_i) \
;         __builtin_amdgcn_global_load_lds((const unsigned*)((const char*)(gbase) + (voff)[_i]), (LAS unsigned*)(lds + (bufoff) + ldsw + _i * 8192), 16, 0, 0); } while (0)
; #define PG8_LDA(dst, b, h) do { _Pragma("unroll") for (int m = 0; m < 4; ++m) _Pragma("unroll") for (int k = 0; k < 2; ++k) dst[m][k] = *(const LAS bf16x8*)(lds + PG8_SA(b, h) + aoff + m * 2048 + k * 1024); } while (0)
; #define PG8_LDB(dst, b, h) do { _Pragma("unroll") for (int n = 0; n < 2; ++n) _Pragma("unroll") for (int k = 0; k < 2; ++k) dst[n][k] = *(const LAS bf16x8*)(lds + PG8_SB(b, h) + boff + n * 2048 + k * 1024); } while (0)
; #define PG8_MMA(ai, bj, At, Bt) do { __builtin_amdgcn_s_setprio(1); _Pragma("unroll") for (int m = 0; m < 4; ++m) _Pragma("unroll") for (int n = 0; n < 2; ++n) _Pragma("unroll") for (int k = 0; k < 2; ++k) \
;         acc[ai][bj][m][n] = __builtin_amdgcn_mfma_f32_16x16x32_bf16(Bt[n][k], At[m][k], acc[ai][bj][m][n], 0, 0, 0); __builtin_amdgcn_s_setprio(0); } while (0)
; #define PG8_WAIT_V(n) asm volatile("s_waitcnt vmcnt(" #n ")" ::: "memory")
; #define PG8_WAIT_L(n) asm volatile("s_waitcnt lgkmcnt(" #n ")" ::: "memory")
; #define PG8_BAR __builtin_amdgcn_s_barrier()
; #define PG8_SCHED __builtin_amdgcn_sched_barrier(0)
; template <class Epi, class Sched, bool ALIGN_EPI>
; __device__ __forceinline__ void gemm_phase(LAS unsigned char* lds, const Gemm g, const Sched& S, const Epi& E, const int wid) {
;     ...
;             PG8_LDB(B0, 0, 0); PG8_LDB(B1, 0, 1); PG8_SCHED; PG8_LDA(At, 0, 0); PG8_STAGE(PG8_SA(1, 1), a1 + hstepA, voffA);
;             PG8_WAIT_V(8); PG8_WAIT_L(0); PG8_BAR; PG8_MMA(0, 0, At, B0); PG8_MMA(0, 1, At, B1); PG8_BAR; PG8_SCHED;
;             PG8_LDA(At, 0, 1); PG8_STAGE(PG8_SB(0, 0), b2, voffB); PG8_STAGE(PG8_SB(0, 1), b2 + hstepB, voffB); PG8_STAGE(PG8_SA(0, 0), a2, voffA);
;             PG8_WAIT_V(8); PG8_WAIT_L(0); PG8_BAR; PG8_MMA(1, 0, At, B0); PG8_MMA(1, 1, At, B1); PG8_BAR; PG8_SCHED;
;             PG8_LDB(B0, 1, 0); PG8_LDB(B1, 1, 1); PG8_SCHED; PG8_LDA(At, 1, 0); PG8_STAGE(PG8_SA(0, 1), a2 + hstepA, voffA);
;             PG8_WAIT_V(8); PG8_WAIT_L(0); PG8_BAR; PG8_MMA(0, 0, At, B0); PG8_MMA(0, 1, At, B1); PG8_BAR; PG8_SCHED;
.LBB0_1672:
	ds_read_b128 v[72:75], v202
	ds_read_b128 v[76:79], v202 offset:1024
	ds_read_b128 v[136:139], v202 offset:2048
	ds_read_b128 v[140:143], v202 offset:3072
	ds_read_b128 v[144:147], v203
	ds_read_b128 v[148:151], v203 offset:1024
	ds_read_b128 v[152:155], v203 offset:2048
	ds_read_b128 v[178:181], v203 offset:3072
	s_add_u32 s38, s16, 0x4000
	s_addc_u32 s60, s17, 0
	s_cmpk_eq_i32 s78, 0xfc
	s_cselect_b32 s64, s51, s38
	s_cselect_b32 s65, s35, s60
	s_cselect_b32 s62, s57, s59
	s_cselect_b32 s63, s49, s77
	s_add_u32 s60, s64, 0x8000
	s_addc_u32 s61, s65, 0
	s_add_i32 m0, s45, 0xc000
	ds_read_b128 v[182:185], v204
	ds_read_b128 v[186:189], v204 offset:1024
	ds_read_b128 v[190:193], v204 offset:2048
	ds_read_b128 v[194:197], v204 offset:3072
	ds_read_b128 v[208:211], v204 offset:4096
	ds_read_b128 v[212:215], v204 offset:5120
	ds_read_b128 v[216:219], v204 offset:6144
	ds_read_b128 v[220:223], v204 offset:7168
	global_load_lds_dwordx4 v168, s[16:17]
	s_add_i32 m0, s45, 0xe000
	s_nop 0
	global_load_lds_dwordx4 v170, s[16:17]
	s_waitcnt vmcnt(8)
	s_waitcnt lgkmcnt(0)
	s_setprio 1
	s_barrier
	v_mfma_f32_16x16x32_bf16 v[132:135], v[72:75], v[182:185], v[132:135]
	v_mfma_f32_16x16x32_bf16 v[128:131], v[136:139], v[182:185], v[128:131]
	v_mfma_f32_16x16x32_bf16 v[116:119], v[72:75], v[190:193], v[116:119]
	v_mfma_f32_16x16x32_bf16 v[112:115], v[136:139], v[190:193], v[112:115]
	v_mfma_f32_16x16x32_bf16 v[100:103], v[72:75], v[208:211], v[100:103]
	v_mfma_f32_16x16x32_bf16 v[96:99], v[136:139], v[208:211], v[96:99]
	v_mfma_f32_16x16x32_bf16 v[84:87], v[72:75], v[216:219], v[84:87]
	v_mfma_f32_16x16x32_bf16 v[80:83], v[136:139], v[216:219], v[80:83]
	v_mfma_f32_16x16x32_bf16 v[132:135], v[76:79], v[186:189], v[132:135]
	v_mfma_f32_16x16x32_bf16 v[128:131], v[140:143], v[186:189], v[128:131]
	v_mfma_f32_16x16x32_bf16 v[116:119], v[76:79], v[194:197], v[116:119]
	v_mfma_f32_16x16x32_bf16 v[112:115], v[140:143], v[194:197], v[112:115]
	v_mfma_f32_16x16x32_bf16 v[100:103], v[76:79], v[212:215], v[100:103]
	v_mfma_f32_16x16x32_bf16 v[96:99], v[140:143], v[212:215], v[96:99]
	v_mfma_f32_16x16x32_bf16 v[84:87], v[76:79], v[220:223], v[84:87]
	v_mfma_f32_16x16x32_bf16 v[80:83], v[140:143], v[220:223], v[80:83]
	v_mfma_f32_16x16x32_bf16 v[124:127], v[144:147], v[182:185], v[124:127]
	v_mfma_f32_16x16x32_bf16 v[120:123], v[152:155], v[182:185], v[120:123]
	v_mfma_f32_16x16x32_bf16 v[108:111], v[144:147], v[190:193], v[108:111]
	v_mfma_f32_16x16x32_bf16 v[104:107], v[152:155], v[190:193], v[104:107]
	v_mfma_f32_16x16x32_bf16 v[92:95], v[144:147], v[208:211], v[92:95]
	v_mfma_f32_16x16x32_bf16 v[88:91], v[152:155], v[208:211], v[88:91]
	v_mfma_f32_16x16x32_bf16 v[68:71], v[144:147], v[216:219], v[68:71]
	v_mfma_f32_16x16x32_bf16 v[64:67], v[152:155], v[216:219], v[64:67]
	v_mfma_f32_16x16x32_bf16 v[124:127], v[148:151], v[186:189], v[124:127]
	v_mfma_f32_16x16x32_bf16 v[120:123], v[178:181], v[186:189], v[120:123]
	v_mfma_f32_16x16x32_bf16 v[108:111], v[148:151], v[194:197], v[108:111]
	v_mfma_f32_16x16x32_bf16 v[104:107], v[178:181], v[194:197], v[104:107]
	v_mfma_f32_16x16x32_bf16 v[92:95], v[148:151], v[212:215], v[92:95]
	v_mfma_f32_16x16x32_bf16 v[88:91], v[178:181], v[212:215], v[88:91]
	v_mfma_f32_16x16x32_bf16 v[68:71], v[148:151], v[220:223], v[68:71]
	v_mfma_f32_16x16x32_bf16 v[64:67], v[178:181], v[220:223], v[64:67]
	s_barrier
	s_setprio 0
	s_add_i32 s38, s72, s3
	s_mov_b32 m0, s38
	ds_read_b128 v[182:185], v204 offset:16384
	ds_read_b128 v[186:189], v204 offset:17408
	ds_read_b128 v[190:193], v204 offset:18432
	ds_read_b128 v[194:197], v204 offset:19456
	ds_read_b128 v[208:211], v204 offset:20480
	ds_read_b128 v[212:215], v204 offset:21504
	ds_read_b128 v[216:219], v204 offset:22528
	ds_read_b128 v[220:223], v204 offset:23552
	global_load_lds_dwordx4 v158, s[62:63]
	s_add_i32 m0, s38, 0x2000
	s_add_u32 s80, s62, 0x1000
	s_addc_u32 s81, s63, 0
	s_add_i32 s38, s73, s3
	global_load_lds_dwordx4 v162, s[62:63]
	s_mov_b32 m0, s38
	s_nop 0
	global_load_lds_dwordx4 v158, s[80:81]
	s_add_i32 m0, s38, 0x2000
	s_nop 0
	global_load_lds_dwordx4 v162, s[80:81]
	s_mov_b32 m0, s45
	s_nop 0
	global_load_lds_dwordx4 v156, s[64:65]
	s_mov_b32 m0, s47
	s_nop 0
	global_load_lds_dwordx4 v160, s[64:65]
	s_waitcnt vmcnt(8)
	s_waitcnt lgkmcnt(0)
	s_setprio 1
	s_barrier
	v_mfma_f32_16x16x32_bf16 v[60:63], v[72:75], v[182:185], v[60:63]
	v_mfma_f32_16x16x32_bf16 v[56:59], v[136:139], v[182:185], v[56:59]
	v_mfma_f32_16x16x32_bf16 v[44:47], v[72:75], v[190:193], v[44:47]
	v_mfma_f32_16x16x32_bf16 v[40:43], v[136:139], v[190:193], v[40:43]
	v_mfma_f32_16x16x32_bf16 v[28:31], v[72:75], v[208:211], v[28:31]
	v_mfma_f32_16x16x32_bf16 v[24:27], v[136:139], v[208:211], v[24:27]
	v_mfma_f32_16x16x32_bf16 v[12:15], v[72:75], v[216:219], v[12:15]
	v_mfma_f32_16x16x32_bf16 v[8:11], v[136:139], v[216:219], v[8:11]
	v_mfma_f32_16x16x32_bf16 v[60:63], v[76:79], v[186:189], v[60:63]
	v_mfma_f32_16x16x32_bf16 v[56:59], v[140:143], v[186:189], v[56:59]
	v_mfma_f32_16x16x32_bf16 v[44:47], v[76:79], v[194:197], v[44:47]
	v_mfma_f32_16x16x32_bf16 v[40:43], v[140:143], v[194:197], v[40:43]
	v_mfma_f32_16x16x32_bf16 v[28:31], v[76:79], v[212:215], v[28:31]
	v_mfma_f32_16x16x32_bf16 v[24:27], v[140:143], v[212:215], v[24:27]
	v_mfma_f32_16x16x32_bf16 v[12:15], v[76:79], v[220:223], v[12:15]
	v_mfma_f32_16x16x32_bf16 v[8:11], v[140:143], v[220:223], v[8:11]
	v_mfma_f32_16x16x32_bf16 v[52:55], v[144:147], v[182:185], v[52:55]
	v_mfma_f32_16x16x32_bf16 v[48:51], v[152:155], v[182:185], v[48:51]
	v_mfma_f32_16x16x32_bf16 v[36:39], v[144:147], v[190:193], v[36:39]
	v_mfma_f32_16x16x32_bf16 v[32:35], v[152:155], v[190:193], v[32:35]
	v_mfma_f32_16x16x32_bf16 v[20:23], v[144:147], v[208:211], v[20:23]
	v_mfma_f32_16x16x32_bf16 v[16:19], v[152:155], v[208:211], v[16:19]
	v_mfma_f32_16x16x32_bf16 v[4:7], v[144:147], v[216:219], v[4:7]
	v_mfma_f32_16x16x32_bf16 v[0:3], v[152:155], v[216:219], v[0:3]
	v_mfma_f32_16x16x32_bf16 v[52:55], v[148:151], v[186:189], v[52:55]
	v_mfma_f32_16x16x32_bf16 v[48:51], v[178:181], v[186:189], v[48:51]
	v_mfma_f32_16x16x32_bf16 v[36:39], v[148:151], v[194:197], v[36:39]
	v_mfma_f32_16x16x32_bf16 v[32:35], v[178:181], v[194:197], v[32:35]
	v_mfma_f32_16x16x32_bf16 v[20:23], v[148:151], v[212:215], v[20:23]
	v_mfma_f32_16x16x32_bf16 v[16:19], v[178:181], v[212:215], v[16:19]
	v_mfma_f32_16x16x32_bf16 v[4:7], v[148:151], v[220:223], v[4:7]
	v_mfma_f32_16x16x32_bf16 v[0:3], v[178:181], v[220:223], v[0:3]
	s_barrier
; #define PG8_STAGE(bufoff, gbase, voff) do { _Pragma("unroll") for (int _i = 0; _i < 2; ++_i) \
;         __builtin_amdgcn_global_load_lds((const unsigned*)((const char*)(gbase) + (voff)[_i]), (LAS unsigned*)(lds + (bufoff) + ldsw + _i * 8192), 16, 0, 0); } while (0)
; #define PG8_LDA(dst, b, h) do { _Pragma("unroll") for (int m = 0; m < 4; ++m) _Pragma("unroll") for (int k = 0; k < 2; ++k) dst[m][k] = *(const LAS bf16x8*)(lds + PG8_SA(b, h) + aoff + m * 2048 + k * 1024); } while (0)
; #define PG8_LDB(dst, b, h) do { _Pragma("unroll") for (int n = 0; n < 2; ++n) _Pragma("unroll") for (int k = 0; k < 2; ++k) dst[n][k] = *(const LAS bf16x8*)(lds + PG8_SB(b, h) + boff + n * 2048 + k * 1024); } while (0)
; #define PG8_MMA(ai, bj, At, Bt) do { __builtin_amdgcn_s_setprio(1); _Pragma("unroll") for (int m = 0; m < 4; ++m) _Pragma("unroll") for (int n = 0; n < 2; ++n) _Pragma("unroll") for (int k = 0; k < 2; ++k) \
;         acc[ai][bj][m][n] = __builtin_amdgcn_mfma_f32_16x16x32_bf16(Bt[n][k], At[m][k], acc[ai][bj][m][n], 0, 0, 0); __builtin_amdgcn_s_setprio(0); } while (0)
; #define PG8_WAIT_V(n) asm volatile("s_waitcnt vmcnt(" #n ")" ::: "memory")
; #define PG8_WAIT_L(n) asm volatile("s_waitcnt lgkmcnt(" #n ")" ::: "memory")
; #define PG8_BAR __builtin_amdgcn_s_barrier()
; #define PG8_SCHED __builtin_amdgcn_sched_barrier(0)
; template <class Epi, class Sched, bool ALIGN_EPI>
; __device__ __forceinline__ void gemm_phase(LAS unsigned char* lds, const Gemm g, const Sched& S, const Epi& E, const int wid) {
;     ...
;             PG8_LDB(B0, 1, 0); PG8_LDB(B1, 1, 1); PG8_SCHED; PG8_LDA(At, 1, 0); PG8_STAGE(PG8_SA(0, 1), a2 + hstepA, voffA);
;             PG8_WAIT_V(8); PG8_WAIT_L(0); PG8_BAR; PG8_MMA(0, 0, At, B0); PG8_MMA(0, 1, At, B1); PG8_BAR; PG8_SCHED;
;             PG8_LDA(At, 1, 1); PG8_STAGE(PG8_SB(1, 0), b3, voffB); PG8_STAGE(PG8_SB(1, 1), b3 + hstepB, voffB); PG8_STAGE(PG8_SA(1, 0), a3, voffA);
;             PG8_WAIT_V(8); PG8_WAIT_L(0); PG8_BAR; PG8_MMA(1, 0, At, B0); PG8_MMA(1, 1, At, B1); PG8_BAR; PG8_SCHED;
;         }
	s_setprio 0
	s_add_i32 s38, 0, 0x18000
	s_add_i32 s79, 0, 0x1c000
	v_add_u32_e32 v140, s38, v198
	v_add_u32_e32 v164, s79, v198
	ds_read_b128 v[72:75], v140
	ds_read_b128 v[76:79], v140 offset:1024
	ds_read_b128 v[136:139], v140 offset:2048
	ds_read_b128 v[140:143], v140 offset:3072
	ds_read_b128 v[144:147], v164
	ds_read_b128 v[148:151], v164 offset:1024
	ds_read_b128 v[152:155], v164 offset:2048
	ds_read_b128 v[178:181], v164 offset:3072
	s_add_u32 s64, s64, 0x4000
	s_addc_u32 s65, s65, 0
	s_mov_b32 m0, s66
	ds_read_b128 v[182:185], v204 offset:32768
	ds_read_b128 v[186:189], v204 offset:33792
	ds_read_b128 v[190:193], v204 offset:34816
	ds_read_b128 v[194:197], v204 offset:35840
	ds_read_b128 v[208:211], v204 offset:36864
	ds_read_b128 v[212:215], v204 offset:37888
	ds_read_b128 v[216:219], v204 offset:38912
	ds_read_b128 v[220:223], v204 offset:39936
	global_load_lds_dwordx4 v156, s[64:65]
	s_mov_b32 m0, s67
	s_nop 0
	global_load_lds_dwordx4 v160, s[64:65]
	s_waitcnt vmcnt(8)
	s_waitcnt lgkmcnt(0)
	s_setprio 1
	s_barrier
	v_mfma_f32_16x16x32_bf16 v[132:135], v[72:75], v[182:185], v[132:135]
	v_mfma_f32_16x16x32_bf16 v[128:131], v[136:139], v[182:185], v[128:131]
	v_mfma_f32_16x16x32_bf16 v[116:119], v[72:75], v[190:193], v[116:119]
	v_mfma_f32_16x16x32_bf16 v[112:115], v[136:139], v[190:193], v[112:115]
	v_mfma_f32_16x16x32_bf16 v[100:103], v[72:75], v[208:211], v[100:103]
	v_mfma_f32_16x16x32_bf16 v[96:99], v[136:139], v[208:211], v[96:99]
	v_mfma_f32_16x16x32_bf16 v[84:87], v[72:75], v[216:219], v[84:87]
	v_mfma_f32_16x16x32_bf16 v[80:83], v[136:139], v[216:219], v[80:83]
	v_mfma_f32_16x16x32_bf16 v[132:135], v[76:79], v[186:189], v[132:135]
	v_mfma_f32_16x16x32_bf16 v[128:131], v[140:143], v[186:189], v[128:131]
	v_mfma_f32_16x16x32_bf16 v[116:119], v[76:79], v[194:197], v[116:119]
	v_mfma_f32_16x16x32_bf16 v[112:115], v[140:143], v[194:197], v[112:115]
	v_mfma_f32_16x16x32_bf16 v[100:103], v[76:79], v[212:215], v[100:103]
	v_mfma_f32_16x16x32_bf16 v[96:99], v[140:143], v[212:215], v[96:99]
	v_mfma_f32_16x16x32_bf16 v[84:87], v[76:79], v[220:223], v[84:87]
	v_mfma_f32_16x16x32_bf16 v[80:83], v[140:143], v[220:223], v[80:83]
	v_mfma_f32_16x16x32_bf16 v[124:127], v[144:147], v[182:185], v[124:127]
	v_mfma_f32_16x16x32_bf16 v[120:123], v[152:155], v[182:185], v[120:123]
	v_mfma_f32_16x16x32_bf16 v[108:111], v[144:147], v[190:193], v[108:111]
	v_mfma_f32_16x16x32_bf16 v[104:107], v[152:155], v[190:193], v[104:107]
	v_mfma_f32_16x16x32_bf16 v[92:95], v[144:147], v[208:211], v[92:95]
	v_mfma_f32_16x16x32_bf16 v[88:91], v[152:155], v[208:211], v[88:91]
	v_mfma_f32_16x16x32_bf16 v[68:71], v[144:147], v[216:219], v[68:71]
	v_mfma_f32_16x16x32_bf16 v[64:67], v[152:155], v[216:219], v[64:67]
	v_mfma_f32_16x16x32_bf16 v[124:127], v[148:151], v[186:189], v[124:127]
	v_mfma_f32_16x16x32_bf16 v[120:123], v[178:181], v[186:189], v[120:123]
	v_mfma_f32_16x16x32_bf16 v[108:111], v[148:151], v[194:197], v[108:111]
	v_mfma_f32_16x16x32_bf16 v[104:107], v[178:181], v[194:197], v[104:107]
	v_mfma_f32_16x16x32_bf16 v[92:95], v[148:151], v[212:215], v[92:95]
	v_mfma_f32_16x16x32_bf16 v[88:91], v[178:181], v[212:215], v[88:91]
	v_mfma_f32_16x16x32_bf16 v[68:71], v[148:151], v[220:223], v[68:71]
	v_mfma_f32_16x16x32_bf16 v[64:67], v[178:181], v[220:223], v[64:67]
	s_barrier
	s_setprio 0
	s_add_u32 s64, s62, 0x8000
	s_addc_u32 s65, s63, 0
	s_add_i32 s38, s38, s3
	s_mov_b32 m0, s38
	ds_read_b128 v[182:185], v204 offset:49152
	ds_read_b128 v[186:189], v204 offset:50176
	ds_read_b128 v[190:193], v204 offset:51200
	ds_read_b128 v[194:197], v204 offset:52224
	ds_read_b128 v[208:211], v204 offset:53248
	ds_read_b128 v[212:215], v204 offset:54272
	ds_read_b128 v[216:219], v204 offset:55296
	ds_read_b128 v[220:223], v204 offset:56320
	global_load_lds_dwordx4 v158, s[64:65]
	s_add_i32 m0, s38, 0x2000
	s_add_u32 s62, s62, 0x9000
	s_addc_u32 s63, s63, 0
	s_add_i32 s38, s79, s3
	global_load_lds_dwordx4 v162, s[64:65]
	s_mov_b32 m0, s38
	s_nop 0
	global_load_lds_dwordx4 v158, s[62:63]
	s_add_i32 m0, s38, 0x2000
	s_nop 0
	global_load_lds_dwordx4 v162, s[62:63]
	s_mov_b32 m0, s69
	s_nop 0
	global_load_lds_dwordx4 v156, s[60:61]
	s_mov_b32 m0, s70
	s_nop 0
	global_load_lds_dwordx4 v160, s[60:61]
	s_waitcnt vmcnt(8)
	s_waitcnt lgkmcnt(0)
	s_setprio 1
	s_barrier
	v_mfma_f32_16x16x32_bf16 v[60:63], v[72:75], v[182:185], v[60:63]
	v_mfma_f32_16x16x32_bf16 v[56:59], v[136:139], v[182:185], v[56:59]
	v_mfma_f32_16x16x32_bf16 v[44:47], v[72:75], v[190:193], v[44:47]
	v_mfma_f32_16x16x32_bf16 v[40:43], v[136:139], v[190:193], v[40:43]
	v_mfma_f32_16x16x32_bf16 v[28:31], v[72:75], v[208:211], v[28:31]
	v_mfma_f32_16x16x32_bf16 v[24:27], v[136:139], v[208:211], v[24:27]
	v_mfma_f32_16x16x32_bf16 v[12:15], v[72:75], v[216:219], v[12:15]
	v_mfma_f32_16x16x32_bf16 v[8:11], v[136:139], v[216:219], v[8:11]
	v_mfma_f32_16x16x32_bf16 v[60:63], v[76:79], v[186:189], v[60:63]
	v_mfma_f32_16x16x32_bf16 v[56:59], v[140:143], v[186:189], v[56:59]
	v_mfma_f32_16x16x32_bf16 v[44:47], v[76:79], v[194:197], v[44:47]
	v_mfma_f32_16x16x32_bf16 v[40:43], v[140:143], v[194:197], v[40:43]
	v_mfma_f32_16x16x32_bf16 v[28:31], v[76:79], v[212:215], v[28:31]
	v_mfma_f32_16x16x32_bf16 v[24:27], v[140:143], v[212:215], v[24:27]
	v_mfma_f32_16x16x32_bf16 v[12:15], v[76:79], v[220:223], v[12:15]
	v_mfma_f32_16x16x32_bf16 v[8:11], v[140:143], v[220:223], v[8:11]
	v_mfma_f32_16x16x32_bf16 v[52:55], v[144:147], v[182:185], v[52:55]
	v_mfma_f32_16x16x32_bf16 v[48:51], v[152:155], v[182:185], v[48:51]
	v_mfma_f32_16x16x32_bf16 v[36:39], v[144:147], v[190:193], v[36:39]
	v_mfma_f32_16x16x32_bf16 v[32:35], v[152:155], v[190:193], v[32:35]
	v_mfma_f32_16x16x32_bf16 v[20:23], v[144:147], v[208:211], v[20:23]
	v_mfma_f32_16x16x32_bf16 v[16:19], v[152:155], v[208:211], v[16:19]
	v_mfma_f32_16x16x32_bf16 v[4:7], v[144:147], v[216:219], v[4:7]
	v_mfma_f32_16x16x32_bf16 v[0:3], v[152:155], v[216:219], v[0:3]
	v_mfma_f32_16x16x32_bf16 v[52:55], v[148:151], v[186:189], v[52:55]
	v_mfma_f32_16x16x32_bf16 v[48:51], v[178:181], v[186:189], v[48:51]
	v_mfma_f32_16x16x32_bf16 v[36:39], v[148:151], v[194:197], v[36:39]
	v_mfma_f32_16x16x32_bf16 v[32:35], v[178:181], v[194:197], v[32:35]
	v_mfma_f32_16x16x32_bf16 v[20:23], v[148:151], v[212:215], v[20:23]
	v_mfma_f32_16x16x32_bf16 v[16:19], v[178:181], v[212:215], v[16:19]
	v_mfma_f32_16x16x32_bf16 v[4:7], v[148:151], v[220:223], v[4:7]
	v_mfma_f32_16x16x32_bf16 v[0:3], v[178:181], v[220:223], v[0:3]
	s_barrier
	s_setprio 0
	s_add_i32 s78, s78, 2
	s_add_u32 s59, s59, 0x10000
	s_addc_u32 s77, s77, 0
	s_add_u32 s16, s16, 0x10000
	s_addc_u32 s17, s17, 0
	s_cmpk_gt_u32 s78, 0xfd
	s_cbranch_scc0 .LBB0_1672
	s_and_b64 vcc, exec, s[28:29]
	s_cbranch_vccz .LBB0_1675
	s_barrier
